# GEMM K-loops: removed 48 redundant back-to-back s_setprio 0/1 pairs (v40 + instruction reduction)
# baseline (speedup 1.0000x reference)
; #define PG8_STAGE(bufoff, gbase, voff) do { _Pragma("unroll") for (int _i = 0; _i < 2; ++_i) \
;         __builtin_amdgcn_global_load_lds((const unsigned*)((const char*)(gbase) + (voff)[_i]), (PG8_LAS unsigned*)(lds + (bufoff) + ldsw + _i * 8192), 16, 0, 0); } while (0)
; #define PG8_LDA(dst, b, h) do { _Pragma("unroll") for (int m = 0; m < 4; ++m) _Pragma("unroll") for (int k = 0; k < 2; ++k) dst[m][k] = *(const PG8_LAS bf16x8*)(lds + PG8_SA(b, h) + aoff + m * 2048 + k * 1024); } while (0)
; #define PG8_LDB(dst, b, h) do { _Pragma("unroll") for (int n = 0; n < 2; ++n) _Pragma("unroll") for (int k = 0; k < 2; ++k) dst[n][k] = *(const PG8_LAS bf16x8*)(lds + PG8_SB(b, h) + boff + n * 2048 + k * 1024); } while (0)
; #define PG8_MMA(ai, bj, At, Bt) do { __builtin_amdgcn_s_setprio(1); _Pragma("unroll") for (int m = 0; m < 4; ++m) _Pragma("unroll") for (int n = 0; n < 2; ++n) _Pragma("unroll") for (int k = 0; k < 2; ++k) \
;         acc[ai][bj][m][n] = __builtin_amdgcn_mfma_f32_16x16x32_bf16(Bt[n][k], At[m][k], acc[ai][bj][m][n], 0, 0, 0); __builtin_amdgcn_s_setprio(0); } while (0)
; #define PG8_WAIT_V(n) asm volatile("s_waitcnt vmcnt(" #n ")" ::: "memory")
; #define PG8_WAIT_L(n) asm volatile("s_waitcnt lgkmcnt(" #n ")" ::: "memory")
; #define PG8_BAR __builtin_amdgcn_s_barrier()
; #define PG8_SCHED __builtin_amdgcn_sched_barrier(0)
; template <class Epi, class Sched, bool ALIGN_EPI = false, bool SP2 = false>
; __device__ __forceinline__ void gemm_phase(PG8_LAS unsigned char* lds, const Gemm g, const Sched& S, const Epi& E) {
;     ...
;             PG8_LDB(B0, 0, 0); PG8_LDB(B1, 0, 1); PG8_SCHED; PG8_LDA(At, 0, 0); PG8_STAGE(PG8_SA(1, 1), a1 + hstep, voffA);
;             PG8_WAIT_V(8); PG8_WAIT_L(0); PG8_BAR; PG8_MMA(0, 0, At, B0); PG8_MMA(0, 1, At, B1); PG8_BAR; PG8_SCHED;
;             PG8_LDA(At, 0, 1); PG8_STAGE(PG8_SB(0, 0), b2, voffB); PG8_STAGE(PG8_SB(0, 1), b2 + hstep, voffB); PG8_STAGE(PG8_SA(0, 0), a2, voffA);
;             PG8_WAIT_V(8); PG8_WAIT_L(0); PG8_BAR; PG8_MMA(1, 0, At, B0); PG8_MMA(1, 1, At, B1); PG8_BAR; PG8_SCHED;
.LBB0_179:
	ds_read_b128 v[146:149], v152
	ds_read_b128 v[156:159], v152 offset:1024
	ds_read_b128 v[162:165], v152 offset:2048
	ds_read_b128 v[166:169], v152 offset:3072
	ds_read_b128 v[170:173], v153
	ds_read_b128 v[178:181], v153 offset:1024
	ds_read_b128 v[182:185], v153 offset:2048
	ds_read_b128 v[186:189], v153 offset:3072
	s_add_u32 s8, s52, 0xfffc0080
	s_addc_u32 s9, s53, -1
	s_cmp_eq_u32 s86, 12
	s_cselect_b32 s57, s37, s9
	s_cselect_b32 s56, s80, s8
	s_cselect_b32 s55, s19, s83
	s_cselect_b32 s54, s81, s82
	v_lshl_add_u64 v[174:175], s[52:53], 0, v[136:137]
	s_add_i32 m0, s51, 0xc000
	ds_read_b128 v[190:193], v154
	ds_read_b128 v[194:197], v154 offset:1024
	ds_read_b128 v[198:201], v154 offset:2048
	ds_read_b128 v[202:205], v154 offset:3072
	ds_read_b128 v[206:209], v154 offset:4096
	ds_read_b128 v[210:213], v154 offset:5120
	ds_read_b128 v[214:217], v154 offset:6144
	ds_read_b128 v[218:221], v154 offset:7168
	global_load_lds_dwordx4 v[174:175], off
	v_lshl_add_u64 v[174:175], s[52:53], 0, v[138:139]
	s_add_i32 m0, s51, 0xe000
	s_nop 0
	global_load_lds_dwordx4 v[174:175], off
	s_waitcnt vmcnt(8)
	s_waitcnt lgkmcnt(0)
	s_barrier
	s_setprio 1
	s_waitcnt lgkmcnt(0)
	v_mfma_f32_16x16x32_bf16 v[124:127], v[146:149], v[190:193], v[124:127]
	v_mfma_f32_16x16x32_bf16 v[120:123], v[162:165], v[190:193], v[120:123]
	v_mfma_f32_16x16x32_bf16 v[112:115], v[146:149], v[198:201], v[112:115]
	v_mfma_f32_16x16x32_bf16 v[104:107], v[162:165], v[198:201], v[104:107]
	v_mfma_f32_16x16x32_bf16 v[96:99], v[146:149], v[206:209], v[96:99]
	v_mfma_f32_16x16x32_bf16 v[88:91], v[162:165], v[206:209], v[88:91]
	v_mfma_f32_16x16x32_bf16 v[80:83], v[146:149], v[214:217], v[80:83]
	v_mfma_f32_16x16x32_bf16 v[72:75], v[162:165], v[214:217], v[72:75]
	v_mfma_f32_16x16x32_bf16 v[124:127], v[156:159], v[194:197], v[124:127]
	v_mfma_f32_16x16x32_bf16 v[120:123], v[166:169], v[194:197], v[120:123]
	v_mfma_f32_16x16x32_bf16 v[112:115], v[156:159], v[202:205], v[112:115]
	v_mfma_f32_16x16x32_bf16 v[104:107], v[166:169], v[202:205], v[104:107]
	v_mfma_f32_16x16x32_bf16 v[96:99], v[156:159], v[210:213], v[96:99]
	v_mfma_f32_16x16x32_bf16 v[88:91], v[166:169], v[210:213], v[88:91]
	v_mfma_f32_16x16x32_bf16 v[80:83], v[156:159], v[218:221], v[80:83]
	v_mfma_f32_16x16x32_bf16 v[72:75], v[166:169], v[218:221], v[72:75]
	v_mfma_f32_16x16x32_bf16 v[116:119], v[170:173], v[190:193], v[116:119]
	v_mfma_f32_16x16x32_bf16 v[108:111], v[182:185], v[190:193], v[108:111]
	v_mfma_f32_16x16x32_bf16 v[100:103], v[170:173], v[198:201], v[100:103]
	v_mfma_f32_16x16x32_bf16 v[92:95], v[182:185], v[198:201], v[92:95]
	v_mfma_f32_16x16x32_bf16 v[84:87], v[170:173], v[206:209], v[84:87]
	v_mfma_f32_16x16x32_bf16 v[76:79], v[182:185], v[206:209], v[76:79]
	v_mfma_f32_16x16x32_bf16 v[68:71], v[170:173], v[214:217], v[68:71]
	v_mfma_f32_16x16x32_bf16 v[64:67], v[182:185], v[214:217], v[64:67]
	v_mfma_f32_16x16x32_bf16 v[116:119], v[178:181], v[194:197], v[116:119]
	v_mfma_f32_16x16x32_bf16 v[108:111], v[186:189], v[194:197], v[108:111]
	v_mfma_f32_16x16x32_bf16 v[100:103], v[178:181], v[202:205], v[100:103]
	v_mfma_f32_16x16x32_bf16 v[92:95], v[186:189], v[202:205], v[92:95]
	v_mfma_f32_16x16x32_bf16 v[84:87], v[178:181], v[210:213], v[84:87]
	v_mfma_f32_16x16x32_bf16 v[76:79], v[186:189], v[210:213], v[76:79]
	v_mfma_f32_16x16x32_bf16 v[68:71], v[178:181], v[218:221], v[68:71]
	v_mfma_f32_16x16x32_bf16 v[64:67], v[186:189], v[218:221], v[64:67]
	s_setprio 0
	s_barrier
	s_add_i32 s8, s76, s3
	v_lshl_add_u64 v[174:175], s[54:55], 0, v[132:133]
	s_mov_b32 m0, s8
	ds_read_b128 v[190:193], v154 offset:16384
	ds_read_b128 v[194:197], v154 offset:17408
	ds_read_b128 v[198:201], v154 offset:18432
	ds_read_b128 v[202:205], v154 offset:19456
	ds_read_b128 v[206:209], v154 offset:20480
	ds_read_b128 v[210:213], v154 offset:21504
	ds_read_b128 v[214:217], v154 offset:22528
	ds_read_b128 v[218:221], v154 offset:23552
	global_load_lds_dwordx4 v[174:175], off
	s_add_i32 m0, s8, 0x2000
	s_add_u32 s8, s54, 0x40000
	v_lshl_add_u64 v[222:223], s[54:55], 0, v[128:129]
	s_addc_u32 s9, s55, 0
	s_add_i32 s60, s77, s3
	global_load_lds_dwordx4 v[222:223], off
	v_lshl_add_u64 v[224:225], s[8:9], 0, v[132:133]
	s_mov_b32 m0, s60
	v_lshl_add_u64 v[226:227], s[56:57], 0, v[130:131]
	global_load_lds_dwordx4 v[224:225], off
	v_lshl_add_u64 v[224:225], s[8:9], 0, v[128:129]
	s_add_i32 m0, s60, 0x2000
	s_nop 0
	global_load_lds_dwordx4 v[224:225], off
	v_lshl_add_u64 v[224:225], s[56:57], 0, v[134:135]
	s_mov_b32 m0, s51
	s_nop 0
	global_load_lds_dwordx4 v[224:225], off
	s_mov_b32 m0, s68
	s_nop 0
	global_load_lds_dwordx4 v[226:227], off
	s_waitcnt vmcnt(8)
	s_waitcnt lgkmcnt(0)
	s_barrier
; #define PG8_STAGE(bufoff, gbase, voff) do { _Pragma("unroll") for (int _i = 0; _i < 2; ++_i) \
;         __builtin_amdgcn_global_load_lds((const unsigned*)((const char*)(gbase) + (voff)[_i]), (PG8_LAS unsigned*)(lds + (bufoff) + ldsw + _i * 8192), 16, 0, 0); } while (0)
; #define PG8_LDA(dst, b, h) do { _Pragma("unroll") for (int m = 0; m < 4; ++m) _Pragma("unroll") for (int k = 0; k < 2; ++k) dst[m][k] = *(const PG8_LAS bf16x8*)(lds + PG8_SA(b, h) + aoff + m * 2048 + k * 1024); } while (0)
; #define PG8_LDB(dst, b, h) do { _Pragma("unroll") for (int n = 0; n < 2; ++n) _Pragma("unroll") for (int k = 0; k < 2; ++k) dst[n][k] = *(const PG8_LAS bf16x8*)(lds + PG8_SB(b, h) + boff + n * 2048 + k * 1024); } while (0)
; #define PG8_MMA(ai, bj, At, Bt) do { __builtin_amdgcn_s_setprio(1); _Pragma("unroll") for (int m = 0; m < 4; ++m) _Pragma("unroll") for (int n = 0; n < 2; ++n) _Pragma("unroll") for (int k = 0; k < 2; ++k) \
;         acc[ai][bj][m][n] = __builtin_amdgcn_mfma_f32_16x16x32_bf16(Bt[n][k], At[m][k], acc[ai][bj][m][n], 0, 0, 0); __builtin_amdgcn_s_setprio(0); } while (0)
; #define PG8_WAIT_V(n) asm volatile("s_waitcnt vmcnt(" #n ")" ::: "memory")
; #define PG8_WAIT_L(n) asm volatile("s_waitcnt lgkmcnt(" #n ")" ::: "memory")
; #define PG8_BAR __builtin_amdgcn_s_barrier()
; #define PG8_SCHED __builtin_amdgcn_sched_barrier(0)
; template <class Epi, class Sched, bool ALIGN_EPI = false, bool SP2 = false>
; __device__ __forceinline__ void gemm_phase(PG8_LAS unsigned char* lds, const Gemm g, const Sched& S, const Epi& E) {
;     ...
;             PG8_WAIT_V(8); PG8_WAIT_L(0); PG8_BAR; PG8_MMA(1, 0, At, B0); PG8_MMA(1, 1, At, B1); PG8_BAR; PG8_SCHED;
;             PG8_LDB(B0, 1, 0); PG8_LDB(B1, 1, 1); PG8_SCHED; PG8_LDA(At, 1, 0); PG8_STAGE(PG8_SA(0, 1), a2 + hstep, voffA);
;             PG8_WAIT_V(8); PG8_WAIT_L(0); PG8_BAR; PG8_MMA(0, 0, At, B0); PG8_MMA(0, 1, At, B1); PG8_BAR; PG8_SCHED;
	s_setprio 1
	s_waitcnt lgkmcnt(0)
	v_mfma_f32_16x16x32_bf16 v[60:63], v[146:149], v[190:193], v[60:63]
	v_mfma_f32_16x16x32_bf16 v[56:59], v[162:165], v[190:193], v[56:59]
	v_mfma_f32_16x16x32_bf16 v[48:51], v[146:149], v[198:201], v[48:51]
	v_mfma_f32_16x16x32_bf16 v[40:43], v[162:165], v[198:201], v[40:43]
	v_mfma_f32_16x16x32_bf16 v[32:35], v[146:149], v[206:209], v[32:35]
	v_mfma_f32_16x16x32_bf16 v[24:27], v[162:165], v[206:209], v[24:27]
	v_mfma_f32_16x16x32_bf16 v[16:19], v[146:149], v[214:217], v[16:19]
	v_mfma_f32_16x16x32_bf16 v[8:11], v[162:165], v[214:217], v[8:11]
	v_mfma_f32_16x16x32_bf16 v[60:63], v[156:159], v[194:197], v[60:63]
	v_mfma_f32_16x16x32_bf16 v[56:59], v[166:169], v[194:197], v[56:59]
	v_mfma_f32_16x16x32_bf16 v[48:51], v[156:159], v[202:205], v[48:51]
	v_mfma_f32_16x16x32_bf16 v[40:43], v[166:169], v[202:205], v[40:43]
	v_mfma_f32_16x16x32_bf16 v[32:35], v[156:159], v[210:213], v[32:35]
	v_mfma_f32_16x16x32_bf16 v[24:27], v[166:169], v[210:213], v[24:27]
	v_mfma_f32_16x16x32_bf16 v[16:19], v[156:159], v[218:221], v[16:19]
	v_mfma_f32_16x16x32_bf16 v[8:11], v[166:169], v[218:221], v[8:11]
	v_mfma_f32_16x16x32_bf16 v[52:55], v[170:173], v[190:193], v[52:55]
	v_mfma_f32_16x16x32_bf16 v[44:47], v[182:185], v[190:193], v[44:47]
	v_mfma_f32_16x16x32_bf16 v[36:39], v[170:173], v[198:201], v[36:39]
	v_mfma_f32_16x16x32_bf16 v[28:31], v[182:185], v[198:201], v[28:31]
	v_mfma_f32_16x16x32_bf16 v[20:23], v[170:173], v[206:209], v[20:23]
	v_mfma_f32_16x16x32_bf16 v[12:15], v[182:185], v[206:209], v[12:15]
	v_mfma_f32_16x16x32_bf16 v[4:7], v[170:173], v[214:217], v[4:7]
	v_mfma_f32_16x16x32_bf16 v[0:3], v[182:185], v[214:217], v[0:3]
	v_mfma_f32_16x16x32_bf16 v[52:55], v[178:181], v[194:197], v[52:55]
	v_mfma_f32_16x16x32_bf16 v[44:47], v[186:189], v[194:197], v[44:47]
	v_mfma_f32_16x16x32_bf16 v[36:39], v[178:181], v[202:205], v[36:39]
	v_mfma_f32_16x16x32_bf16 v[28:31], v[186:189], v[202:205], v[28:31]
	v_mfma_f32_16x16x32_bf16 v[20:23], v[178:181], v[210:213], v[20:23]
	v_mfma_f32_16x16x32_bf16 v[12:15], v[186:189], v[210:213], v[12:15]
	v_mfma_f32_16x16x32_bf16 v[4:7], v[178:181], v[218:221], v[4:7]
	v_mfma_f32_16x16x32_bf16 v[0:3], v[186:189], v[218:221], v[0:3]
	s_setprio 0
	s_barrier
	s_add_i32 s60, 0, 0x18000
	v_add_u32_e32 v144, s60, v150
	s_add_i32 s61, 0, 0x1c000
	ds_read_b128 v[146:149], v144
	ds_read_b128 v[156:159], v144 offset:1024
	ds_read_b128 v[162:165], v144 offset:2048
	ds_read_b128 v[166:169], v144 offset:3072
	v_add_u32_e32 v144, s61, v150
	ds_read_b128 v[170:173], v144
	ds_read_b128 v[178:181], v144 offset:1024
	ds_read_b128 v[182:185], v144 offset:2048
	ds_read_b128 v[186:189], v144 offset:3072
	s_add_u32 s8, s56, 0x40000
	s_addc_u32 s9, s57, 0
	s_mov_b32 m0, s69
	v_lshl_add_u64 v[228:229], s[8:9], 0, v[134:135]
	ds_read_b128 v[190:193], v154 offset:32768
	ds_read_b128 v[194:197], v154 offset:33792
	ds_read_b128 v[198:201], v154 offset:34816
	ds_read_b128 v[202:205], v154 offset:35840
	ds_read_b128 v[206:209], v154 offset:36864
	ds_read_b128 v[210:213], v154 offset:37888
	ds_read_b128 v[214:217], v154 offset:38912
	ds_read_b128 v[218:221], v154 offset:39936
	global_load_lds_dwordx4 v[228:229], off
	v_lshl_add_u64 v[228:229], s[8:9], 0, v[130:131]
	s_mov_b32 m0, s70
	s_nop 0
	global_load_lds_dwordx4 v[228:229], off
	s_waitcnt vmcnt(8)
	s_waitcnt lgkmcnt(0)
	s_barrier
	s_setprio 1
	s_waitcnt lgkmcnt(0)
	v_mfma_f32_16x16x32_bf16 v[124:127], v[146:149], v[190:193], v[124:127]
	v_mfma_f32_16x16x32_bf16 v[120:123], v[162:165], v[190:193], v[120:123]
	v_mfma_f32_16x16x32_bf16 v[112:115], v[146:149], v[198:201], v[112:115]
	v_mfma_f32_16x16x32_bf16 v[104:107], v[162:165], v[198:201], v[104:107]
	v_mfma_f32_16x16x32_bf16 v[96:99], v[146:149], v[206:209], v[96:99]
	v_mfma_f32_16x16x32_bf16 v[88:91], v[162:165], v[206:209], v[88:91]
	v_mfma_f32_16x16x32_bf16 v[80:83], v[146:149], v[214:217], v[80:83]
	v_mfma_f32_16x16x32_bf16 v[72:75], v[162:165], v[214:217], v[72:75]
	v_mfma_f32_16x16x32_bf16 v[124:127], v[156:159], v[194:197], v[124:127]
	v_mfma_f32_16x16x32_bf16 v[120:123], v[166:169], v[194:197], v[120:123]
	v_mfma_f32_16x16x32_bf16 v[112:115], v[156:159], v[202:205], v[112:115]
	v_mfma_f32_16x16x32_bf16 v[104:107], v[166:169], v[202:205], v[104:107]
	v_mfma_f32_16x16x32_bf16 v[96:99], v[156:159], v[210:213], v[96:99]
	v_mfma_f32_16x16x32_bf16 v[88:91], v[166:169], v[210:213], v[88:91]
	v_mfma_f32_16x16x32_bf16 v[80:83], v[156:159], v[218:221], v[80:83]
	v_mfma_f32_16x16x32_bf16 v[72:75], v[166:169], v[218:221], v[72:75]
	v_mfma_f32_16x16x32_bf16 v[116:119], v[170:173], v[190:193], v[116:119]
	v_mfma_f32_16x16x32_bf16 v[108:111], v[182:185], v[190:193], v[108:111]
	v_mfma_f32_16x16x32_bf16 v[100:103], v[170:173], v[198:201], v[100:103]
	v_mfma_f32_16x16x32_bf16 v[92:95], v[182:185], v[198:201], v[92:95]
	v_mfma_f32_16x16x32_bf16 v[84:87], v[170:173], v[206:209], v[84:87]
	v_mfma_f32_16x16x32_bf16 v[76:79], v[182:185], v[206:209], v[76:79]
	v_mfma_f32_16x16x32_bf16 v[68:71], v[170:173], v[214:217], v[68:71]
	v_mfma_f32_16x16x32_bf16 v[64:67], v[182:185], v[214:217], v[64:67]
	v_mfma_f32_16x16x32_bf16 v[116:119], v[178:181], v[194:197], v[116:119]
	v_mfma_f32_16x16x32_bf16 v[108:111], v[186:189], v[194:197], v[108:111]
	v_mfma_f32_16x16x32_bf16 v[100:103], v[178:181], v[202:205], v[100:103]
	v_mfma_f32_16x16x32_bf16 v[92:95], v[186:189], v[202:205], v[92:95]
	v_mfma_f32_16x16x32_bf16 v[84:87], v[178:181], v[210:213], v[84:87]
	v_mfma_f32_16x16x32_bf16 v[76:79], v[186:189], v[210:213], v[76:79]
	v_mfma_f32_16x16x32_bf16 v[68:71], v[178:181], v[218:221], v[68:71]
	v_mfma_f32_16x16x32_bf16 v[64:67], v[186:189], v[218:221], v[64:67]
	s_setprio 0
	s_barrier
; #define PG8_STAGE(bufoff, gbase, voff) do { _Pragma("unroll") for (int _i = 0; _i < 2; ++_i) \
;         __builtin_amdgcn_global_load_lds((const unsigned*)((const char*)(gbase) + (voff)[_i]), (PG8_LAS unsigned*)(lds + (bufoff) + ldsw + _i * 8192), 16, 0, 0); } while (0)
; #define PG8_LDA(dst, b, h) do { _Pragma("unroll") for (int m = 0; m < 4; ++m) _Pragma("unroll") for (int k = 0; k < 2; ++k) dst[m][k] = *(const PG8_LAS bf16x8*)(lds + PG8_SA(b, h) + aoff + m * 2048 + k * 1024); } while (0)
; #define PG8_MMA(ai, bj, At, Bt) do { __builtin_amdgcn_s_setprio(1); _Pragma("unroll") for (int m = 0; m < 4; ++m) _Pragma("unroll") for (int n = 0; n < 2; ++n) _Pragma("unroll") for (int k = 0; k < 2; ++k) \
;         acc[ai][bj][m][n] = __builtin_amdgcn_mfma_f32_16x16x32_bf16(Bt[n][k], At[m][k], acc[ai][bj][m][n], 0, 0, 0); __builtin_amdgcn_s_setprio(0); } while (0)
; #define PG8_WAIT_V(n) asm volatile("s_waitcnt vmcnt(" #n ")" ::: "memory")
; #define PG8_WAIT_L(n) asm volatile("s_waitcnt lgkmcnt(" #n ")" ::: "memory")
; #define PG8_BAR __builtin_amdgcn_s_barrier()
; #define PG8_SCHED __builtin_amdgcn_sched_barrier(0)
; template <class Epi, class Sched, bool ALIGN_EPI = false, bool SP2 = false>
; __device__ __forceinline__ void gemm_phase(PG8_LAS unsigned char* lds, const Gemm g, const Sched& S, const Epi& E) {
;     ...
;     for (;;) {
;         const bool has_next = S.next(ui + 1, nxt);
;         const char* nA = has_next ? (const char*)g.A + (size_t)nxt.pm * tstep : cA; const char* nB = has_next ? (const char*)g.Bt + (size_t)nxt.pn * tstep : cB;
;         for (int t = 0; t < nt; t += 2) {
;             const bool last = (t == nt - 2);
;             const char* a1 = cA + (size_t)(t + 1) * kstep;
;             const char* a2 = last ? nA : cA + (size_t)(t + 2) * kstep; const char* b2 = last ? nB : cB + (size_t)(t + 2) * kstep;
;     ...
;             PG8_LDA(At, 1, 1); PG8_STAGE(PG8_SB(1, 0), b3, voffB); PG8_STAGE(PG8_SB(1, 1), b3 + hstep, voffB); PG8_STAGE(PG8_SA(1, 0), a3, voffA);
;             PG8_WAIT_V(8); PG8_WAIT_L(0); PG8_BAR; PG8_MMA(1, 0, At, B0); PG8_MMA(1, 1, At, B1); PG8_BAR; PG8_SCHED;
	s_add_i32 s8, s60, s3
	v_lshl_add_u64 v[174:175], v[174:175], 0, s[6:7]
	s_mov_b32 m0, s8
	ds_read_b128 v[190:193], v154 offset:49152
	ds_read_b128 v[194:197], v154 offset:50176
	ds_read_b128 v[198:201], v154 offset:51200
	ds_read_b128 v[202:205], v154 offset:52224
	ds_read_b128 v[206:209], v154 offset:53248
	ds_read_b128 v[210:213], v154 offset:54272
	ds_read_b128 v[214:217], v154 offset:55296
	ds_read_b128 v[218:221], v154 offset:56320
	global_load_lds_dwordx4 v[174:175], off
	s_add_i32 m0, s8, 0x2000
	s_add_u32 s8, s54, 0x40080
	v_lshl_add_u64 v[174:175], v[222:223], 0, s[6:7]
	s_addc_u32 s9, s55, 0
	s_add_i32 s54, s61, s3
	global_load_lds_dwordx4 v[174:175], off
	v_lshl_add_u64 v[174:175], s[8:9], 0, v[132:133]
	s_mov_b32 m0, s54
	s_nop 0
	global_load_lds_dwordx4 v[174:175], off
	v_lshl_add_u64 v[174:175], s[8:9], 0, v[128:129]
	s_add_i32 m0, s54, 0x2000
	s_nop 0
	global_load_lds_dwordx4 v[174:175], off
	v_lshl_add_u64 v[174:175], v[224:225], 0, s[6:7]
	s_mov_b32 m0, s72
	s_nop 0
	global_load_lds_dwordx4 v[174:175], off
	v_lshl_add_u64 v[174:175], v[226:227], 0, s[6:7]
	s_mov_b32 m0, s73
	s_nop 0
	global_load_lds_dwordx4 v[174:175], off
	s_waitcnt vmcnt(8)
	s_waitcnt lgkmcnt(0)
	s_barrier
	s_setprio 1
	s_waitcnt lgkmcnt(0)
	v_mfma_f32_16x16x32_bf16 v[60:63], v[146:149], v[190:193], v[60:63]
	v_mfma_f32_16x16x32_bf16 v[56:59], v[162:165], v[190:193], v[56:59]
	v_mfma_f32_16x16x32_bf16 v[48:51], v[146:149], v[198:201], v[48:51]
	v_mfma_f32_16x16x32_bf16 v[40:43], v[162:165], v[198:201], v[40:43]
	v_mfma_f32_16x16x32_bf16 v[32:35], v[146:149], v[206:209], v[32:35]
	v_mfma_f32_16x16x32_bf16 v[24:27], v[162:165], v[206:209], v[24:27]
	v_mfma_f32_16x16x32_bf16 v[16:19], v[146:149], v[214:217], v[16:19]
	v_mfma_f32_16x16x32_bf16 v[8:11], v[162:165], v[214:217], v[8:11]
	v_mfma_f32_16x16x32_bf16 v[60:63], v[156:159], v[194:197], v[60:63]
	v_mfma_f32_16x16x32_bf16 v[56:59], v[166:169], v[194:197], v[56:59]
	v_mfma_f32_16x16x32_bf16 v[48:51], v[156:159], v[202:205], v[48:51]
	v_mfma_f32_16x16x32_bf16 v[40:43], v[166:169], v[202:205], v[40:43]
	v_mfma_f32_16x16x32_bf16 v[32:35], v[156:159], v[210:213], v[32:35]
	v_mfma_f32_16x16x32_bf16 v[24:27], v[166:169], v[210:213], v[24:27]
	v_mfma_f32_16x16x32_bf16 v[16:19], v[156:159], v[218:221], v[16:19]
	v_mfma_f32_16x16x32_bf16 v[8:11], v[166:169], v[218:221], v[8:11]
	v_mfma_f32_16x16x32_bf16 v[52:55], v[170:173], v[190:193], v[52:55]
	v_mfma_f32_16x16x32_bf16 v[44:47], v[182:185], v[190:193], v[44:47]
	v_mfma_f32_16x16x32_bf16 v[36:39], v[170:173], v[198:201], v[36:39]
	v_mfma_f32_16x16x32_bf16 v[28:31], v[182:185], v[198:201], v[28:31]
	v_mfma_f32_16x16x32_bf16 v[20:23], v[170:173], v[206:209], v[20:23]
	v_mfma_f32_16x16x32_bf16 v[12:15], v[182:185], v[206:209], v[12:15]
	v_mfma_f32_16x16x32_bf16 v[4:7], v[170:173], v[214:217], v[4:7]
	v_mfma_f32_16x16x32_bf16 v[0:3], v[182:185], v[214:217], v[0:3]
	v_mfma_f32_16x16x32_bf16 v[52:55], v[178:181], v[194:197], v[52:55]
	v_mfma_f32_16x16x32_bf16 v[44:47], v[186:189], v[194:197], v[44:47]
	v_mfma_f32_16x16x32_bf16 v[36:39], v[178:181], v[202:205], v[36:39]
	v_mfma_f32_16x16x32_bf16 v[28:31], v[186:189], v[202:205], v[28:31]
	v_mfma_f32_16x16x32_bf16 v[20:23], v[178:181], v[210:213], v[20:23]
	v_mfma_f32_16x16x32_bf16 v[12:15], v[186:189], v[210:213], v[12:15]
	v_mfma_f32_16x16x32_bf16 v[4:7], v[178:181], v[218:221], v[4:7]
	v_mfma_f32_16x16x32_bf16 v[0:3], v[186:189], v[218:221], v[0:3]
	s_setprio 0
	s_add_i32 s86, s86, 2
	s_add_u32 s52, s52, 0x100
	s_addc_u32 s53, s53, 0
	s_add_u32 s82, s82, 0x100
	s_addc_u32 s83, s83, 0
	s_cmp_gt_u32 s86, 13
	s_barrier
	s_cbranch_scc0 .LBB0_179
	s_and_b64 vcc, exec, s[16:17]
	s_cbranch_vccz .LBB0_182
	s_barrier

; #define PG8_STAGE(bufoff, gbase, voff) do { _Pragma("unroll") for (int _i = 0; _i < 2; ++_i) \
;         __builtin_amdgcn_global_load_lds((const unsigned*)((const char*)(gbase) + (voff)[_i]), (PG8_LAS unsigned*)(lds + (bufoff) + ldsw + _i * 8192), 16, 0, 0); } while (0)
; #define PG8_LDA(dst, b, h) do { _Pragma("unroll") for (int m = 0; m < 4; ++m) _Pragma("unroll") for (int k = 0; k < 2; ++k) dst[m][k] = *(const PG8_LAS bf16x8*)(lds + PG8_SA(b, h) + aoff + m * 2048 + k * 1024); } while (0)
; #define PG8_LDB(dst, b, h) do { _Pragma("unroll") for (int n = 0; n < 2; ++n) _Pragma("unroll") for (int k = 0; k < 2; ++k) dst[n][k] = *(const PG8_LAS bf16x8*)(lds + PG8_SB(b, h) + boff + n * 2048 + k * 1024); } while (0)
; #define PG8_MMA(ai, bj, At, Bt) do { __builtin_amdgcn_s_setprio(1); _Pragma("unroll") for (int m = 0; m < 4; ++m) _Pragma("unroll") for (int n = 0; n < 2; ++n) _Pragma("unroll") for (int k = 0; k < 2; ++k) \
;         acc[ai][bj][m][n] = __builtin_amdgcn_mfma_f32_16x16x32_bf16(Bt[n][k], At[m][k], acc[ai][bj][m][n], 0, 0, 0); __builtin_amdgcn_s_setprio(0); } while (0)
; #define PG8_WAIT_V(n) asm volatile("s_waitcnt vmcnt(" #n ")" ::: "memory")
; #define PG8_WAIT_L(n) asm volatile("s_waitcnt lgkmcnt(" #n ")" ::: "memory")
; #define PG8_BAR __builtin_amdgcn_s_barrier()
; #define PG8_SCHED __builtin_amdgcn_sched_barrier(0)
; template <class Epi, class Sched, bool ALIGN_EPI = false, bool SP2 = false>
; __device__ __forceinline__ void gemm_phase(PG8_LAS unsigned char* lds, const Gemm g, const Sched& S, const Epi& E) {
;     ...
;             PG8_LDB(B0, 0, 0); PG8_LDB(B1, 0, 1); PG8_SCHED; PG8_LDA(At, 0, 0); PG8_STAGE(PG8_SA(1, 1), a1 + hstep, voffA);
;             PG8_WAIT_V(8); PG8_WAIT_L(0); PG8_BAR; PG8_MMA(0, 0, At, B0); PG8_MMA(0, 1, At, B1); PG8_BAR; PG8_SCHED;
;             PG8_LDA(At, 0, 1); PG8_STAGE(PG8_SB(0, 0), b2, voffB); PG8_STAGE(PG8_SB(0, 1), b2 + hstep, voffB); PG8_STAGE(PG8_SA(0, 0), a2, voffA);
;             PG8_WAIT_V(8); PG8_WAIT_L(0); PG8_BAR; PG8_MMA(1, 0, At, B0); PG8_MMA(1, 1, At, B1); PG8_BAR; PG8_SCHED;
.LBB0_375:
	ds_read_b128 v[154:157], v150
	ds_read_b128 v[162:165], v150 offset:1024
	ds_read_b128 v[166:169], v150 offset:2048
	ds_read_b128 v[170:173], v150 offset:3072
	ds_read_b128 v[178:181], v151
	ds_read_b128 v[182:185], v151 offset:1024
	ds_read_b128 v[186:189], v151 offset:2048
	ds_read_b128 v[190:193], v151 offset:3072
	s_add_u32 s8, s68, 0xfffc0080
	s_addc_u32 s9, s69, -1
	s_cmp_eq_u32 s97, 12
	s_cselect_b32 s73, s53, s9
	s_cselect_b32 s72, s93, s8
	s_cselect_b32 s71, s51, s96
	s_cselect_b32 s70, s94, s95
	v_lshl_add_u64 v[146:147], s[68:69], 0, v[136:137]
	s_add_i32 m0, s67, 0xc000
	ds_read_b128 v[194:197], v152
	ds_read_b128 v[198:201], v152 offset:1024
	ds_read_b128 v[202:205], v152 offset:2048
	ds_read_b128 v[206:209], v152 offset:3072
	ds_read_b128 v[210:213], v152 offset:4096
	ds_read_b128 v[214:217], v152 offset:5120
	ds_read_b128 v[218:221], v152 offset:6144
	ds_read_b128 v[222:225], v152 offset:7168
	global_load_lds_dwordx4 v[146:147], off
	v_lshl_add_u64 v[146:147], s[68:69], 0, v[138:139]
	s_add_i32 m0, s67, 0xe000
	s_nop 0
	global_load_lds_dwordx4 v[146:147], off
	s_waitcnt vmcnt(8)
	s_waitcnt lgkmcnt(0)
	s_barrier
	s_setprio 1
	s_waitcnt lgkmcnt(0)
	v_mfma_f32_16x16x32_bf16 v[124:127], v[154:157], v[194:197], v[124:127]
	v_mfma_f32_16x16x32_bf16 v[120:123], v[166:169], v[194:197], v[120:123]
	v_mfma_f32_16x16x32_bf16 v[112:115], v[154:157], v[202:205], v[112:115]
	v_mfma_f32_16x16x32_bf16 v[104:107], v[166:169], v[202:205], v[104:107]
	v_mfma_f32_16x16x32_bf16 v[96:99], v[154:157], v[210:213], v[96:99]
	v_mfma_f32_16x16x32_bf16 v[88:91], v[166:169], v[210:213], v[88:91]
	v_mfma_f32_16x16x32_bf16 v[80:83], v[154:157], v[218:221], v[80:83]
	v_mfma_f32_16x16x32_bf16 v[72:75], v[166:169], v[218:221], v[72:75]
	v_mfma_f32_16x16x32_bf16 v[124:127], v[162:165], v[198:201], v[124:127]
	v_mfma_f32_16x16x32_bf16 v[120:123], v[170:173], v[198:201], v[120:123]
	v_mfma_f32_16x16x32_bf16 v[112:115], v[162:165], v[206:209], v[112:115]
	v_mfma_f32_16x16x32_bf16 v[104:107], v[170:173], v[206:209], v[104:107]
	v_mfma_f32_16x16x32_bf16 v[96:99], v[162:165], v[214:217], v[96:99]
	v_mfma_f32_16x16x32_bf16 v[88:91], v[170:173], v[214:217], v[88:91]
	v_mfma_f32_16x16x32_bf16 v[80:83], v[162:165], v[222:225], v[80:83]
	v_mfma_f32_16x16x32_bf16 v[72:75], v[170:173], v[222:225], v[72:75]
	v_mfma_f32_16x16x32_bf16 v[116:119], v[178:181], v[194:197], v[116:119]
	v_mfma_f32_16x16x32_bf16 v[108:111], v[186:189], v[194:197], v[108:111]
	v_mfma_f32_16x16x32_bf16 v[100:103], v[178:181], v[202:205], v[100:103]
	v_mfma_f32_16x16x32_bf16 v[92:95], v[186:189], v[202:205], v[92:95]
	v_mfma_f32_16x16x32_bf16 v[84:87], v[178:181], v[210:213], v[84:87]
	v_mfma_f32_16x16x32_bf16 v[76:79], v[186:189], v[210:213], v[76:79]
	v_mfma_f32_16x16x32_bf16 v[68:71], v[178:181], v[218:221], v[68:71]
	v_mfma_f32_16x16x32_bf16 v[64:67], v[186:189], v[218:221], v[64:67]
	v_mfma_f32_16x16x32_bf16 v[116:119], v[182:185], v[198:201], v[116:119]
	v_mfma_f32_16x16x32_bf16 v[108:111], v[190:193], v[198:201], v[108:111]
	v_mfma_f32_16x16x32_bf16 v[100:103], v[182:185], v[206:209], v[100:103]
	v_mfma_f32_16x16x32_bf16 v[92:95], v[190:193], v[206:209], v[92:95]
	v_mfma_f32_16x16x32_bf16 v[84:87], v[182:185], v[214:217], v[84:87]
	v_mfma_f32_16x16x32_bf16 v[76:79], v[190:193], v[214:217], v[76:79]
	v_mfma_f32_16x16x32_bf16 v[68:71], v[182:185], v[222:225], v[68:71]
	v_mfma_f32_16x16x32_bf16 v[64:67], v[190:193], v[222:225], v[64:67]
	s_setprio 0
	s_barrier
	s_add_i32 s8, s86, s75
	v_lshl_add_u64 v[146:147], s[70:71], 0, v[130:131]
	s_mov_b32 m0, s8
	ds_read_b128 v[194:197], v152 offset:16384
	ds_read_b128 v[198:201], v152 offset:17408
	ds_read_b128 v[202:205], v152 offset:18432
	ds_read_b128 v[206:209], v152 offset:19456
	ds_read_b128 v[210:213], v152 offset:20480
	ds_read_b128 v[214:217], v152 offset:21504
	ds_read_b128 v[218:221], v152 offset:22528
	ds_read_b128 v[222:225], v152 offset:23552
	global_load_lds_dwordx4 v[146:147], off
	s_add_i32 m0, s8, 0x2000
	s_add_u32 s8, s70, 0x40000
	v_lshl_add_u64 v[158:159], s[70:71], 0, v[134:135]
	s_addc_u32 s9, s71, 0
	s_add_i32 s60, s87, s75
	global_load_lds_dwordx4 v[158:159], off
	v_lshl_add_u64 v[174:175], s[8:9], 0, v[130:131]
	s_mov_b32 m0, s60
	v_lshl_add_u64 v[226:227], s[72:73], 0, v[132:133]
	global_load_lds_dwordx4 v[174:175], off
	v_lshl_add_u64 v[174:175], s[8:9], 0, v[134:135]
	s_add_i32 m0, s60, 0x2000
	s_nop 0
	global_load_lds_dwordx4 v[174:175], off
	v_lshl_add_u64 v[174:175], s[72:73], 0, v[128:129]
	s_mov_b32 m0, s67
	s_nop 0
	global_load_lds_dwordx4 v[174:175], off
	s_mov_b32 m0, s76
	s_nop 0
	global_load_lds_dwordx4 v[226:227], off
	s_waitcnt vmcnt(8)
	s_waitcnt lgkmcnt(0)
	s_barrier
; #define PG8_STAGE(bufoff, gbase, voff) do { _Pragma("unroll") for (int _i = 0; _i < 2; ++_i) \
;         __builtin_amdgcn_global_load_lds((const unsigned*)((const char*)(gbase) + (voff)[_i]), (PG8_LAS unsigned*)(lds + (bufoff) + ldsw + _i * 8192), 16, 0, 0); } while (0)
; #define PG8_LDA(dst, b, h) do { _Pragma("unroll") for (int m = 0; m < 4; ++m) _Pragma("unroll") for (int k = 0; k < 2; ++k) dst[m][k] = *(const PG8_LAS bf16x8*)(lds + PG8_SA(b, h) + aoff + m * 2048 + k * 1024); } while (0)
; #define PG8_LDB(dst, b, h) do { _Pragma("unroll") for (int n = 0; n < 2; ++n) _Pragma("unroll") for (int k = 0; k < 2; ++k) dst[n][k] = *(const PG8_LAS bf16x8*)(lds + PG8_SB(b, h) + boff + n * 2048 + k * 1024); } while (0)
; #define PG8_MMA(ai, bj, At, Bt) do { __builtin_amdgcn_s_setprio(1); _Pragma("unroll") for (int m = 0; m < 4; ++m) _Pragma("unroll") for (int n = 0; n < 2; ++n) _Pragma("unroll") for (int k = 0; k < 2; ++k) \
;         acc[ai][bj][m][n] = __builtin_amdgcn_mfma_f32_16x16x32_bf16(Bt[n][k], At[m][k], acc[ai][bj][m][n], 0, 0, 0); __builtin_amdgcn_s_setprio(0); } while (0)
; #define PG8_WAIT_V(n) asm volatile("s_waitcnt vmcnt(" #n ")" ::: "memory")
; #define PG8_WAIT_L(n) asm volatile("s_waitcnt lgkmcnt(" #n ")" ::: "memory")
; #define PG8_BAR __builtin_amdgcn_s_barrier()
; #define PG8_SCHED __builtin_amdgcn_sched_barrier(0)
; template <class Epi, class Sched, bool ALIGN_EPI = false, bool SP2 = false>
; __device__ __forceinline__ void gemm_phase(PG8_LAS unsigned char* lds, const Gemm g, const Sched& S, const Epi& E) {
;     ...
;             PG8_WAIT_V(8); PG8_WAIT_L(0); PG8_BAR; PG8_MMA(1, 0, At, B0); PG8_MMA(1, 1, At, B1); PG8_BAR; PG8_SCHED;
;             PG8_LDB(B0, 1, 0); PG8_LDB(B1, 1, 1); PG8_SCHED; PG8_LDA(At, 1, 0); PG8_STAGE(PG8_SA(0, 1), a2 + hstep, voffA);
;             PG8_WAIT_V(8); PG8_WAIT_L(0); PG8_BAR; PG8_MMA(0, 0, At, B0); PG8_MMA(0, 1, At, B1); PG8_BAR; PG8_SCHED;
	s_setprio 1
	s_waitcnt lgkmcnt(0)
	v_mfma_f32_16x16x32_bf16 v[60:63], v[154:157], v[194:197], v[60:63]
	v_mfma_f32_16x16x32_bf16 v[56:59], v[166:169], v[194:197], v[56:59]
	v_mfma_f32_16x16x32_bf16 v[48:51], v[154:157], v[202:205], v[48:51]
	v_mfma_f32_16x16x32_bf16 v[40:43], v[166:169], v[202:205], v[40:43]
	v_mfma_f32_16x16x32_bf16 v[32:35], v[154:157], v[210:213], v[32:35]
	v_mfma_f32_16x16x32_bf16 v[24:27], v[166:169], v[210:213], v[24:27]
	v_mfma_f32_16x16x32_bf16 v[16:19], v[154:157], v[218:221], v[16:19]
	v_mfma_f32_16x16x32_bf16 v[8:11], v[166:169], v[218:221], v[8:11]
	v_mfma_f32_16x16x32_bf16 v[60:63], v[162:165], v[198:201], v[60:63]
	v_mfma_f32_16x16x32_bf16 v[56:59], v[170:173], v[198:201], v[56:59]
	v_mfma_f32_16x16x32_bf16 v[48:51], v[162:165], v[206:209], v[48:51]
	v_mfma_f32_16x16x32_bf16 v[40:43], v[170:173], v[206:209], v[40:43]
	v_mfma_f32_16x16x32_bf16 v[32:35], v[162:165], v[214:217], v[32:35]
	v_mfma_f32_16x16x32_bf16 v[24:27], v[170:173], v[214:217], v[24:27]
	v_mfma_f32_16x16x32_bf16 v[16:19], v[162:165], v[222:225], v[16:19]
	v_mfma_f32_16x16x32_bf16 v[8:11], v[170:173], v[222:225], v[8:11]
	v_mfma_f32_16x16x32_bf16 v[52:55], v[178:181], v[194:197], v[52:55]
	v_mfma_f32_16x16x32_bf16 v[44:47], v[186:189], v[194:197], v[44:47]
	v_mfma_f32_16x16x32_bf16 v[36:39], v[178:181], v[202:205], v[36:39]
	v_mfma_f32_16x16x32_bf16 v[28:31], v[186:189], v[202:205], v[28:31]
	v_mfma_f32_16x16x32_bf16 v[20:23], v[178:181], v[210:213], v[20:23]
	v_mfma_f32_16x16x32_bf16 v[12:15], v[186:189], v[210:213], v[12:15]
	v_mfma_f32_16x16x32_bf16 v[4:7], v[178:181], v[218:221], v[4:7]
	v_mfma_f32_16x16x32_bf16 v[0:3], v[186:189], v[218:221], v[0:3]
	v_mfma_f32_16x16x32_bf16 v[52:55], v[182:185], v[198:201], v[52:55]
	v_mfma_f32_16x16x32_bf16 v[44:47], v[190:193], v[198:201], v[44:47]
	v_mfma_f32_16x16x32_bf16 v[36:39], v[182:185], v[206:209], v[36:39]
	v_mfma_f32_16x16x32_bf16 v[28:31], v[190:193], v[206:209], v[28:31]
	v_mfma_f32_16x16x32_bf16 v[20:23], v[182:185], v[214:217], v[20:23]
	v_mfma_f32_16x16x32_bf16 v[12:15], v[190:193], v[214:217], v[12:15]
	v_mfma_f32_16x16x32_bf16 v[4:7], v[182:185], v[222:225], v[4:7]
	v_mfma_f32_16x16x32_bf16 v[0:3], v[190:193], v[222:225], v[0:3]
	s_setprio 0
	s_barrier
	s_add_i32 s60, 0, 0x18000
	v_add_u32_e32 v144, s60, v148
	s_add_i32 s61, 0, 0x1c000
	ds_read_b128 v[154:157], v144
	ds_read_b128 v[162:165], v144 offset:1024
	ds_read_b128 v[166:169], v144 offset:2048
	ds_read_b128 v[170:173], v144 offset:3072
	v_add_u32_e32 v144, s61, v148
	ds_read_b128 v[178:181], v144
	ds_read_b128 v[182:185], v144 offset:1024
	ds_read_b128 v[186:189], v144 offset:2048
	ds_read_b128 v[190:193], v144 offset:3072
	s_add_u32 s8, s72, 0x40000
	s_addc_u32 s9, s73, 0
	s_mov_b32 m0, s77
	v_lshl_add_u64 v[228:229], s[8:9], 0, v[128:129]
	ds_read_b128 v[194:197], v152 offset:32768
	ds_read_b128 v[198:201], v152 offset:33792
	ds_read_b128 v[202:205], v152 offset:34816
	ds_read_b128 v[206:209], v152 offset:35840
	ds_read_b128 v[210:213], v152 offset:36864
	ds_read_b128 v[214:217], v152 offset:37888
	ds_read_b128 v[218:221], v152 offset:38912
	ds_read_b128 v[222:225], v152 offset:39936
	global_load_lds_dwordx4 v[228:229], off
	v_lshl_add_u64 v[228:229], s[8:9], 0, v[132:133]
	s_mov_b32 m0, s78
	s_nop 0
	global_load_lds_dwordx4 v[228:229], off
	s_waitcnt vmcnt(8)
	s_waitcnt lgkmcnt(0)
	s_barrier
	s_setprio 1
	s_waitcnt lgkmcnt(0)
	v_mfma_f32_16x16x32_bf16 v[124:127], v[154:157], v[194:197], v[124:127]
	v_mfma_f32_16x16x32_bf16 v[120:123], v[166:169], v[194:197], v[120:123]
	v_mfma_f32_16x16x32_bf16 v[112:115], v[154:157], v[202:205], v[112:115]
	v_mfma_f32_16x16x32_bf16 v[104:107], v[166:169], v[202:205], v[104:107]
	v_mfma_f32_16x16x32_bf16 v[96:99], v[154:157], v[210:213], v[96:99]
	v_mfma_f32_16x16x32_bf16 v[88:91], v[166:169], v[210:213], v[88:91]
	v_mfma_f32_16x16x32_bf16 v[80:83], v[154:157], v[218:221], v[80:83]
	v_mfma_f32_16x16x32_bf16 v[72:75], v[166:169], v[218:221], v[72:75]
	v_mfma_f32_16x16x32_bf16 v[124:127], v[162:165], v[198:201], v[124:127]
	v_mfma_f32_16x16x32_bf16 v[120:123], v[170:173], v[198:201], v[120:123]
	v_mfma_f32_16x16x32_bf16 v[112:115], v[162:165], v[206:209], v[112:115]
	v_mfma_f32_16x16x32_bf16 v[104:107], v[170:173], v[206:209], v[104:107]
	v_mfma_f32_16x16x32_bf16 v[96:99], v[162:165], v[214:217], v[96:99]
	v_mfma_f32_16x16x32_bf16 v[88:91], v[170:173], v[214:217], v[88:91]
	v_mfma_f32_16x16x32_bf16 v[80:83], v[162:165], v[222:225], v[80:83]
	v_mfma_f32_16x16x32_bf16 v[72:75], v[170:173], v[222:225], v[72:75]
	v_mfma_f32_16x16x32_bf16 v[116:119], v[178:181], v[194:197], v[116:119]
	v_mfma_f32_16x16x32_bf16 v[108:111], v[186:189], v[194:197], v[108:111]
	v_mfma_f32_16x16x32_bf16 v[100:103], v[178:181], v[202:205], v[100:103]
	v_mfma_f32_16x16x32_bf16 v[92:95], v[186:189], v[202:205], v[92:95]
	v_mfma_f32_16x16x32_bf16 v[84:87], v[178:181], v[210:213], v[84:87]
	v_mfma_f32_16x16x32_bf16 v[76:79], v[186:189], v[210:213], v[76:79]
	v_mfma_f32_16x16x32_bf16 v[68:71], v[178:181], v[218:221], v[68:71]
	v_mfma_f32_16x16x32_bf16 v[64:67], v[186:189], v[218:221], v[64:67]
	v_mfma_f32_16x16x32_bf16 v[116:119], v[182:185], v[198:201], v[116:119]
	v_mfma_f32_16x16x32_bf16 v[108:111], v[190:193], v[198:201], v[108:111]
	v_mfma_f32_16x16x32_bf16 v[100:103], v[182:185], v[206:209], v[100:103]
	v_mfma_f32_16x16x32_bf16 v[92:95], v[190:193], v[206:209], v[92:95]
	v_mfma_f32_16x16x32_bf16 v[84:87], v[182:185], v[214:217], v[84:87]
	v_mfma_f32_16x16x32_bf16 v[76:79], v[190:193], v[214:217], v[76:79]
	v_mfma_f32_16x16x32_bf16 v[68:71], v[182:185], v[222:225], v[68:71]
	v_mfma_f32_16x16x32_bf16 v[64:67], v[190:193], v[222:225], v[64:67]
	s_setprio 0
	s_barrier
; #define PG8_STAGE(bufoff, gbase, voff) do { _Pragma("unroll") for (int _i = 0; _i < 2; ++_i) \
;         __builtin_amdgcn_global_load_lds((const unsigned*)((const char*)(gbase) + (voff)[_i]), (PG8_LAS unsigned*)(lds + (bufoff) + ldsw + _i * 8192), 16, 0, 0); } while (0)
; #define PG8_LDA(dst, b, h) do { _Pragma("unroll") for (int m = 0; m < 4; ++m) _Pragma("unroll") for (int k = 0; k < 2; ++k) dst[m][k] = *(const PG8_LAS bf16x8*)(lds + PG8_SA(b, h) + aoff + m * 2048 + k * 1024); } while (0)
; #define PG8_MMA(ai, bj, At, Bt) do { __builtin_amdgcn_s_setprio(1); _Pragma("unroll") for (int m = 0; m < 4; ++m) _Pragma("unroll") for (int n = 0; n < 2; ++n) _Pragma("unroll") for (int k = 0; k < 2; ++k) \
;         acc[ai][bj][m][n] = __builtin_amdgcn_mfma_f32_16x16x32_bf16(Bt[n][k], At[m][k], acc[ai][bj][m][n], 0, 0, 0); __builtin_amdgcn_s_setprio(0); } while (0)
; #define PG8_WAIT_V(n) asm volatile("s_waitcnt vmcnt(" #n ")" ::: "memory")
; #define PG8_WAIT_L(n) asm volatile("s_waitcnt lgkmcnt(" #n ")" ::: "memory")
; #define PG8_BAR __builtin_amdgcn_s_barrier()
; #define PG8_SCHED __builtin_amdgcn_sched_barrier(0)
; template <class Epi, class Sched, bool ALIGN_EPI = false, bool SP2 = false>
; __device__ __forceinline__ void gemm_phase(PG8_LAS unsigned char* lds, const Gemm g, const Sched& S, const Epi& E) {
;     ...
;     for (;;) {
;         const bool has_next = S.next(ui + 1, nxt);
;         const char* nA = has_next ? (const char*)g.A + (size_t)nxt.pm * tstep : cA; const char* nB = has_next ? (const char*)g.Bt + (size_t)nxt.pn * tstep : cB;
;         for (int t = 0; t < nt; t += 2) {
;             const bool last = (t == nt - 2);
;             const char* a1 = cA + (size_t)(t + 1) * kstep;
;             const char* a2 = last ? nA : cA + (size_t)(t + 2) * kstep; const char* b2 = last ? nB : cB + (size_t)(t + 2) * kstep;
;     ...
;             PG8_LDA(At, 1, 1); PG8_STAGE(PG8_SB(1, 0), b3, voffB); PG8_STAGE(PG8_SB(1, 1), b3 + hstep, voffB); PG8_STAGE(PG8_SA(1, 0), a3, voffA);
;             PG8_WAIT_V(8); PG8_WAIT_L(0); PG8_BAR; PG8_MMA(1, 0, At, B0); PG8_MMA(1, 1, At, B1); PG8_BAR; PG8_SCHED;
	s_add_i32 s8, s60, s75
	v_lshl_add_u64 v[146:147], v[146:147], 0, s[16:17]
	s_mov_b32 m0, s8
	ds_read_b128 v[194:197], v152 offset:49152
	ds_read_b128 v[198:201], v152 offset:50176
	ds_read_b128 v[202:205], v152 offset:51200
	ds_read_b128 v[206:209], v152 offset:52224
	ds_read_b128 v[210:213], v152 offset:53248
	ds_read_b128 v[214:217], v152 offset:54272
	ds_read_b128 v[218:221], v152 offset:55296
	ds_read_b128 v[222:225], v152 offset:56320
	global_load_lds_dwordx4 v[146:147], off
	s_add_i32 m0, s8, 0x2000
	s_add_u32 s8, s70, 0x40080
	v_lshl_add_u64 v[146:147], v[158:159], 0, s[16:17]
	s_addc_u32 s9, s71, 0
	s_add_i32 s60, s61, s75
	global_load_lds_dwordx4 v[146:147], off
	v_lshl_add_u64 v[146:147], s[8:9], 0, v[130:131]
	s_mov_b32 m0, s60
	s_nop 0
	global_load_lds_dwordx4 v[146:147], off
	v_lshl_add_u64 v[146:147], s[8:9], 0, v[134:135]
	s_add_i32 m0, s60, 0x2000
	s_nop 0
	global_load_lds_dwordx4 v[146:147], off
	v_lshl_add_u64 v[146:147], v[174:175], 0, s[16:17]
	s_mov_b32 m0, s80
	s_nop 0
	global_load_lds_dwordx4 v[146:147], off
	v_lshl_add_u64 v[146:147], v[226:227], 0, s[16:17]
	s_mov_b32 m0, s81
	s_nop 0
	global_load_lds_dwordx4 v[146:147], off
	s_waitcnt vmcnt(8)
	s_waitcnt lgkmcnt(0)
	s_barrier
	s_setprio 1
	s_waitcnt lgkmcnt(0)
	v_mfma_f32_16x16x32_bf16 v[60:63], v[154:157], v[194:197], v[60:63]
	v_mfma_f32_16x16x32_bf16 v[56:59], v[166:169], v[194:197], v[56:59]
	v_mfma_f32_16x16x32_bf16 v[48:51], v[154:157], v[202:205], v[48:51]
	v_mfma_f32_16x16x32_bf16 v[40:43], v[166:169], v[202:205], v[40:43]
	v_mfma_f32_16x16x32_bf16 v[32:35], v[154:157], v[210:213], v[32:35]
	v_mfma_f32_16x16x32_bf16 v[24:27], v[166:169], v[210:213], v[24:27]
	v_mfma_f32_16x16x32_bf16 v[16:19], v[154:157], v[218:221], v[16:19]
	v_mfma_f32_16x16x32_bf16 v[8:11], v[166:169], v[218:221], v[8:11]
	v_mfma_f32_16x16x32_bf16 v[60:63], v[162:165], v[198:201], v[60:63]
	v_mfma_f32_16x16x32_bf16 v[56:59], v[170:173], v[198:201], v[56:59]
	v_mfma_f32_16x16x32_bf16 v[48:51], v[162:165], v[206:209], v[48:51]
	v_mfma_f32_16x16x32_bf16 v[40:43], v[170:173], v[206:209], v[40:43]
	v_mfma_f32_16x16x32_bf16 v[32:35], v[162:165], v[214:217], v[32:35]
	v_mfma_f32_16x16x32_bf16 v[24:27], v[170:173], v[214:217], v[24:27]
	v_mfma_f32_16x16x32_bf16 v[16:19], v[162:165], v[222:225], v[16:19]
	v_mfma_f32_16x16x32_bf16 v[8:11], v[170:173], v[222:225], v[8:11]
	v_mfma_f32_16x16x32_bf16 v[52:55], v[178:181], v[194:197], v[52:55]
	v_mfma_f32_16x16x32_bf16 v[44:47], v[186:189], v[194:197], v[44:47]
	v_mfma_f32_16x16x32_bf16 v[36:39], v[178:181], v[202:205], v[36:39]
	v_mfma_f32_16x16x32_bf16 v[28:31], v[186:189], v[202:205], v[28:31]
	v_mfma_f32_16x16x32_bf16 v[20:23], v[178:181], v[210:213], v[20:23]
	v_mfma_f32_16x16x32_bf16 v[12:15], v[186:189], v[210:213], v[12:15]
	v_mfma_f32_16x16x32_bf16 v[4:7], v[178:181], v[218:221], v[4:7]
	v_mfma_f32_16x16x32_bf16 v[0:3], v[186:189], v[218:221], v[0:3]
	v_mfma_f32_16x16x32_bf16 v[52:55], v[182:185], v[198:201], v[52:55]
	v_mfma_f32_16x16x32_bf16 v[44:47], v[190:193], v[198:201], v[44:47]
	v_mfma_f32_16x16x32_bf16 v[36:39], v[182:185], v[206:209], v[36:39]
	v_mfma_f32_16x16x32_bf16 v[28:31], v[190:193], v[206:209], v[28:31]
	v_mfma_f32_16x16x32_bf16 v[20:23], v[182:185], v[214:217], v[20:23]
	v_mfma_f32_16x16x32_bf16 v[12:15], v[190:193], v[214:217], v[12:15]
	v_mfma_f32_16x16x32_bf16 v[4:7], v[182:185], v[222:225], v[4:7]
	v_mfma_f32_16x16x32_bf16 v[0:3], v[190:193], v[222:225], v[0:3]
	s_setprio 0
	s_add_i32 s97, s97, 2
	s_add_u32 s68, s68, 0x100
	s_addc_u32 s69, s69, 0
	s_add_u32 s95, s95, 0x100
	s_addc_u32 s96, s96, 0
	s_cmp_gt_u32 s97, 13
	s_barrier
	s_cbranch_scc0 .LBB0_375
	s_and_b64 vcc, exec, s[18:19]
	s_cbranch_vccz .LBB0_378
	s_barrier

; #define PG8_STAGE(bufoff, gbase, voff) do { _Pragma("unroll") for (int _i = 0; _i < 2; ++_i) \
;         __builtin_amdgcn_global_load_lds((const unsigned*)((const char*)(gbase) + (voff)[_i]), (PG8_LAS unsigned*)(lds + (bufoff) + ldsw + _i * 8192), 16, 0, 0); } while (0)
; #define PG8_LDA(dst, b, h) do { _Pragma("unroll") for (int m = 0; m < 4; ++m) _Pragma("unroll") for (int k = 0; k < 2; ++k) dst[m][k] = *(const PG8_LAS bf16x8*)(lds + PG8_SA(b, h) + aoff + m * 2048 + k * 1024); } while (0)
; #define PG8_LDB(dst, b, h) do { _Pragma("unroll") for (int n = 0; n < 2; ++n) _Pragma("unroll") for (int k = 0; k < 2; ++k) dst[n][k] = *(const PG8_LAS bf16x8*)(lds + PG8_SB(b, h) + boff + n * 2048 + k * 1024); } while (0)
; #define PG8_MMA(ai, bj, At, Bt) do { __builtin_amdgcn_s_setprio(1); _Pragma("unroll") for (int m = 0; m < 4; ++m) _Pragma("unroll") for (int n = 0; n < 2; ++n) _Pragma("unroll") for (int k = 0; k < 2; ++k) \
;         acc[ai][bj][m][n] = __builtin_amdgcn_mfma_f32_16x16x32_bf16(Bt[n][k], At[m][k], acc[ai][bj][m][n], 0, 0, 0); __builtin_amdgcn_s_setprio(0); } while (0)
; #define PG8_WAIT_V(n) asm volatile("s_waitcnt vmcnt(" #n ")" ::: "memory")
; template <class Epi, class Sched, bool ALIGN_EPI = false, bool SP2 = false>
; __device__ __forceinline__ void gemm_phase(PG8_LAS unsigned char* lds, const Gemm g, const Sched& S, const Epi& E) {
;     ...
;         const char* nA = has_next ? (const char*)g.A + (size_t)nxt.pm * tstep : cA; const char* nB = has_next ? (const char*)g.Bt + (size_t)nxt.pn * tstep : cB;
;         for (int t = 0; t < nt; t += 2) {
;             const bool last = (t == nt - 2);
;             const char* a1 = cA + (size_t)(t + 1) * kstep;
;             const char* a2 = last ? nA : cA + (size_t)(t + 2) * kstep; const char* b2 = last ? nB : cB + (size_t)(t + 2) * kstep;
;             const char* a3 = a2 + kstep; const char* b3 = b2 + kstep;
;             if (last && has_next) S.a_ready(nxt);
;             if constexpr (SP2) {
;             PG8_LDB(B0, 0, 0); PG8_LDB(B1, 0, 1); PG8_SCHED; PG8_LDA(At, 0, 0); PG8_STAGE(PG8_SA(1, 1), a1 + hstep, voffA);
;             PG8_WAIT_V(8); PG8_WAIT_L(0); PG8_BAR; PG8_MMA(0, 0, At, B0); PG8_MMA(0, 1, At, B1); PG8_BAR; PG8_SCHED;
;             PG8_LDA(At, 0, 1); PG8_STAGE(PG8_SB(0, 0), b2, voffB); PG8_STAGE(PG8_SB(0, 1), b2 + hstep, voffB); PG8_STAGE(PG8_SA(0, 0), a2, voffA);
.LBB0_557:
	ds_read_b128 v[152:155], v149
	ds_read_b128 v[156:159], v149 offset:1024
	ds_read_b128 v[162:165], v149 offset:2048
	ds_read_b128 v[166:169], v149 offset:3072
	ds_read_b128 v[170:173], v150
	ds_read_b128 v[178:181], v150 offset:1024
	ds_read_b128 v[182:185], v150 offset:2048
	ds_read_b128 v[186:189], v150 offset:3072
	s_add_u32 s8, s50, 0xfffc0080
	s_addc_u32 s9, s51, -1
	s_cmp_eq_u32 s83, 12
	s_cselect_b32 s55, s19, s9
	s_cselect_b32 s54, s79, s8
	s_cselect_b32 s53, s15, s82
	s_cselect_b32 s52, s80, s81
	v_lshl_add_u64 v[144:145], s[50:51], 0, v[136:137]
	s_add_i32 m0, s49, 0xc000
	ds_read_b128 v[190:193], v151
	ds_read_b128 v[194:197], v151 offset:1024
	ds_read_b128 v[198:201], v151 offset:2048
	ds_read_b128 v[202:205], v151 offset:3072
	ds_read_b128 v[206:209], v151 offset:4096
	ds_read_b128 v[210:213], v151 offset:5120
	ds_read_b128 v[214:217], v151 offset:6144
	ds_read_b128 v[218:221], v151 offset:7168
	global_load_lds_dwordx4 v[144:145], off
	v_lshl_add_u64 v[144:145], s[50:51], 0, v[138:139]
	s_add_i32 m0, s49, 0xe000
	s_nop 0
	global_load_lds_dwordx4 v[144:145], off
	s_waitcnt vmcnt(8)
	s_waitcnt lgkmcnt(0)
	s_barrier
	s_setprio 1
	s_waitcnt lgkmcnt(0)
	v_mfma_f32_16x16x32_bf16 v[124:127], v[152:155], v[190:193], v[124:127]
	v_mfma_f32_16x16x32_bf16 v[120:123], v[162:165], v[190:193], v[120:123]
	v_mfma_f32_16x16x32_bf16 v[108:111], v[152:155], v[198:201], v[108:111]
	v_mfma_f32_16x16x32_bf16 v[104:107], v[162:165], v[198:201], v[104:107]
	v_mfma_f32_16x16x32_bf16 v[92:95], v[152:155], v[206:209], v[92:95]
	v_mfma_f32_16x16x32_bf16 v[88:91], v[162:165], v[206:209], v[88:91]
	v_mfma_f32_16x16x32_bf16 v[76:79], v[152:155], v[214:217], v[76:79]
	v_mfma_f32_16x16x32_bf16 v[72:75], v[162:165], v[214:217], v[72:75]
	v_mfma_f32_16x16x32_bf16 v[124:127], v[156:159], v[194:197], v[124:127]
	v_mfma_f32_16x16x32_bf16 v[120:123], v[166:169], v[194:197], v[120:123]
	v_mfma_f32_16x16x32_bf16 v[108:111], v[156:159], v[202:205], v[108:111]
	v_mfma_f32_16x16x32_bf16 v[104:107], v[166:169], v[202:205], v[104:107]
	v_mfma_f32_16x16x32_bf16 v[92:95], v[156:159], v[210:213], v[92:95]
	v_mfma_f32_16x16x32_bf16 v[88:91], v[166:169], v[210:213], v[88:91]
	v_mfma_f32_16x16x32_bf16 v[76:79], v[156:159], v[218:221], v[76:79]
	v_mfma_f32_16x16x32_bf16 v[72:75], v[166:169], v[218:221], v[72:75]
	v_mfma_f32_16x16x32_bf16 v[116:119], v[170:173], v[190:193], v[116:119]
	v_mfma_f32_16x16x32_bf16 v[112:115], v[182:185], v[190:193], v[112:115]
	v_mfma_f32_16x16x32_bf16 v[100:103], v[170:173], v[198:201], v[100:103]
	v_mfma_f32_16x16x32_bf16 v[96:99], v[182:185], v[198:201], v[96:99]
	v_mfma_f32_16x16x32_bf16 v[84:87], v[170:173], v[206:209], v[84:87]
	v_mfma_f32_16x16x32_bf16 v[80:83], v[182:185], v[206:209], v[80:83]
	v_mfma_f32_16x16x32_bf16 v[68:71], v[170:173], v[214:217], v[68:71]
	v_mfma_f32_16x16x32_bf16 v[64:67], v[182:185], v[214:217], v[64:67]
	v_mfma_f32_16x16x32_bf16 v[116:119], v[178:181], v[194:197], v[116:119]
	v_mfma_f32_16x16x32_bf16 v[112:115], v[186:189], v[194:197], v[112:115]
	v_mfma_f32_16x16x32_bf16 v[100:103], v[178:181], v[202:205], v[100:103]
	v_mfma_f32_16x16x32_bf16 v[96:99], v[186:189], v[202:205], v[96:99]
	v_mfma_f32_16x16x32_bf16 v[84:87], v[178:181], v[210:213], v[84:87]
	v_mfma_f32_16x16x32_bf16 v[80:83], v[186:189], v[210:213], v[80:83]
	v_mfma_f32_16x16x32_bf16 v[68:71], v[178:181], v[218:221], v[68:71]
	v_mfma_f32_16x16x32_bf16 v[64:67], v[186:189], v[218:221], v[64:67]
	s_setprio 0
	s_barrier
	s_add_i32 s8, s75, s57
	v_lshl_add_u64 v[144:145], s[52:53], 0, v[132:133]
	s_mov_b32 m0, s8
	ds_read_b128 v[190:193], v151 offset:16384
	ds_read_b128 v[194:197], v151 offset:17408
	ds_read_b128 v[198:201], v151 offset:18432
	ds_read_b128 v[202:205], v151 offset:19456
	ds_read_b128 v[206:209], v151 offset:20480
	ds_read_b128 v[210:213], v151 offset:21504
	ds_read_b128 v[214:217], v151 offset:22528
	ds_read_b128 v[218:221], v151 offset:23552
	global_load_lds_dwordx4 v[144:145], off
	s_add_i32 m0, s8, 0x2000
	s_add_u32 s8, s52, 0x40000
	v_lshl_add_u64 v[174:175], s[52:53], 0, v[128:129]
	s_addc_u32 s9, s53, 0
	s_add_i32 s60, s76, s57
	global_load_lds_dwordx4 v[174:175], off
	v_lshl_add_u64 v[222:223], s[8:9], 0, v[132:133]
	s_mov_b32 m0, s60
	v_lshl_add_u64 v[224:225], s[54:55], 0, v[130:131]
	global_load_lds_dwordx4 v[222:223], off
	v_lshl_add_u64 v[222:223], s[8:9], 0, v[128:129]
	s_add_i32 m0, s60, 0x2000
	s_nop 0
	global_load_lds_dwordx4 v[222:223], off
	v_lshl_add_u64 v[222:223], s[54:55], 0, v[134:135]
	s_mov_b32 m0, s49
	s_nop 0
	global_load_lds_dwordx4 v[222:223], off
	s_mov_b32 m0, s67
	s_nop 0
	global_load_lds_dwordx4 v[224:225], off
	s_waitcnt vmcnt(8)
	s_waitcnt lgkmcnt(0)
	s_barrier
; #define PG8_STAGE(bufoff, gbase, voff) do { _Pragma("unroll") for (int _i = 0; _i < 2; ++_i) \
;         __builtin_amdgcn_global_load_lds((const unsigned*)((const char*)(gbase) + (voff)[_i]), (PG8_LAS unsigned*)(lds + (bufoff) + ldsw + _i * 8192), 16, 0, 0); } while (0)
; #define PG8_LDA(dst, b, h) do { _Pragma("unroll") for (int m = 0; m < 4; ++m) _Pragma("unroll") for (int k = 0; k < 2; ++k) dst[m][k] = *(const PG8_LAS bf16x8*)(lds + PG8_SA(b, h) + aoff + m * 2048 + k * 1024); } while (0)
; #define PG8_LDB(dst, b, h) do { _Pragma("unroll") for (int n = 0; n < 2; ++n) _Pragma("unroll") for (int k = 0; k < 2; ++k) dst[n][k] = *(const PG8_LAS bf16x8*)(lds + PG8_SB(b, h) + boff + n * 2048 + k * 1024); } while (0)
; #define PG8_MMA(ai, bj, At, Bt) do { __builtin_amdgcn_s_setprio(1); _Pragma("unroll") for (int m = 0; m < 4; ++m) _Pragma("unroll") for (int n = 0; n < 2; ++n) _Pragma("unroll") for (int k = 0; k < 2; ++k) \
;         acc[ai][bj][m][n] = __builtin_amdgcn_mfma_f32_16x16x32_bf16(Bt[n][k], At[m][k], acc[ai][bj][m][n], 0, 0, 0); __builtin_amdgcn_s_setprio(0); } while (0)
; #define PG8_WAIT_V(n) asm volatile("s_waitcnt vmcnt(" #n ")" ::: "memory")
; #define PG8_WAIT_L(n) asm volatile("s_waitcnt lgkmcnt(" #n ")" ::: "memory")
; #define PG8_BAR __builtin_amdgcn_s_barrier()
; #define PG8_SCHED __builtin_amdgcn_sched_barrier(0)
; template <class Epi, class Sched, bool ALIGN_EPI = false, bool SP2 = false>
; __device__ __forceinline__ void gemm_phase(PG8_LAS unsigned char* lds, const Gemm g, const Sched& S, const Epi& E) {
;     ...
;             PG8_WAIT_V(8); PG8_WAIT_L(0); PG8_BAR; PG8_MMA(1, 0, At, B0); PG8_MMA(1, 1, At, B1); PG8_BAR; PG8_SCHED;
;             PG8_LDB(B0, 1, 0); PG8_LDB(B1, 1, 1); PG8_SCHED; PG8_LDA(At, 1, 0); PG8_STAGE(PG8_SA(0, 1), a2 + hstep, voffA);
;             PG8_WAIT_V(8); PG8_WAIT_L(0); PG8_BAR; PG8_MMA(0, 0, At, B0); PG8_MMA(0, 1, At, B1); PG8_BAR; PG8_SCHED;
	s_setprio 1
	s_waitcnt lgkmcnt(0)
	v_mfma_f32_16x16x32_bf16 v[60:63], v[152:155], v[190:193], v[60:63]
	v_mfma_f32_16x16x32_bf16 v[56:59], v[162:165], v[190:193], v[56:59]
	v_mfma_f32_16x16x32_bf16 v[44:47], v[152:155], v[198:201], v[44:47]
	v_mfma_f32_16x16x32_bf16 v[40:43], v[162:165], v[198:201], v[40:43]
	v_mfma_f32_16x16x32_bf16 v[28:31], v[152:155], v[206:209], v[28:31]
	v_mfma_f32_16x16x32_bf16 v[24:27], v[162:165], v[206:209], v[24:27]
	v_mfma_f32_16x16x32_bf16 v[12:15], v[152:155], v[214:217], v[12:15]
	v_mfma_f32_16x16x32_bf16 v[8:11], v[162:165], v[214:217], v[8:11]
	v_mfma_f32_16x16x32_bf16 v[60:63], v[156:159], v[194:197], v[60:63]
	v_mfma_f32_16x16x32_bf16 v[56:59], v[166:169], v[194:197], v[56:59]
	v_mfma_f32_16x16x32_bf16 v[44:47], v[156:159], v[202:205], v[44:47]
	v_mfma_f32_16x16x32_bf16 v[40:43], v[166:169], v[202:205], v[40:43]
	v_mfma_f32_16x16x32_bf16 v[28:31], v[156:159], v[210:213], v[28:31]
	v_mfma_f32_16x16x32_bf16 v[24:27], v[166:169], v[210:213], v[24:27]
	v_mfma_f32_16x16x32_bf16 v[12:15], v[156:159], v[218:221], v[12:15]
	v_mfma_f32_16x16x32_bf16 v[8:11], v[166:169], v[218:221], v[8:11]
	v_mfma_f32_16x16x32_bf16 v[52:55], v[170:173], v[190:193], v[52:55]
	v_mfma_f32_16x16x32_bf16 v[48:51], v[182:185], v[190:193], v[48:51]
	v_mfma_f32_16x16x32_bf16 v[36:39], v[170:173], v[198:201], v[36:39]
	v_mfma_f32_16x16x32_bf16 v[32:35], v[182:185], v[198:201], v[32:35]
	v_mfma_f32_16x16x32_bf16 v[20:23], v[170:173], v[206:209], v[20:23]
	v_mfma_f32_16x16x32_bf16 v[16:19], v[182:185], v[206:209], v[16:19]
	v_mfma_f32_16x16x32_bf16 v[4:7], v[170:173], v[214:217], v[4:7]
	v_mfma_f32_16x16x32_bf16 v[0:3], v[182:185], v[214:217], v[0:3]
	v_mfma_f32_16x16x32_bf16 v[52:55], v[178:181], v[194:197], v[52:55]
	v_mfma_f32_16x16x32_bf16 v[48:51], v[186:189], v[194:197], v[48:51]
	v_mfma_f32_16x16x32_bf16 v[36:39], v[178:181], v[202:205], v[36:39]
	v_mfma_f32_16x16x32_bf16 v[32:35], v[186:189], v[202:205], v[32:35]
	v_mfma_f32_16x16x32_bf16 v[20:23], v[178:181], v[210:213], v[20:23]
	v_mfma_f32_16x16x32_bf16 v[16:19], v[186:189], v[210:213], v[16:19]
	v_mfma_f32_16x16x32_bf16 v[4:7], v[178:181], v[218:221], v[4:7]
	v_mfma_f32_16x16x32_bf16 v[0:3], v[186:189], v[218:221], v[0:3]
	s_setprio 0
	s_barrier
	s_add_i32 s60, 0, 0x18000
	v_add_u32_e32 v161, s60, v147
	s_add_i32 s61, 0, 0x1c000
	ds_read_b128 v[152:155], v161
	ds_read_b128 v[156:159], v161 offset:1024
	ds_read_b128 v[162:165], v161 offset:2048
	ds_read_b128 v[166:169], v161 offset:3072
	v_add_u32_e32 v161, s61, v147
	ds_read_b128 v[170:173], v161
	ds_read_b128 v[178:181], v161 offset:1024
	ds_read_b128 v[182:185], v161 offset:2048
	ds_read_b128 v[186:189], v161 offset:3072
	s_add_u32 s8, s54, 0x40000
	s_addc_u32 s9, s55, 0
	s_mov_b32 m0, s68
	v_lshl_add_u64 v[226:227], s[8:9], 0, v[134:135]
	ds_read_b128 v[190:193], v151 offset:32768
	ds_read_b128 v[194:197], v151 offset:33792
	ds_read_b128 v[198:201], v151 offset:34816
	ds_read_b128 v[202:205], v151 offset:35840
	ds_read_b128 v[206:209], v151 offset:36864
	ds_read_b128 v[210:213], v151 offset:37888
	ds_read_b128 v[214:217], v151 offset:38912
	ds_read_b128 v[218:221], v151 offset:39936
	global_load_lds_dwordx4 v[226:227], off
	v_lshl_add_u64 v[226:227], s[8:9], 0, v[130:131]
	s_mov_b32 m0, s69
	s_nop 0
	global_load_lds_dwordx4 v[226:227], off
	s_waitcnt vmcnt(8)
	s_waitcnt lgkmcnt(0)
	s_barrier
	s_setprio 1
	s_waitcnt lgkmcnt(0)
	v_mfma_f32_16x16x32_bf16 v[124:127], v[152:155], v[190:193], v[124:127]
	v_mfma_f32_16x16x32_bf16 v[120:123], v[162:165], v[190:193], v[120:123]
	v_mfma_f32_16x16x32_bf16 v[108:111], v[152:155], v[198:201], v[108:111]
	v_mfma_f32_16x16x32_bf16 v[104:107], v[162:165], v[198:201], v[104:107]
	v_mfma_f32_16x16x32_bf16 v[92:95], v[152:155], v[206:209], v[92:95]
	v_mfma_f32_16x16x32_bf16 v[88:91], v[162:165], v[206:209], v[88:91]
	v_mfma_f32_16x16x32_bf16 v[76:79], v[152:155], v[214:217], v[76:79]
	v_mfma_f32_16x16x32_bf16 v[72:75], v[162:165], v[214:217], v[72:75]
	v_mfma_f32_16x16x32_bf16 v[124:127], v[156:159], v[194:197], v[124:127]
	v_mfma_f32_16x16x32_bf16 v[120:123], v[166:169], v[194:197], v[120:123]
	v_mfma_f32_16x16x32_bf16 v[108:111], v[156:159], v[202:205], v[108:111]
	v_mfma_f32_16x16x32_bf16 v[104:107], v[166:169], v[202:205], v[104:107]
	v_mfma_f32_16x16x32_bf16 v[92:95], v[156:159], v[210:213], v[92:95]
	v_mfma_f32_16x16x32_bf16 v[88:91], v[166:169], v[210:213], v[88:91]
	v_mfma_f32_16x16x32_bf16 v[76:79], v[156:159], v[218:221], v[76:79]
	v_mfma_f32_16x16x32_bf16 v[72:75], v[166:169], v[218:221], v[72:75]
	v_mfma_f32_16x16x32_bf16 v[116:119], v[170:173], v[190:193], v[116:119]
	v_mfma_f32_16x16x32_bf16 v[112:115], v[182:185], v[190:193], v[112:115]
	v_mfma_f32_16x16x32_bf16 v[100:103], v[170:173], v[198:201], v[100:103]
	v_mfma_f32_16x16x32_bf16 v[96:99], v[182:185], v[198:201], v[96:99]
	v_mfma_f32_16x16x32_bf16 v[84:87], v[170:173], v[206:209], v[84:87]
	v_mfma_f32_16x16x32_bf16 v[80:83], v[182:185], v[206:209], v[80:83]
	v_mfma_f32_16x16x32_bf16 v[68:71], v[170:173], v[214:217], v[68:71]
	v_mfma_f32_16x16x32_bf16 v[64:67], v[182:185], v[214:217], v[64:67]
	v_mfma_f32_16x16x32_bf16 v[116:119], v[178:181], v[194:197], v[116:119]
	v_mfma_f32_16x16x32_bf16 v[112:115], v[186:189], v[194:197], v[112:115]
	v_mfma_f32_16x16x32_bf16 v[100:103], v[178:181], v[202:205], v[100:103]
	v_mfma_f32_16x16x32_bf16 v[96:99], v[186:189], v[202:205], v[96:99]
	v_mfma_f32_16x16x32_bf16 v[84:87], v[178:181], v[210:213], v[84:87]
	v_mfma_f32_16x16x32_bf16 v[80:83], v[186:189], v[210:213], v[80:83]
	v_mfma_f32_16x16x32_bf16 v[68:71], v[178:181], v[218:221], v[68:71]
	v_mfma_f32_16x16x32_bf16 v[64:67], v[186:189], v[218:221], v[64:67]
	s_setprio 0
	s_barrier
; #define PG8_STAGE(bufoff, gbase, voff) do { _Pragma("unroll") for (int _i = 0; _i < 2; ++_i) \
;         __builtin_amdgcn_global_load_lds((const unsigned*)((const char*)(gbase) + (voff)[_i]), (PG8_LAS unsigned*)(lds + (bufoff) + ldsw + _i * 8192), 16, 0, 0); } while (0)
; #define PG8_LDA(dst, b, h) do { _Pragma("unroll") for (int m = 0; m < 4; ++m) _Pragma("unroll") for (int k = 0; k < 2; ++k) dst[m][k] = *(const PG8_LAS bf16x8*)(lds + PG8_SA(b, h) + aoff + m * 2048 + k * 1024); } while (0)
; #define PG8_MMA(ai, bj, At, Bt) do { __builtin_amdgcn_s_setprio(1); _Pragma("unroll") for (int m = 0; m < 4; ++m) _Pragma("unroll") for (int n = 0; n < 2; ++n) _Pragma("unroll") for (int k = 0; k < 2; ++k) \
;         acc[ai][bj][m][n] = __builtin_amdgcn_mfma_f32_16x16x32_bf16(Bt[n][k], At[m][k], acc[ai][bj][m][n], 0, 0, 0); __builtin_amdgcn_s_setprio(0); } while (0)
; #define PG8_WAIT_V(n) asm volatile("s_waitcnt vmcnt(" #n ")" ::: "memory")
; #define PG8_WAIT_L(n) asm volatile("s_waitcnt lgkmcnt(" #n ")" ::: "memory")
; #define PG8_BAR __builtin_amdgcn_s_barrier()
; #define PG8_SCHED __builtin_amdgcn_sched_barrier(0)
; template <class Epi, class Sched, bool ALIGN_EPI = false, bool SP2 = false>
; __device__ __forceinline__ void gemm_phase(PG8_LAS unsigned char* lds, const Gemm g, const Sched& S, const Epi& E) {
;     ...
;             PG8_LDA(At, 1, 1); PG8_STAGE(PG8_SB(1, 0), b3, voffB); PG8_STAGE(PG8_SB(1, 1), b3 + hstep, voffB); PG8_STAGE(PG8_SA(1, 0), a3, voffA);
;             PG8_WAIT_V(8); PG8_WAIT_L(0); PG8_BAR; PG8_MMA(1, 0, At, B0); PG8_MMA(1, 1, At, B1); PG8_BAR; PG8_SCHED;
;     ...
;         if constexpr (ALIGN_EPI) { if (wr == 0) PG8_BAR; }
	s_add_i32 s8, s60, s57
	v_lshl_add_u64 v[144:145], v[144:145], 0, s[6:7]
	s_mov_b32 m0, s8
	ds_read_b128 v[190:193], v151 offset:49152
	ds_read_b128 v[194:197], v151 offset:50176
	ds_read_b128 v[198:201], v151 offset:51200
	ds_read_b128 v[202:205], v151 offset:52224
	ds_read_b128 v[206:209], v151 offset:53248
	ds_read_b128 v[210:213], v151 offset:54272
	ds_read_b128 v[214:217], v151 offset:55296
	ds_read_b128 v[218:221], v151 offset:56320
	global_load_lds_dwordx4 v[144:145], off
	s_add_i32 m0, s8, 0x2000
	s_add_u32 s8, s52, 0x40080
	v_lshl_add_u64 v[144:145], v[174:175], 0, s[6:7]
	s_addc_u32 s9, s53, 0
	s_add_i32 s52, s61, s57
	global_load_lds_dwordx4 v[144:145], off
	v_lshl_add_u64 v[144:145], s[8:9], 0, v[132:133]
	s_mov_b32 m0, s52
	s_nop 0
	global_load_lds_dwordx4 v[144:145], off
	v_lshl_add_u64 v[144:145], s[8:9], 0, v[128:129]
	s_add_i32 m0, s52, 0x2000
	s_nop 0
	global_load_lds_dwordx4 v[144:145], off
	v_lshl_add_u64 v[144:145], v[222:223], 0, s[6:7]
	s_mov_b32 m0, s71
	s_nop 0
	global_load_lds_dwordx4 v[144:145], off
	v_lshl_add_u64 v[144:145], v[224:225], 0, s[6:7]
	s_mov_b32 m0, s72
	s_nop 0
	global_load_lds_dwordx4 v[144:145], off
	s_waitcnt vmcnt(8)
	s_waitcnt lgkmcnt(0)
	s_barrier
	s_setprio 1
	s_waitcnt lgkmcnt(0)
	v_mfma_f32_16x16x32_bf16 v[60:63], v[152:155], v[190:193], v[60:63]
	v_mfma_f32_16x16x32_bf16 v[56:59], v[162:165], v[190:193], v[56:59]
	v_mfma_f32_16x16x32_bf16 v[44:47], v[152:155], v[198:201], v[44:47]
	v_mfma_f32_16x16x32_bf16 v[40:43], v[162:165], v[198:201], v[40:43]
	v_mfma_f32_16x16x32_bf16 v[28:31], v[152:155], v[206:209], v[28:31]
	v_mfma_f32_16x16x32_bf16 v[24:27], v[162:165], v[206:209], v[24:27]
	v_mfma_f32_16x16x32_bf16 v[12:15], v[152:155], v[214:217], v[12:15]
	v_mfma_f32_16x16x32_bf16 v[8:11], v[162:165], v[214:217], v[8:11]
	v_mfma_f32_16x16x32_bf16 v[60:63], v[156:159], v[194:197], v[60:63]
	v_mfma_f32_16x16x32_bf16 v[56:59], v[166:169], v[194:197], v[56:59]
	v_mfma_f32_16x16x32_bf16 v[44:47], v[156:159], v[202:205], v[44:47]
	v_mfma_f32_16x16x32_bf16 v[40:43], v[166:169], v[202:205], v[40:43]
	v_mfma_f32_16x16x32_bf16 v[28:31], v[156:159], v[210:213], v[28:31]
	v_mfma_f32_16x16x32_bf16 v[24:27], v[166:169], v[210:213], v[24:27]
	v_mfma_f32_16x16x32_bf16 v[12:15], v[156:159], v[218:221], v[12:15]
	v_mfma_f32_16x16x32_bf16 v[8:11], v[166:169], v[218:221], v[8:11]
	v_mfma_f32_16x16x32_bf16 v[52:55], v[170:173], v[190:193], v[52:55]
	v_mfma_f32_16x16x32_bf16 v[48:51], v[182:185], v[190:193], v[48:51]
	v_mfma_f32_16x16x32_bf16 v[36:39], v[170:173], v[198:201], v[36:39]
	v_mfma_f32_16x16x32_bf16 v[32:35], v[182:185], v[198:201], v[32:35]
	v_mfma_f32_16x16x32_bf16 v[20:23], v[170:173], v[206:209], v[20:23]
	v_mfma_f32_16x16x32_bf16 v[16:19], v[182:185], v[206:209], v[16:19]
	v_mfma_f32_16x16x32_bf16 v[4:7], v[170:173], v[214:217], v[4:7]
	v_mfma_f32_16x16x32_bf16 v[0:3], v[182:185], v[214:217], v[0:3]
	v_mfma_f32_16x16x32_bf16 v[52:55], v[178:181], v[194:197], v[52:55]
	v_mfma_f32_16x16x32_bf16 v[48:51], v[186:189], v[194:197], v[48:51]
	v_mfma_f32_16x16x32_bf16 v[36:39], v[178:181], v[202:205], v[36:39]
	v_mfma_f32_16x16x32_bf16 v[32:35], v[186:189], v[202:205], v[32:35]
	v_mfma_f32_16x16x32_bf16 v[20:23], v[178:181], v[210:213], v[20:23]
	v_mfma_f32_16x16x32_bf16 v[16:19], v[186:189], v[210:213], v[16:19]
	v_mfma_f32_16x16x32_bf16 v[4:7], v[178:181], v[218:221], v[4:7]
	v_mfma_f32_16x16x32_bf16 v[0:3], v[186:189], v[218:221], v[0:3]
	s_setprio 0
	s_add_i32 s83, s83, 2
	s_add_u32 s50, s50, 0x100
	s_addc_u32 s51, s51, 0
	s_add_u32 s81, s81, 0x100
	s_addc_u32 s82, s82, 0
	s_cmp_gt_u32 s83, 13
	s_barrier
	s_cbranch_scc0 .LBB0_557
	s_and_b64 vcc, exec, s[12:13]
	s_cbranch_vccz .LBB0_560
	s_barrier

; #define PG8_STAGE(bufoff, gbase, voff) do { _Pragma("unroll") for (int _i = 0; _i < 2; ++_i) \
;         __builtin_amdgcn_global_load_lds((const unsigned*)((const char*)(gbase) + (voff)[_i]), (PG8_LAS unsigned*)(lds + (bufoff) + ldsw + _i * 8192), 16, 0, 0); } while (0)
; #define PG8_LDA(dst, b, h) do { _Pragma("unroll") for (int m = 0; m < 4; ++m) _Pragma("unroll") for (int k = 0; k < 2; ++k) dst[m][k] = *(const PG8_LAS bf16x8*)(lds + PG8_SA(b, h) + aoff + m * 2048 + k * 1024); } while (0)
; #define PG8_LDB(dst, b, h) do { _Pragma("unroll") for (int n = 0; n < 2; ++n) _Pragma("unroll") for (int k = 0; k < 2; ++k) dst[n][k] = *(const PG8_LAS bf16x8*)(lds + PG8_SB(b, h) + boff + n * 2048 + k * 1024); } while (0)
; #define PG8_MMA(ai, bj, At, Bt) do { __builtin_amdgcn_s_setprio(1); _Pragma("unroll") for (int m = 0; m < 4; ++m) _Pragma("unroll") for (int n = 0; n < 2; ++n) _Pragma("unroll") for (int k = 0; k < 2; ++k) \
;         acc[ai][bj][m][n] = __builtin_amdgcn_mfma_f32_16x16x32_bf16(Bt[n][k], At[m][k], acc[ai][bj][m][n], 0, 0, 0); __builtin_amdgcn_s_setprio(0); } while (0)
; #define PG8_WAIT_V(n) asm volatile("s_waitcnt vmcnt(" #n ")" ::: "memory")
; template <class Epi, class Sched, bool ALIGN_EPI = false, bool SP2 = false>
; __device__ __forceinline__ void gemm_phase(PG8_LAS unsigned char* lds, const Gemm g, const Sched& S, const Epi& E) {
;     ...
;         const char* nA = has_next ? (const char*)g.A + (size_t)nxt.pm * tstep : cA; const char* nB = has_next ? (const char*)g.Bt + (size_t)nxt.pn * tstep : cB;
;         for (int t = 0; t < nt; t += 2) {
;             const bool last = (t == nt - 2);
;             const char* a1 = cA + (size_t)(t + 1) * kstep;
;             const char* a2 = last ? nA : cA + (size_t)(t + 2) * kstep; const char* b2 = last ? nB : cB + (size_t)(t + 2) * kstep;
;             const char* a3 = a2 + kstep; const char* b3 = b2 + kstep;
;             if (last && has_next) S.a_ready(nxt);
;             if constexpr (SP2) {
;             PG8_LDB(B0, 0, 0); PG8_LDB(B1, 0, 1); PG8_SCHED; PG8_LDA(At, 0, 0); PG8_STAGE(PG8_SA(1, 1), a1 + hstep, voffA);
;             PG8_WAIT_V(8); PG8_WAIT_L(0); PG8_BAR; PG8_MMA(0, 0, At, B0); PG8_MMA(0, 1, At, B1); PG8_BAR; PG8_SCHED;
;             PG8_LDA(At, 0, 1); PG8_STAGE(PG8_SB(0, 0), b2, voffB); PG8_STAGE(PG8_SB(0, 1), b2 + hstep, voffB); PG8_STAGE(PG8_SA(0, 0), a2, voffA);
.LBB0_640:
	ds_read_b128 v[164:167], v159
	ds_read_b128 v[168:171], v159 offset:1024
	ds_read_b128 v[172:175], v159 offset:2048
	ds_read_b128 v[178:181], v159 offset:3072
	ds_read_b128 v[182:185], v161
	ds_read_b128 v[186:189], v161 offset:1024
	ds_read_b128 v[190:193], v161 offset:2048
	ds_read_b128 v[194:197], v161 offset:3072
	s_add_u32 s8, s54, 0xfff50080
	s_addc_u32 s9, s55, -1
	s_cmp_eq_u32 s93, 40
	s_cselect_b32 s67, s1, s9
	s_cselect_b32 s66, s0, s8
	s_cselect_b32 s57, s53, s92
	s_cselect_b32 s56, s52, s91
	v_lshl_add_u64 v[146:147], s[54:55], 0, v[136:137]
	s_add_i32 m0, s70, 0xc000
	ds_read_b128 v[198:201], v162
	ds_read_b128 v[202:205], v162 offset:1024
	ds_read_b128 v[206:209], v162 offset:2048
	ds_read_b128 v[210:213], v162 offset:3072
	ds_read_b128 v[214:217], v162 offset:4096
	ds_read_b128 v[218:221], v162 offset:5120
	ds_read_b128 v[222:225], v162 offset:6144
	ds_read_b128 v[226:229], v162 offset:7168
	global_load_lds_dwordx4 v[146:147], off
	v_lshl_add_u64 v[146:147], s[54:55], 0, v[138:139]
	s_add_i32 m0, s70, 0xe000
	s_nop 0
	global_load_lds_dwordx4 v[146:147], off
	s_waitcnt vmcnt(8)
	s_waitcnt lgkmcnt(0)
	s_barrier
	s_setprio 1
	s_waitcnt lgkmcnt(0)
	v_mfma_f32_16x16x32_bf16 v[124:127], v[164:167], v[198:201], v[124:127]
	v_mfma_f32_16x16x32_bf16 v[120:123], v[172:175], v[198:201], v[120:123]
	v_mfma_f32_16x16x32_bf16 v[112:115], v[164:167], v[206:209], v[112:115]
	v_mfma_f32_16x16x32_bf16 v[104:107], v[172:175], v[206:209], v[104:107]
	v_mfma_f32_16x16x32_bf16 v[96:99], v[164:167], v[214:217], v[96:99]
	v_mfma_f32_16x16x32_bf16 v[88:91], v[172:175], v[214:217], v[88:91]
	v_mfma_f32_16x16x32_bf16 v[80:83], v[164:167], v[222:225], v[80:83]
	v_mfma_f32_16x16x32_bf16 v[72:75], v[172:175], v[222:225], v[72:75]
	v_mfma_f32_16x16x32_bf16 v[124:127], v[168:171], v[202:205], v[124:127]
	v_mfma_f32_16x16x32_bf16 v[120:123], v[178:181], v[202:205], v[120:123]
	v_mfma_f32_16x16x32_bf16 v[112:115], v[168:171], v[210:213], v[112:115]
	v_mfma_f32_16x16x32_bf16 v[104:107], v[178:181], v[210:213], v[104:107]
	v_mfma_f32_16x16x32_bf16 v[96:99], v[168:171], v[218:221], v[96:99]
	v_mfma_f32_16x16x32_bf16 v[88:91], v[178:181], v[218:221], v[88:91]
	v_mfma_f32_16x16x32_bf16 v[80:83], v[168:171], v[226:229], v[80:83]
	v_mfma_f32_16x16x32_bf16 v[72:75], v[178:181], v[226:229], v[72:75]
	v_mfma_f32_16x16x32_bf16 v[116:119], v[182:185], v[198:201], v[116:119]
	v_mfma_f32_16x16x32_bf16 v[108:111], v[190:193], v[198:201], v[108:111]
	v_mfma_f32_16x16x32_bf16 v[100:103], v[182:185], v[206:209], v[100:103]
	v_mfma_f32_16x16x32_bf16 v[92:95], v[190:193], v[206:209], v[92:95]
	v_mfma_f32_16x16x32_bf16 v[84:87], v[182:185], v[214:217], v[84:87]
	v_mfma_f32_16x16x32_bf16 v[76:79], v[190:193], v[214:217], v[76:79]
	v_mfma_f32_16x16x32_bf16 v[68:71], v[182:185], v[222:225], v[68:71]
	v_mfma_f32_16x16x32_bf16 v[64:67], v[190:193], v[222:225], v[64:67]
	v_mfma_f32_16x16x32_bf16 v[116:119], v[186:189], v[202:205], v[116:119]
	v_mfma_f32_16x16x32_bf16 v[108:111], v[194:197], v[202:205], v[108:111]
	v_mfma_f32_16x16x32_bf16 v[100:103], v[186:189], v[210:213], v[100:103]
	v_mfma_f32_16x16x32_bf16 v[92:95], v[194:197], v[210:213], v[92:95]
	v_mfma_f32_16x16x32_bf16 v[84:87], v[186:189], v[218:221], v[84:87]
	v_mfma_f32_16x16x32_bf16 v[76:79], v[194:197], v[218:221], v[76:79]
	v_mfma_f32_16x16x32_bf16 v[68:71], v[186:189], v[226:229], v[68:71]
	v_mfma_f32_16x16x32_bf16 v[64:67], v[194:197], v[226:229], v[64:67]
	s_setprio 0
	s_barrier
	s_add_i32 s8, s79, s69
	v_lshl_add_u64 v[146:147], s[56:57], 0, v[130:131]
	s_mov_b32 m0, s8
	ds_read_b128 v[198:201], v162 offset:16384
	ds_read_b128 v[202:205], v162 offset:17408
	ds_read_b128 v[206:209], v162 offset:18432
	ds_read_b128 v[210:213], v162 offset:19456
	ds_read_b128 v[214:217], v162 offset:20480
	ds_read_b128 v[218:221], v162 offset:21504
	ds_read_b128 v[222:225], v162 offset:22528
	ds_read_b128 v[226:229], v162 offset:23552
	global_load_lds_dwordx4 v[146:147], off
	s_add_i32 m0, s8, 0x2000
	s_add_u32 s8, s56, 0xb0000
	v_lshl_add_u64 v[230:231], s[56:57], 0, v[134:135]
	s_addc_u32 s9, s57, 0
	s_add_i32 s60, s80, s69
	global_load_lds_dwordx4 v[230:231], off
	v_lshl_add_u64 v[232:233], s[8:9], 0, v[130:131]
	s_mov_b32 m0, s60
	v_lshl_add_u64 v[234:235], s[66:67], 0, v[132:133]
	global_load_lds_dwordx4 v[232:233], off
	v_lshl_add_u64 v[232:233], s[8:9], 0, v[134:135]
	s_add_i32 m0, s60, 0x2000
	s_nop 0
	global_load_lds_dwordx4 v[232:233], off
	v_lshl_add_u64 v[232:233], s[66:67], 0, v[128:129]
	s_mov_b32 m0, s70
	s_nop 0
	global_load_lds_dwordx4 v[232:233], off
	s_mov_b32 m0, s71
	s_nop 0
	global_load_lds_dwordx4 v[234:235], off
	s_waitcnt vmcnt(8)
	s_waitcnt lgkmcnt(0)
	s_barrier
; #define PG8_STAGE(bufoff, gbase, voff) do { _Pragma("unroll") for (int _i = 0; _i < 2; ++_i) \
;         __builtin_amdgcn_global_load_lds((const unsigned*)((const char*)(gbase) + (voff)[_i]), (PG8_LAS unsigned*)(lds + (bufoff) + ldsw + _i * 8192), 16, 0, 0); } while (0)
; #define PG8_LDA(dst, b, h) do { _Pragma("unroll") for (int m = 0; m < 4; ++m) _Pragma("unroll") for (int k = 0; k < 2; ++k) dst[m][k] = *(const PG8_LAS bf16x8*)(lds + PG8_SA(b, h) + aoff + m * 2048 + k * 1024); } while (0)
; #define PG8_LDB(dst, b, h) do { _Pragma("unroll") for (int n = 0; n < 2; ++n) _Pragma("unroll") for (int k = 0; k < 2; ++k) dst[n][k] = *(const PG8_LAS bf16x8*)(lds + PG8_SB(b, h) + boff + n * 2048 + k * 1024); } while (0)
; #define PG8_MMA(ai, bj, At, Bt) do { __builtin_amdgcn_s_setprio(1); _Pragma("unroll") for (int m = 0; m < 4; ++m) _Pragma("unroll") for (int n = 0; n < 2; ++n) _Pragma("unroll") for (int k = 0; k < 2; ++k) \
;         acc[ai][bj][m][n] = __builtin_amdgcn_mfma_f32_16x16x32_bf16(Bt[n][k], At[m][k], acc[ai][bj][m][n], 0, 0, 0); __builtin_amdgcn_s_setprio(0); } while (0)
; #define PG8_WAIT_V(n) asm volatile("s_waitcnt vmcnt(" #n ")" ::: "memory")
; #define PG8_WAIT_L(n) asm volatile("s_waitcnt lgkmcnt(" #n ")" ::: "memory")
; #define PG8_BAR __builtin_amdgcn_s_barrier()
; #define PG8_SCHED __builtin_amdgcn_sched_barrier(0)
; template <class Epi, class Sched, bool ALIGN_EPI = false, bool SP2 = false>
; __device__ __forceinline__ void gemm_phase(PG8_LAS unsigned char* lds, const Gemm g, const Sched& S, const Epi& E) {
;     ...
;             PG8_WAIT_V(8); PG8_WAIT_L(0); PG8_BAR; PG8_MMA(1, 0, At, B0); PG8_MMA(1, 1, At, B1); PG8_BAR; PG8_SCHED;
;             PG8_LDB(B0, 1, 0); PG8_LDB(B1, 1, 1); PG8_SCHED; PG8_LDA(At, 1, 0); PG8_STAGE(PG8_SA(0, 1), a2 + hstep, voffA);
;             PG8_WAIT_V(8); PG8_WAIT_L(0); PG8_BAR; PG8_MMA(0, 0, At, B0); PG8_MMA(0, 1, At, B1); PG8_BAR; PG8_SCHED;
	s_setprio 1
	s_waitcnt lgkmcnt(0)
	v_mfma_f32_16x16x32_bf16 v[60:63], v[164:167], v[198:201], v[60:63]
	v_mfma_f32_16x16x32_bf16 v[56:59], v[172:175], v[198:201], v[56:59]
	v_mfma_f32_16x16x32_bf16 v[48:51], v[164:167], v[206:209], v[48:51]
	v_mfma_f32_16x16x32_bf16 v[40:43], v[172:175], v[206:209], v[40:43]
	v_mfma_f32_16x16x32_bf16 v[32:35], v[164:167], v[214:217], v[32:35]
	v_mfma_f32_16x16x32_bf16 v[24:27], v[172:175], v[214:217], v[24:27]
	v_mfma_f32_16x16x32_bf16 v[16:19], v[164:167], v[222:225], v[16:19]
	v_mfma_f32_16x16x32_bf16 v[8:11], v[172:175], v[222:225], v[8:11]
	v_mfma_f32_16x16x32_bf16 v[60:63], v[168:171], v[202:205], v[60:63]
	v_mfma_f32_16x16x32_bf16 v[56:59], v[178:181], v[202:205], v[56:59]
	v_mfma_f32_16x16x32_bf16 v[48:51], v[168:171], v[210:213], v[48:51]
	v_mfma_f32_16x16x32_bf16 v[40:43], v[178:181], v[210:213], v[40:43]
	v_mfma_f32_16x16x32_bf16 v[32:35], v[168:171], v[218:221], v[32:35]
	v_mfma_f32_16x16x32_bf16 v[24:27], v[178:181], v[218:221], v[24:27]
	v_mfma_f32_16x16x32_bf16 v[16:19], v[168:171], v[226:229], v[16:19]
	v_mfma_f32_16x16x32_bf16 v[8:11], v[178:181], v[226:229], v[8:11]
	v_mfma_f32_16x16x32_bf16 v[52:55], v[182:185], v[198:201], v[52:55]
	v_mfma_f32_16x16x32_bf16 v[44:47], v[190:193], v[198:201], v[44:47]
	v_mfma_f32_16x16x32_bf16 v[36:39], v[182:185], v[206:209], v[36:39]
	v_mfma_f32_16x16x32_bf16 v[28:31], v[190:193], v[206:209], v[28:31]
	v_mfma_f32_16x16x32_bf16 v[20:23], v[182:185], v[214:217], v[20:23]
	v_mfma_f32_16x16x32_bf16 v[12:15], v[190:193], v[214:217], v[12:15]
	v_mfma_f32_16x16x32_bf16 v[4:7], v[182:185], v[222:225], v[4:7]
	v_mfma_f32_16x16x32_bf16 v[0:3], v[190:193], v[222:225], v[0:3]
	v_mfma_f32_16x16x32_bf16 v[52:55], v[186:189], v[202:205], v[52:55]
	v_mfma_f32_16x16x32_bf16 v[44:47], v[194:197], v[202:205], v[44:47]
	v_mfma_f32_16x16x32_bf16 v[36:39], v[186:189], v[210:213], v[36:39]
	v_mfma_f32_16x16x32_bf16 v[28:31], v[194:197], v[210:213], v[28:31]
	v_mfma_f32_16x16x32_bf16 v[20:23], v[186:189], v[218:221], v[20:23]
	v_mfma_f32_16x16x32_bf16 v[12:15], v[194:197], v[218:221], v[12:15]
	v_mfma_f32_16x16x32_bf16 v[4:7], v[186:189], v[226:229], v[4:7]
	v_mfma_f32_16x16x32_bf16 v[0:3], v[194:197], v[226:229], v[0:3]
	s_setprio 0
	s_barrier
	s_add_i32 s60, 0, 0x18000
	v_add_u32_e32 v144, s60, v157
	s_add_i32 s61, 0, 0x1c000
	ds_read_b128 v[164:167], v144
	ds_read_b128 v[168:171], v144 offset:1024
	ds_read_b128 v[172:175], v144 offset:2048
	ds_read_b128 v[178:181], v144 offset:3072
	v_add_u32_e32 v144, s61, v157
	ds_read_b128 v[182:185], v144
	ds_read_b128 v[186:189], v144 offset:1024
	ds_read_b128 v[190:193], v144 offset:2048
	ds_read_b128 v[194:197], v144 offset:3072
	s_add_u32 s8, s66, 0xb0000
	s_addc_u32 s9, s67, 0
	s_mov_b32 m0, s72
	v_lshl_add_u64 v[236:237], s[8:9], 0, v[128:129]
	ds_read_b128 v[198:201], v162 offset:32768
	ds_read_b128 v[202:205], v162 offset:33792
	ds_read_b128 v[206:209], v162 offset:34816
	ds_read_b128 v[210:213], v162 offset:35840
	ds_read_b128 v[214:217], v162 offset:36864
	ds_read_b128 v[218:221], v162 offset:37888
	ds_read_b128 v[222:225], v162 offset:38912
	ds_read_b128 v[226:229], v162 offset:39936
	global_load_lds_dwordx4 v[236:237], off
	v_lshl_add_u64 v[236:237], s[8:9], 0, v[132:133]
	s_mov_b32 m0, s73
	s_nop 0
	global_load_lds_dwordx4 v[236:237], off
	s_waitcnt vmcnt(8)
	s_waitcnt lgkmcnt(0)
	s_barrier
	s_setprio 1
	s_waitcnt lgkmcnt(0)
	v_mfma_f32_16x16x32_bf16 v[124:127], v[164:167], v[198:201], v[124:127]
	v_mfma_f32_16x16x32_bf16 v[120:123], v[172:175], v[198:201], v[120:123]
	v_mfma_f32_16x16x32_bf16 v[112:115], v[164:167], v[206:209], v[112:115]
	v_mfma_f32_16x16x32_bf16 v[104:107], v[172:175], v[206:209], v[104:107]
	v_mfma_f32_16x16x32_bf16 v[96:99], v[164:167], v[214:217], v[96:99]
	v_mfma_f32_16x16x32_bf16 v[88:91], v[172:175], v[214:217], v[88:91]
	v_mfma_f32_16x16x32_bf16 v[80:83], v[164:167], v[222:225], v[80:83]
	v_mfma_f32_16x16x32_bf16 v[72:75], v[172:175], v[222:225], v[72:75]
	v_mfma_f32_16x16x32_bf16 v[124:127], v[168:171], v[202:205], v[124:127]
	v_mfma_f32_16x16x32_bf16 v[120:123], v[178:181], v[202:205], v[120:123]
	v_mfma_f32_16x16x32_bf16 v[112:115], v[168:171], v[210:213], v[112:115]
	v_mfma_f32_16x16x32_bf16 v[104:107], v[178:181], v[210:213], v[104:107]
	v_mfma_f32_16x16x32_bf16 v[96:99], v[168:171], v[218:221], v[96:99]
	v_mfma_f32_16x16x32_bf16 v[88:91], v[178:181], v[218:221], v[88:91]
	v_mfma_f32_16x16x32_bf16 v[80:83], v[168:171], v[226:229], v[80:83]
	v_mfma_f32_16x16x32_bf16 v[72:75], v[178:181], v[226:229], v[72:75]
	v_mfma_f32_16x16x32_bf16 v[116:119], v[182:185], v[198:201], v[116:119]
	v_mfma_f32_16x16x32_bf16 v[108:111], v[190:193], v[198:201], v[108:111]
	v_mfma_f32_16x16x32_bf16 v[100:103], v[182:185], v[206:209], v[100:103]
	v_mfma_f32_16x16x32_bf16 v[92:95], v[190:193], v[206:209], v[92:95]
	v_mfma_f32_16x16x32_bf16 v[84:87], v[182:185], v[214:217], v[84:87]
	v_mfma_f32_16x16x32_bf16 v[76:79], v[190:193], v[214:217], v[76:79]
	v_mfma_f32_16x16x32_bf16 v[68:71], v[182:185], v[222:225], v[68:71]
	v_mfma_f32_16x16x32_bf16 v[64:67], v[190:193], v[222:225], v[64:67]
	v_mfma_f32_16x16x32_bf16 v[116:119], v[186:189], v[202:205], v[116:119]
	v_mfma_f32_16x16x32_bf16 v[108:111], v[194:197], v[202:205], v[108:111]
	v_mfma_f32_16x16x32_bf16 v[100:103], v[186:189], v[210:213], v[100:103]
	v_mfma_f32_16x16x32_bf16 v[92:95], v[194:197], v[210:213], v[92:95]
	v_mfma_f32_16x16x32_bf16 v[84:87], v[186:189], v[218:221], v[84:87]
	v_mfma_f32_16x16x32_bf16 v[76:79], v[194:197], v[218:221], v[76:79]
	v_mfma_f32_16x16x32_bf16 v[68:71], v[186:189], v[226:229], v[68:71]
	v_mfma_f32_16x16x32_bf16 v[64:67], v[194:197], v[226:229], v[64:67]
	s_setprio 0
	s_barrier
; #define PG8_STAGE(bufoff, gbase, voff) do { _Pragma("unroll") for (int _i = 0; _i < 2; ++_i) \
;         __builtin_amdgcn_global_load_lds((const unsigned*)((const char*)(gbase) + (voff)[_i]), (PG8_LAS unsigned*)(lds + (bufoff) + ldsw + _i * 8192), 16, 0, 0); } while (0)
; #define PG8_LDA(dst, b, h) do { _Pragma("unroll") for (int m = 0; m < 4; ++m) _Pragma("unroll") for (int k = 0; k < 2; ++k) dst[m][k] = *(const PG8_LAS bf16x8*)(lds + PG8_SA(b, h) + aoff + m * 2048 + k * 1024); } while (0)
; #define PG8_MMA(ai, bj, At, Bt) do { __builtin_amdgcn_s_setprio(1); _Pragma("unroll") for (int m = 0; m < 4; ++m) _Pragma("unroll") for (int n = 0; n < 2; ++n) _Pragma("unroll") for (int k = 0; k < 2; ++k) \
;         acc[ai][bj][m][n] = __builtin_amdgcn_mfma_f32_16x16x32_bf16(Bt[n][k], At[m][k], acc[ai][bj][m][n], 0, 0, 0); __builtin_amdgcn_s_setprio(0); } while (0)
; #define PG8_WAIT_V(n) asm volatile("s_waitcnt vmcnt(" #n ")" ::: "memory")
; #define PG8_WAIT_L(n) asm volatile("s_waitcnt lgkmcnt(" #n ")" ::: "memory")
; #define PG8_BAR __builtin_amdgcn_s_barrier()
; #define PG8_SCHED __builtin_amdgcn_sched_barrier(0)
; template <class Epi, class Sched, bool ALIGN_EPI = false, bool SP2 = false>
; __device__ __forceinline__ void gemm_phase(PG8_LAS unsigned char* lds, const Gemm g, const Sched& S, const Epi& E) {
;     ...
;             PG8_LDA(At, 1, 1); PG8_STAGE(PG8_SB(1, 0), b3, voffB); PG8_STAGE(PG8_SB(1, 1), b3 + hstep, voffB); PG8_STAGE(PG8_SA(1, 0), a3, voffA);
;             PG8_WAIT_V(8); PG8_WAIT_L(0); PG8_BAR; PG8_MMA(1, 0, At, B0); PG8_MMA(1, 1, At, B1); PG8_BAR; PG8_SCHED;
;     ...
;         if constexpr (ALIGN_EPI) { if (wr == 0) PG8_BAR; }
	s_add_i32 s8, s60, s69
	v_lshl_add_u64 v[146:147], v[146:147], 0, s[14:15]
	s_mov_b32 m0, s8
	ds_read_b128 v[198:201], v162 offset:49152
	ds_read_b128 v[202:205], v162 offset:50176
	ds_read_b128 v[206:209], v162 offset:51200
	ds_read_b128 v[210:213], v162 offset:52224
	ds_read_b128 v[214:217], v162 offset:53248
	ds_read_b128 v[218:221], v162 offset:54272
	ds_read_b128 v[222:225], v162 offset:55296
	ds_read_b128 v[226:229], v162 offset:56320
	global_load_lds_dwordx4 v[146:147], off
	s_add_i32 m0, s8, 0x2000
	s_add_u32 s8, s56, 0xb0080
	v_lshl_add_u64 v[146:147], v[230:231], 0, s[14:15]
	s_addc_u32 s9, s57, 0
	s_add_i32 s56, s61, s69
	global_load_lds_dwordx4 v[146:147], off
	v_lshl_add_u64 v[146:147], s[8:9], 0, v[130:131]
	s_mov_b32 m0, s56
	s_nop 0
	global_load_lds_dwordx4 v[146:147], off
	v_lshl_add_u64 v[146:147], s[8:9], 0, v[134:135]
	s_add_i32 m0, s56, 0x2000
	s_nop 0
	global_load_lds_dwordx4 v[146:147], off
	v_lshl_add_u64 v[146:147], v[232:233], 0, s[14:15]
	s_mov_b32 m0, s75
	s_nop 0
	global_load_lds_dwordx4 v[146:147], off
	v_lshl_add_u64 v[146:147], v[234:235], 0, s[14:15]
	s_mov_b32 m0, s76
	s_nop 0
	global_load_lds_dwordx4 v[146:147], off
	s_waitcnt vmcnt(8)
	s_waitcnt lgkmcnt(0)
	s_barrier
	s_setprio 1
	s_waitcnt lgkmcnt(0)
	v_mfma_f32_16x16x32_bf16 v[60:63], v[164:167], v[198:201], v[60:63]
	v_mfma_f32_16x16x32_bf16 v[56:59], v[172:175], v[198:201], v[56:59]
	v_mfma_f32_16x16x32_bf16 v[48:51], v[164:167], v[206:209], v[48:51]
	v_mfma_f32_16x16x32_bf16 v[40:43], v[172:175], v[206:209], v[40:43]
	v_mfma_f32_16x16x32_bf16 v[32:35], v[164:167], v[214:217], v[32:35]
	v_mfma_f32_16x16x32_bf16 v[24:27], v[172:175], v[214:217], v[24:27]
	v_mfma_f32_16x16x32_bf16 v[16:19], v[164:167], v[222:225], v[16:19]
	v_mfma_f32_16x16x32_bf16 v[8:11], v[172:175], v[222:225], v[8:11]
	v_mfma_f32_16x16x32_bf16 v[60:63], v[168:171], v[202:205], v[60:63]
	v_mfma_f32_16x16x32_bf16 v[56:59], v[178:181], v[202:205], v[56:59]
	v_mfma_f32_16x16x32_bf16 v[48:51], v[168:171], v[210:213], v[48:51]
	v_mfma_f32_16x16x32_bf16 v[40:43], v[178:181], v[210:213], v[40:43]
	v_mfma_f32_16x16x32_bf16 v[32:35], v[168:171], v[218:221], v[32:35]
	v_mfma_f32_16x16x32_bf16 v[24:27], v[178:181], v[218:221], v[24:27]
	v_mfma_f32_16x16x32_bf16 v[16:19], v[168:171], v[226:229], v[16:19]
	v_mfma_f32_16x16x32_bf16 v[8:11], v[178:181], v[226:229], v[8:11]
	v_mfma_f32_16x16x32_bf16 v[52:55], v[182:185], v[198:201], v[52:55]
	v_mfma_f32_16x16x32_bf16 v[44:47], v[190:193], v[198:201], v[44:47]
	v_mfma_f32_16x16x32_bf16 v[36:39], v[182:185], v[206:209], v[36:39]
	v_mfma_f32_16x16x32_bf16 v[28:31], v[190:193], v[206:209], v[28:31]
	v_mfma_f32_16x16x32_bf16 v[20:23], v[182:185], v[214:217], v[20:23]
	v_mfma_f32_16x16x32_bf16 v[12:15], v[190:193], v[214:217], v[12:15]
	v_mfma_f32_16x16x32_bf16 v[4:7], v[182:185], v[222:225], v[4:7]
	v_mfma_f32_16x16x32_bf16 v[0:3], v[190:193], v[222:225], v[0:3]
	v_mfma_f32_16x16x32_bf16 v[52:55], v[186:189], v[202:205], v[52:55]
	v_mfma_f32_16x16x32_bf16 v[44:47], v[194:197], v[202:205], v[44:47]
	v_mfma_f32_16x16x32_bf16 v[36:39], v[186:189], v[210:213], v[36:39]
	v_mfma_f32_16x16x32_bf16 v[28:31], v[194:197], v[210:213], v[28:31]
	v_mfma_f32_16x16x32_bf16 v[20:23], v[186:189], v[218:221], v[20:23]
	v_mfma_f32_16x16x32_bf16 v[12:15], v[194:197], v[218:221], v[12:15]
	v_mfma_f32_16x16x32_bf16 v[4:7], v[186:189], v[226:229], v[4:7]
	v_mfma_f32_16x16x32_bf16 v[0:3], v[194:197], v[226:229], v[0:3]
	s_setprio 0
	s_add_i32 s93, s93, 2
	s_add_u32 s54, s54, 0x100
	s_addc_u32 s55, s55, 0
	s_add_u32 s91, s91, 0x100
	s_addc_u32 s92, s92, 0
	s_cmp_gt_u32 s93, 41
	s_barrier
	s_cbranch_scc0 .LBB0_640
	s_and_b64 vcc, exec, s[18:19]
	s_cbranch_vccz .LBB0_643
	s_barrier

; #define PG8_STAGE(bufoff, gbase, voff) do { _Pragma("unroll") for (int _i = 0; _i < 2; ++_i) \
;         __builtin_amdgcn_global_load_lds((const unsigned*)((const char*)(gbase) + (voff)[_i]), (PG8_LAS unsigned*)(lds + (bufoff) + ldsw + _i * 8192), 16, 0, 0); } while (0)
; #define PG8_LDA(dst, b, h) do { _Pragma("unroll") for (int m = 0; m < 4; ++m) _Pragma("unroll") for (int k = 0; k < 2; ++k) dst[m][k] = *(const PG8_LAS bf16x8*)(lds + PG8_SA(b, h) + aoff + m * 2048 + k * 1024); } while (0)
; #define PG8_LDB(dst, b, h) do { _Pragma("unroll") for (int n = 0; n < 2; ++n) _Pragma("unroll") for (int k = 0; k < 2; ++k) dst[n][k] = *(const PG8_LAS bf16x8*)(lds + PG8_SB(b, h) + boff + n * 2048 + k * 1024); } while (0)
; #define PG8_MMA(ai, bj, At, Bt) do { __builtin_amdgcn_s_setprio(1); _Pragma("unroll") for (int m = 0; m < 4; ++m) _Pragma("unroll") for (int n = 0; n < 2; ++n) _Pragma("unroll") for (int k = 0; k < 2; ++k) \
;         acc[ai][bj][m][n] = __builtin_amdgcn_mfma_f32_16x16x32_bf16(Bt[n][k], At[m][k], acc[ai][bj][m][n], 0, 0, 0); __builtin_amdgcn_s_setprio(0); } while (0)
; #define PG8_WAIT_V(n) asm volatile("s_waitcnt vmcnt(" #n ")" ::: "memory")
; template <class Epi, class Sched, bool ALIGN_EPI = false, bool SP2 = false>
; __device__ __forceinline__ void gemm_phase(PG8_LAS unsigned char* lds, const Gemm g, const Sched& S, const Epi& E) {
;     ...
;         const char* nA = has_next ? (const char*)g.A + (size_t)nxt.pm * tstep : cA; const char* nB = has_next ? (const char*)g.Bt + (size_t)nxt.pn * tstep : cB;
;         for (int t = 0; t < nt; t += 2) {
;             const bool last = (t == nt - 2);
;             const char* a1 = cA + (size_t)(t + 1) * kstep;
;             const char* a2 = last ? nA : cA + (size_t)(t + 2) * kstep; const char* b2 = last ? nB : cB + (size_t)(t + 2) * kstep;
;             const char* a3 = a2 + kstep; const char* b3 = b2 + kstep;
;             if (last && has_next) S.a_ready(nxt);
;             if constexpr (SP2) {
;             PG8_LDB(B0, 0, 0); PG8_LDB(B1, 0, 1); PG8_SCHED; PG8_LDA(At, 0, 0); PG8_STAGE(PG8_SA(1, 1), a1 + hstep, voffA);
;             PG8_WAIT_V(8); PG8_WAIT_L(0); PG8_BAR; PG8_MMA(0, 0, At, B0); PG8_MMA(0, 1, At, B1); PG8_BAR; PG8_SCHED;
;             PG8_LDA(At, 0, 1); PG8_STAGE(PG8_SB(0, 0), b2, voffB); PG8_STAGE(PG8_SB(0, 1), b2 + hstep, voffB); PG8_STAGE(PG8_SA(0, 0), a2, voffA);
.LBB0_664:
	s_add_u32 s49, s52, s66
	s_addc_u32 s61, s53, 0
	s_add_u32 s67, s49, 0x100
	s_addc_u32 s68, s61, 0
	s_and_b64 s[8:9], s[56:57], exec
	s_cselect_b32 s69, s19, s68
	s_cselect_b32 s68, s91, s67
	s_add_u32 s8, s50, s66
	s_addc_u32 s9, s51, 0
	s_add_u32 s66, s8, 0x100
	s_addc_u32 s67, s9, 0
	s_and_b64 s[8:9], s[56:57], exec
	s_cselect_b32 s71, s15, s67
	s_cselect_b32 s70, s92, s66
	s_add_u32 s74, s49, 0x10080
	ds_read_b128 v[150:153], v146
	ds_read_b128 v[154:157], v146 offset:1024
	ds_read_b128 v[162:165], v146 offset:2048
	ds_read_b128 v[166:169], v146 offset:3072
	ds_read_b128 v[170:173], v147
	ds_read_b128 v[178:181], v147 offset:1024
	ds_read_b128 v[182:185], v147 offset:2048
	ds_read_b128 v[186:189], v147 offset:3072
	s_addc_u32 s75, s61, 0
	s_add_i32 s9, s88, s77
	s_add_i32 m0, s60, 0xc000
	s_add_i32 s49, s60, 0xe000
	s_add_i32 vcc_hi, s9, 0x2000
	s_add_u32 s72, s70, 0x10000
	s_addc_u32 s73, s71, 0
	s_add_i32 s84, s89, s77
	s_add_i32 s8, s84, 0x2000
	s_add_i32 vcc_lo, 0, 0x18000
	s_add_i32 s97, 0, 0x1c000
	s_add_u32 s66, s68, 0x10000
	s_addc_u32 s67, s69, 0
	s_add_i32 s96, vcc_lo, s77
	s_add_i32 s94, s96, 0x2000
	s_add_u32 s56, s70, 0x10080
	s_addc_u32 s57, s71, 0
	s_add_i32 s95, s97, s77
	s_add_i32 s93, s95, 0x2000
	v_lshl_add_u64 v[142:143], s[74:75], 0, v[128:129]
	ds_read_b128 v[190:193], v148
	ds_read_b128 v[194:197], v148 offset:1024
	ds_read_b128 v[198:201], v148 offset:2048
	ds_read_b128 v[202:205], v148 offset:3072
	ds_read_b128 v[206:209], v148 offset:4096
	ds_read_b128 v[210:213], v148 offset:5120
	ds_read_b128 v[214:217], v148 offset:6144
	ds_read_b128 v[218:221], v148 offset:7168
	global_load_lds_dwordx4 v[142:143], off
	v_lshl_add_u64 v[142:143], s[74:75], 0, v[132:133]
	s_mov_b32 m0, s49
	s_nop 0
	global_load_lds_dwordx4 v[142:143], off
	s_waitcnt vmcnt(8)
	s_waitcnt lgkmcnt(0)
	s_barrier
	s_setprio 1
	s_waitcnt lgkmcnt(0)
	v_mfma_f32_16x16x32_bf16 v[124:127], v[150:153], v[190:193], v[124:127]
	v_mfma_f32_16x16x32_bf16 v[120:123], v[162:165], v[190:193], v[120:123]
	v_mfma_f32_16x16x32_bf16 v[112:115], v[150:153], v[198:201], v[112:115]
	v_mfma_f32_16x16x32_bf16 v[104:107], v[162:165], v[198:201], v[104:107]
	v_mfma_f32_16x16x32_bf16 v[96:99], v[150:153], v[206:209], v[96:99]
	v_mfma_f32_16x16x32_bf16 v[88:91], v[162:165], v[206:209], v[88:91]
	v_mfma_f32_16x16x32_bf16 v[80:83], v[150:153], v[214:217], v[80:83]
	v_mfma_f32_16x16x32_bf16 v[72:75], v[162:165], v[214:217], v[72:75]
	v_mfma_f32_16x16x32_bf16 v[124:127], v[154:157], v[194:197], v[124:127]
	v_mfma_f32_16x16x32_bf16 v[120:123], v[166:169], v[194:197], v[120:123]
	v_mfma_f32_16x16x32_bf16 v[112:115], v[154:157], v[202:205], v[112:115]
	v_mfma_f32_16x16x32_bf16 v[104:107], v[166:169], v[202:205], v[104:107]
	v_mfma_f32_16x16x32_bf16 v[96:99], v[154:157], v[210:213], v[96:99]
	v_mfma_f32_16x16x32_bf16 v[88:91], v[166:169], v[210:213], v[88:91]
	v_mfma_f32_16x16x32_bf16 v[80:83], v[154:157], v[218:221], v[80:83]
	v_mfma_f32_16x16x32_bf16 v[72:75], v[166:169], v[218:221], v[72:75]
	v_mfma_f32_16x16x32_bf16 v[116:119], v[170:173], v[190:193], v[116:119]
	v_mfma_f32_16x16x32_bf16 v[108:111], v[182:185], v[190:193], v[108:111]
	v_mfma_f32_16x16x32_bf16 v[100:103], v[170:173], v[198:201], v[100:103]
	v_mfma_f32_16x16x32_bf16 v[92:95], v[182:185], v[198:201], v[92:95]
	v_mfma_f32_16x16x32_bf16 v[84:87], v[170:173], v[206:209], v[84:87]
	v_mfma_f32_16x16x32_bf16 v[76:79], v[182:185], v[206:209], v[76:79]
	v_mfma_f32_16x16x32_bf16 v[68:71], v[170:173], v[214:217], v[68:71]
	v_mfma_f32_16x16x32_bf16 v[64:67], v[182:185], v[214:217], v[64:67]
	v_mfma_f32_16x16x32_bf16 v[116:119], v[178:181], v[194:197], v[116:119]
	v_mfma_f32_16x16x32_bf16 v[108:111], v[186:189], v[194:197], v[108:111]
	v_mfma_f32_16x16x32_bf16 v[100:103], v[178:181], v[202:205], v[100:103]
	v_mfma_f32_16x16x32_bf16 v[92:95], v[186:189], v[202:205], v[92:95]
	v_mfma_f32_16x16x32_bf16 v[84:87], v[178:181], v[210:213], v[84:87]
	v_mfma_f32_16x16x32_bf16 v[76:79], v[186:189], v[210:213], v[76:79]
	v_mfma_f32_16x16x32_bf16 v[68:71], v[178:181], v[218:221], v[68:71]
	v_mfma_f32_16x16x32_bf16 v[64:67], v[186:189], v[218:221], v[64:67]
	s_setprio 0
	s_barrier
	s_mov_b32 m0, s9
	v_lshl_add_u64 v[142:143], s[70:71], 0, v[130:131]
	ds_read_b128 v[190:193], v148 offset:16384
	ds_read_b128 v[194:197], v148 offset:17408
	ds_read_b128 v[198:201], v148 offset:18432
	ds_read_b128 v[202:205], v148 offset:19456
	ds_read_b128 v[206:209], v148 offset:20480
	ds_read_b128 v[210:213], v148 offset:21504
	ds_read_b128 v[214:217], v148 offset:22528
	ds_read_b128 v[218:221], v148 offset:23552
	global_load_lds_dwordx4 v[142:143], off
	v_lshl_add_u64 v[158:159], s[70:71], 0, v[134:135]
	s_mov_b32 m0, vcc_hi
	v_lshl_add_u64 v[174:175], s[72:73], 0, v[130:131]
	global_load_lds_dwordx4 v[158:159], off
	s_mov_b32 m0, s84
	v_lshl_add_u64 v[222:223], s[68:69], 0, v[132:133]
	global_load_lds_dwordx4 v[174:175], off
	v_lshl_add_u64 v[174:175], s[72:73], 0, v[134:135]
	s_mov_b32 m0, s8
	s_nop 0
	global_load_lds_dwordx4 v[174:175], off
	v_lshl_add_u64 v[174:175], s[68:69], 0, v[128:129]
	s_mov_b32 m0, s60
	s_nop 0
	global_load_lds_dwordx4 v[174:175], off
	s_mov_b32 m0, s78
	s_nop 0
	global_load_lds_dwordx4 v[222:223], off
	s_waitcnt vmcnt(8)
	s_waitcnt lgkmcnt(0)
	s_barrier
; #define PG8_STAGE(bufoff, gbase, voff) do { _Pragma("unroll") for (int _i = 0; _i < 2; ++_i) \
;         __builtin_amdgcn_global_load_lds((const unsigned*)((const char*)(gbase) + (voff)[_i]), (PG8_LAS unsigned*)(lds + (bufoff) + ldsw + _i * 8192), 16, 0, 0); } while (0)
; #define PG8_LDA(dst, b, h) do { _Pragma("unroll") for (int m = 0; m < 4; ++m) _Pragma("unroll") for (int k = 0; k < 2; ++k) dst[m][k] = *(const PG8_LAS bf16x8*)(lds + PG8_SA(b, h) + aoff + m * 2048 + k * 1024); } while (0)
; #define PG8_LDB(dst, b, h) do { _Pragma("unroll") for (int n = 0; n < 2; ++n) _Pragma("unroll") for (int k = 0; k < 2; ++k) dst[n][k] = *(const PG8_LAS bf16x8*)(lds + PG8_SB(b, h) + boff + n * 2048 + k * 1024); } while (0)
; #define PG8_MMA(ai, bj, At, Bt) do { __builtin_amdgcn_s_setprio(1); _Pragma("unroll") for (int m = 0; m < 4; ++m) _Pragma("unroll") for (int n = 0; n < 2; ++n) _Pragma("unroll") for (int k = 0; k < 2; ++k) \
;         acc[ai][bj][m][n] = __builtin_amdgcn_mfma_f32_16x16x32_bf16(Bt[n][k], At[m][k], acc[ai][bj][m][n], 0, 0, 0); __builtin_amdgcn_s_setprio(0); } while (0)
; #define PG8_WAIT_V(n) asm volatile("s_waitcnt vmcnt(" #n ")" ::: "memory")
; #define PG8_WAIT_L(n) asm volatile("s_waitcnt lgkmcnt(" #n ")" ::: "memory")
; #define PG8_BAR __builtin_amdgcn_s_barrier()
; #define PG8_SCHED __builtin_amdgcn_sched_barrier(0)
; template <class Epi, class Sched, bool ALIGN_EPI = false, bool SP2 = false>
; __device__ __forceinline__ void gemm_phase(PG8_LAS unsigned char* lds, const Gemm g, const Sched& S, const Epi& E) {
;     ...
;             PG8_WAIT_V(8); PG8_WAIT_L(0); PG8_BAR; PG8_MMA(1, 0, At, B0); PG8_MMA(1, 1, At, B1); PG8_BAR; PG8_SCHED;
;             PG8_LDB(B0, 1, 0); PG8_LDB(B1, 1, 1); PG8_SCHED; PG8_LDA(At, 1, 0); PG8_STAGE(PG8_SA(0, 1), a2 + hstep, voffA);
;             PG8_WAIT_V(8); PG8_WAIT_L(0); PG8_BAR; PG8_MMA(0, 0, At, B0); PG8_MMA(0, 1, At, B1); PG8_BAR; PG8_SCHED;
	s_setprio 1
	s_waitcnt lgkmcnt(0)
	v_mfma_f32_16x16x32_bf16 v[60:63], v[150:153], v[190:193], v[60:63]
	v_mfma_f32_16x16x32_bf16 v[56:59], v[162:165], v[190:193], v[56:59]
	v_mfma_f32_16x16x32_bf16 v[48:51], v[150:153], v[198:201], v[48:51]
	v_mfma_f32_16x16x32_bf16 v[40:43], v[162:165], v[198:201], v[40:43]
	v_mfma_f32_16x16x32_bf16 v[32:35], v[150:153], v[206:209], v[32:35]
	v_mfma_f32_16x16x32_bf16 v[24:27], v[162:165], v[206:209], v[24:27]
	v_mfma_f32_16x16x32_bf16 v[16:19], v[150:153], v[214:217], v[16:19]
	v_mfma_f32_16x16x32_bf16 v[8:11], v[162:165], v[214:217], v[8:11]
	v_mfma_f32_16x16x32_bf16 v[60:63], v[154:157], v[194:197], v[60:63]
	v_mfma_f32_16x16x32_bf16 v[56:59], v[166:169], v[194:197], v[56:59]
	v_mfma_f32_16x16x32_bf16 v[48:51], v[154:157], v[202:205], v[48:51]
	v_mfma_f32_16x16x32_bf16 v[40:43], v[166:169], v[202:205], v[40:43]
	v_mfma_f32_16x16x32_bf16 v[32:35], v[154:157], v[210:213], v[32:35]
	v_mfma_f32_16x16x32_bf16 v[24:27], v[166:169], v[210:213], v[24:27]
	v_mfma_f32_16x16x32_bf16 v[16:19], v[154:157], v[218:221], v[16:19]
	v_mfma_f32_16x16x32_bf16 v[8:11], v[166:169], v[218:221], v[8:11]
	v_mfma_f32_16x16x32_bf16 v[52:55], v[170:173], v[190:193], v[52:55]
	v_mfma_f32_16x16x32_bf16 v[44:47], v[182:185], v[190:193], v[44:47]
	v_mfma_f32_16x16x32_bf16 v[36:39], v[170:173], v[198:201], v[36:39]
	v_mfma_f32_16x16x32_bf16 v[28:31], v[182:185], v[198:201], v[28:31]
	v_mfma_f32_16x16x32_bf16 v[20:23], v[170:173], v[206:209], v[20:23]
	v_mfma_f32_16x16x32_bf16 v[12:15], v[182:185], v[206:209], v[12:15]
	v_mfma_f32_16x16x32_bf16 v[4:7], v[170:173], v[214:217], v[4:7]
	v_mfma_f32_16x16x32_bf16 v[0:3], v[182:185], v[214:217], v[0:3]
	v_mfma_f32_16x16x32_bf16 v[52:55], v[178:181], v[194:197], v[52:55]
	v_mfma_f32_16x16x32_bf16 v[44:47], v[186:189], v[194:197], v[44:47]
	v_mfma_f32_16x16x32_bf16 v[36:39], v[178:181], v[202:205], v[36:39]
	v_mfma_f32_16x16x32_bf16 v[28:31], v[186:189], v[202:205], v[28:31]
	v_mfma_f32_16x16x32_bf16 v[20:23], v[178:181], v[210:213], v[20:23]
	v_mfma_f32_16x16x32_bf16 v[12:15], v[186:189], v[210:213], v[12:15]
	v_mfma_f32_16x16x32_bf16 v[4:7], v[178:181], v[218:221], v[4:7]
	v_mfma_f32_16x16x32_bf16 v[0:3], v[186:189], v[218:221], v[0:3]
	s_setprio 0
	s_barrier
	v_add_u32_e32 v140, vcc_lo, v144
	ds_read_b128 v[150:153], v140
	ds_read_b128 v[154:157], v140 offset:1024
	ds_read_b128 v[162:165], v140 offset:2048
	ds_read_b128 v[166:169], v140 offset:3072
	v_add_u32_e32 v140, s97, v144
	ds_read_b128 v[170:173], v140
	ds_read_b128 v[178:181], v140 offset:1024
	ds_read_b128 v[182:185], v140 offset:2048
	ds_read_b128 v[186:189], v140 offset:3072
	s_mov_b32 m0, s79
	v_lshl_add_u64 v[224:225], s[66:67], 0, v[128:129]
	ds_read_b128 v[190:193], v148 offset:32768
	ds_read_b128 v[194:197], v148 offset:33792
	ds_read_b128 v[198:201], v148 offset:34816
	ds_read_b128 v[202:205], v148 offset:35840
	ds_read_b128 v[206:209], v148 offset:36864
	ds_read_b128 v[210:213], v148 offset:37888
	ds_read_b128 v[214:217], v148 offset:38912
	ds_read_b128 v[218:221], v148 offset:39936
	global_load_lds_dwordx4 v[224:225], off
	v_lshl_add_u64 v[224:225], s[66:67], 0, v[132:133]
	s_mov_b32 m0, s80
	s_nop 0
	global_load_lds_dwordx4 v[224:225], off
	s_waitcnt vmcnt(8)
	s_waitcnt lgkmcnt(0)
	s_barrier
	s_setprio 1
	s_waitcnt lgkmcnt(0)
	v_mfma_f32_16x16x32_bf16 v[124:127], v[150:153], v[190:193], v[124:127]
	v_mfma_f32_16x16x32_bf16 v[120:123], v[162:165], v[190:193], v[120:123]
	v_mfma_f32_16x16x32_bf16 v[112:115], v[150:153], v[198:201], v[112:115]
	v_mfma_f32_16x16x32_bf16 v[104:107], v[162:165], v[198:201], v[104:107]
	v_mfma_f32_16x16x32_bf16 v[96:99], v[150:153], v[206:209], v[96:99]
	v_mfma_f32_16x16x32_bf16 v[88:91], v[162:165], v[206:209], v[88:91]
	v_mfma_f32_16x16x32_bf16 v[80:83], v[150:153], v[214:217], v[80:83]
	v_mfma_f32_16x16x32_bf16 v[72:75], v[162:165], v[214:217], v[72:75]
	v_mfma_f32_16x16x32_bf16 v[124:127], v[154:157], v[194:197], v[124:127]
	v_mfma_f32_16x16x32_bf16 v[120:123], v[166:169], v[194:197], v[120:123]
	v_mfma_f32_16x16x32_bf16 v[112:115], v[154:157], v[202:205], v[112:115]
	v_mfma_f32_16x16x32_bf16 v[104:107], v[166:169], v[202:205], v[104:107]
	v_mfma_f32_16x16x32_bf16 v[96:99], v[154:157], v[210:213], v[96:99]
	v_mfma_f32_16x16x32_bf16 v[88:91], v[166:169], v[210:213], v[88:91]
	v_mfma_f32_16x16x32_bf16 v[80:83], v[154:157], v[218:221], v[80:83]
	v_mfma_f32_16x16x32_bf16 v[72:75], v[166:169], v[218:221], v[72:75]
	v_mfma_f32_16x16x32_bf16 v[116:119], v[170:173], v[190:193], v[116:119]
	v_mfma_f32_16x16x32_bf16 v[108:111], v[182:185], v[190:193], v[108:111]
	v_mfma_f32_16x16x32_bf16 v[100:103], v[170:173], v[198:201], v[100:103]
	v_mfma_f32_16x16x32_bf16 v[92:95], v[182:185], v[198:201], v[92:95]
	v_mfma_f32_16x16x32_bf16 v[84:87], v[170:173], v[206:209], v[84:87]
	v_mfma_f32_16x16x32_bf16 v[76:79], v[182:185], v[206:209], v[76:79]
	v_mfma_f32_16x16x32_bf16 v[68:71], v[170:173], v[214:217], v[68:71]
	v_mfma_f32_16x16x32_bf16 v[64:67], v[182:185], v[214:217], v[64:67]
	v_mfma_f32_16x16x32_bf16 v[116:119], v[178:181], v[194:197], v[116:119]
	v_mfma_f32_16x16x32_bf16 v[108:111], v[186:189], v[194:197], v[108:111]
	v_mfma_f32_16x16x32_bf16 v[100:103], v[178:181], v[202:205], v[100:103]
	v_mfma_f32_16x16x32_bf16 v[92:95], v[186:189], v[202:205], v[92:95]
	v_mfma_f32_16x16x32_bf16 v[84:87], v[178:181], v[210:213], v[84:87]
	v_mfma_f32_16x16x32_bf16 v[76:79], v[186:189], v[210:213], v[76:79]
	v_mfma_f32_16x16x32_bf16 v[68:71], v[178:181], v[218:221], v[68:71]
	v_mfma_f32_16x16x32_bf16 v[64:67], v[186:189], v[218:221], v[64:67]
	s_setprio 0
	s_barrier
; #define PG8_STAGE(bufoff, gbase, voff) do { _Pragma("unroll") for (int _i = 0; _i < 2; ++_i) \
;         __builtin_amdgcn_global_load_lds((const unsigned*)((const char*)(gbase) + (voff)[_i]), (PG8_LAS unsigned*)(lds + (bufoff) + ldsw + _i * 8192), 16, 0, 0); } while (0)
; #define PG8_LDA(dst, b, h) do { _Pragma("unroll") for (int m = 0; m < 4; ++m) _Pragma("unroll") for (int k = 0; k < 2; ++k) dst[m][k] = *(const PG8_LAS bf16x8*)(lds + PG8_SA(b, h) + aoff + m * 2048 + k * 1024); } while (0)
; #define PG8_MMA(ai, bj, At, Bt) do { __builtin_amdgcn_s_setprio(1); _Pragma("unroll") for (int m = 0; m < 4; ++m) _Pragma("unroll") for (int n = 0; n < 2; ++n) _Pragma("unroll") for (int k = 0; k < 2; ++k) \
;         acc[ai][bj][m][n] = __builtin_amdgcn_mfma_f32_16x16x32_bf16(Bt[n][k], At[m][k], acc[ai][bj][m][n], 0, 0, 0); __builtin_amdgcn_s_setprio(0); } while (0)
; #define PG8_WAIT_V(n) asm volatile("s_waitcnt vmcnt(" #n ")" ::: "memory")
; #define PG8_WAIT_L(n) asm volatile("s_waitcnt lgkmcnt(" #n ")" ::: "memory")
; #define PG8_BAR __builtin_amdgcn_s_barrier()
; #define PG8_SCHED __builtin_amdgcn_sched_barrier(0)
; template <class Epi, class Sched, bool ALIGN_EPI = false, bool SP2 = false>
; __device__ __forceinline__ void gemm_phase(PG8_LAS unsigned char* lds, const Gemm g, const Sched& S, const Epi& E) {
;     ...
;             PG8_LDA(At, 1, 1); PG8_STAGE(PG8_SB(1, 0), b3, voffB); PG8_STAGE(PG8_SB(1, 1), b3 + hstep, voffB); PG8_STAGE(PG8_SA(1, 0), a3, voffA);
;             PG8_WAIT_V(8); PG8_WAIT_L(0); PG8_BAR; PG8_MMA(1, 0, At, B0); PG8_MMA(1, 1, At, B1); PG8_BAR; PG8_SCHED;
;     ...
;         if constexpr (ALIGN_EPI) { if (wr == 0) PG8_BAR; }
	s_mov_b32 m0, s96
	v_lshl_add_u64 v[142:143], v[142:143], 0, s[6:7]
	ds_read_b128 v[190:193], v148 offset:49152
	ds_read_b128 v[194:197], v148 offset:50176
	ds_read_b128 v[198:201], v148 offset:51200
	ds_read_b128 v[202:205], v148 offset:52224
	ds_read_b128 v[206:209], v148 offset:53248
	ds_read_b128 v[210:213], v148 offset:54272
	ds_read_b128 v[214:217], v148 offset:55296
	ds_read_b128 v[218:221], v148 offset:56320
	global_load_lds_dwordx4 v[142:143], off
	v_lshl_add_u64 v[142:143], v[158:159], 0, s[6:7]
	s_mov_b32 m0, s94
	s_nop 0
	global_load_lds_dwordx4 v[142:143], off
	v_lshl_add_u64 v[142:143], s[56:57], 0, v[130:131]
	s_mov_b32 m0, s95
	s_nop 0
	global_load_lds_dwordx4 v[142:143], off
	v_lshl_add_u64 v[142:143], s[56:57], 0, v[134:135]
	s_mov_b32 m0, s93
	s_nop 0
	global_load_lds_dwordx4 v[142:143], off
	v_lshl_add_u64 v[142:143], v[174:175], 0, s[6:7]
	s_mov_b32 m0, s82
	s_nop 0
	global_load_lds_dwordx4 v[142:143], off
	v_lshl_add_u64 v[142:143], v[222:223], 0, s[6:7]
	s_mov_b32 m0, s83
	s_nop 0
	global_load_lds_dwordx4 v[142:143], off
	s_waitcnt vmcnt(8)
	s_waitcnt lgkmcnt(0)
	s_barrier
	s_setprio 1
	s_waitcnt lgkmcnt(0)
	v_mfma_f32_16x16x32_bf16 v[60:63], v[150:153], v[190:193], v[60:63]
	v_mfma_f32_16x16x32_bf16 v[56:59], v[162:165], v[190:193], v[56:59]
	v_mfma_f32_16x16x32_bf16 v[48:51], v[150:153], v[198:201], v[48:51]
	v_mfma_f32_16x16x32_bf16 v[40:43], v[162:165], v[198:201], v[40:43]
	v_mfma_f32_16x16x32_bf16 v[32:35], v[150:153], v[206:209], v[32:35]
	v_mfma_f32_16x16x32_bf16 v[24:27], v[162:165], v[206:209], v[24:27]
	v_mfma_f32_16x16x32_bf16 v[16:19], v[150:153], v[214:217], v[16:19]
	v_mfma_f32_16x16x32_bf16 v[8:11], v[162:165], v[214:217], v[8:11]
	v_mfma_f32_16x16x32_bf16 v[60:63], v[154:157], v[194:197], v[60:63]
	v_mfma_f32_16x16x32_bf16 v[56:59], v[166:169], v[194:197], v[56:59]
	v_mfma_f32_16x16x32_bf16 v[48:51], v[154:157], v[202:205], v[48:51]
	v_mfma_f32_16x16x32_bf16 v[40:43], v[166:169], v[202:205], v[40:43]
	v_mfma_f32_16x16x32_bf16 v[32:35], v[154:157], v[210:213], v[32:35]
	v_mfma_f32_16x16x32_bf16 v[24:27], v[166:169], v[210:213], v[24:27]
	v_mfma_f32_16x16x32_bf16 v[16:19], v[154:157], v[218:221], v[16:19]
	v_mfma_f32_16x16x32_bf16 v[8:11], v[166:169], v[218:221], v[8:11]
	v_mfma_f32_16x16x32_bf16 v[52:55], v[170:173], v[190:193], v[52:55]
	v_mfma_f32_16x16x32_bf16 v[44:47], v[182:185], v[190:193], v[44:47]
	v_mfma_f32_16x16x32_bf16 v[36:39], v[170:173], v[198:201], v[36:39]
	v_mfma_f32_16x16x32_bf16 v[28:31], v[182:185], v[198:201], v[28:31]
	v_mfma_f32_16x16x32_bf16 v[20:23], v[170:173], v[206:209], v[20:23]
	v_mfma_f32_16x16x32_bf16 v[12:15], v[182:185], v[206:209], v[12:15]
	v_mfma_f32_16x16x32_bf16 v[4:7], v[170:173], v[214:217], v[4:7]
	v_mfma_f32_16x16x32_bf16 v[0:3], v[182:185], v[214:217], v[0:3]
	v_mfma_f32_16x16x32_bf16 v[52:55], v[178:181], v[194:197], v[52:55]
	v_mfma_f32_16x16x32_bf16 v[44:47], v[186:189], v[194:197], v[44:47]
	v_mfma_f32_16x16x32_bf16 v[36:39], v[178:181], v[202:205], v[36:39]
	v_mfma_f32_16x16x32_bf16 v[28:31], v[186:189], v[202:205], v[28:31]
	v_mfma_f32_16x16x32_bf16 v[20:23], v[178:181], v[210:213], v[20:23]
	v_mfma_f32_16x16x32_bf16 v[12:15], v[186:189], v[210:213], v[12:15]
	v_mfma_f32_16x16x32_bf16 v[4:7], v[178:181], v[218:221], v[4:7]
	v_mfma_f32_16x16x32_bf16 v[0:3], v[186:189], v[218:221], v[0:3]
	s_setprio 0
	s_barrier
	s_movk_i32 s66, 0x100
	s_andn2_b64 vcc, exec, s[54:55]
	s_mov_b64 s[56:57], -1
	s_mov_b64 s[54:55], 0
	s_cbranch_vccz .LBB0_664
	s_and_b64 vcc, exec, s[12:13]
	s_cbranch_vccz .LBB0_667
	s_barrier

; #define PG8_STAGE(bufoff, gbase, voff) do { _Pragma("unroll") for (int _i = 0; _i < 2; ++_i) \
;         __builtin_amdgcn_global_load_lds((const unsigned*)((const char*)(gbase) + (voff)[_i]), (PG8_LAS unsigned*)(lds + (bufoff) + ldsw + _i * 8192), 16, 0, 0); } while (0)
; #define PG8_LDA(dst, b, h) do { _Pragma("unroll") for (int m = 0; m < 4; ++m) _Pragma("unroll") for (int k = 0; k < 2; ++k) dst[m][k] = *(const PG8_LAS bf16x8*)(lds + PG8_SA(b, h) + aoff + m * 2048 + k * 1024); } while (0)
; #define PG8_LDB(dst, b, h) do { _Pragma("unroll") for (int n = 0; n < 2; ++n) _Pragma("unroll") for (int k = 0; k < 2; ++k) dst[n][k] = *(const PG8_LAS bf16x8*)(lds + PG8_SB(b, h) + boff + n * 2048 + k * 1024); } while (0)
; #define PG8_MMA(ai, bj, At, Bt) do { __builtin_amdgcn_s_setprio(1); _Pragma("unroll") for (int m = 0; m < 4; ++m) _Pragma("unroll") for (int n = 0; n < 2; ++n) _Pragma("unroll") for (int k = 0; k < 2; ++k) \
;         acc[ai][bj][m][n] = __builtin_amdgcn_mfma_f32_16x16x32_bf16(Bt[n][k], At[m][k], acc[ai][bj][m][n], 0, 0, 0); __builtin_amdgcn_s_setprio(0); } while (0)
; #define PG8_WAIT_V(n) asm volatile("s_waitcnt vmcnt(" #n ")" ::: "memory")
; template <class Epi, class Sched, bool ALIGN_EPI = false, bool SP2 = false>
; __device__ __forceinline__ void gemm_phase(PG8_LAS unsigned char* lds, const Gemm g, const Sched& S, const Epi& E) {
;     ...
;         const char* nA = has_next ? (const char*)g.A + (size_t)nxt.pm * tstep : cA; const char* nB = has_next ? (const char*)g.Bt + (size_t)nxt.pn * tstep : cB;
;         for (int t = 0; t < nt; t += 2) {
;             const bool last = (t == nt - 2);
;             const char* a1 = cA + (size_t)(t + 1) * kstep;
;             const char* a2 = last ? nA : cA + (size_t)(t + 2) * kstep; const char* b2 = last ? nB : cB + (size_t)(t + 2) * kstep;
;             const char* a3 = a2 + kstep; const char* b3 = b2 + kstep;
;             if (last && has_next) S.a_ready(nxt);
;             if constexpr (SP2) {
;             PG8_LDB(B0, 0, 0); PG8_LDB(B1, 0, 1); PG8_SCHED; PG8_LDA(At, 0, 0); PG8_STAGE(PG8_SA(1, 1), a1 + hstep, voffA);
;             PG8_WAIT_V(8); PG8_WAIT_L(0); PG8_BAR; PG8_MMA(0, 0, At, B0); PG8_MMA(0, 1, At, B1); PG8_BAR; PG8_SCHED;
;             PG8_LDA(At, 0, 1); PG8_STAGE(PG8_SB(0, 0), b2, voffB); PG8_STAGE(PG8_SB(0, 1), b2 + hstep, voffB); PG8_STAGE(PG8_SA(0, 0), a2, voffA);
.LBB0_836:
	ds_read_b128 v[48:51], v162
	ds_read_b128 v[52:55], v162 offset:1024
	ds_read_b128 v[152:155], v162 offset:2048
	ds_read_b128 v[166:169], v162 offset:3072
	ds_read_b128 v[170:173], v163
	ds_read_b128 v[178:181], v163 offset:1024
	ds_read_b128 v[182:185], v163 offset:2048
	ds_read_b128 v[186:189], v163 offset:3072
	s_add_u32 s8, s64, 0xfffc0080
	s_addc_u32 s9, s65, -1
	s_cmp_eq_u32 s87, 12
	s_cselect_b32 s69, s49, s9
	s_cselect_b32 s68, s55, s8
	s_cselect_b32 s67, s43, s86
	s_cselect_b32 s66, s82, s83
	v_lshl_add_u64 v[156:157], s[64:65], 0, v[144:145]
	s_add_i32 m0, s57, 0xc000
	ds_read_b128 v[190:193], v164
	ds_read_b128 v[194:197], v164 offset:1024
	ds_read_b128 v[198:201], v164 offset:2048
	ds_read_b128 v[202:205], v164 offset:3072
	ds_read_b128 v[206:209], v164 offset:4096
	ds_read_b128 v[210:213], v164 offset:5120
	ds_read_b128 v[214:217], v164 offset:6144
	ds_read_b128 v[218:221], v164 offset:7168
	global_load_lds_dwordx4 v[156:157], off
	v_lshl_add_u64 v[156:157], s[64:65], 0, v[146:147]
	s_add_i32 m0, s57, 0xe000
	s_nop 0
	global_load_lds_dwordx4 v[156:157], off
	s_waitcnt vmcnt(8)
	s_waitcnt lgkmcnt(0)
	s_barrier
	s_setprio 1
	s_waitcnt lgkmcnt(0)
	v_mfma_f32_16x16x32_bf16 v[44:47], v[48:51], v[190:193], v[44:47]
	v_mfma_f32_16x16x32_bf16 v[36:39], v[152:155], v[190:193], v[36:39]
	v_mfma_f32_16x16x32_bf16 v[124:127], v[48:51], v[198:201], v[124:127]
	v_mfma_f32_16x16x32_bf16 v[120:123], v[152:155], v[198:201], v[120:123]
	v_mfma_f32_16x16x32_bf16 v[108:111], v[48:51], v[206:209], v[108:111]
	v_mfma_f32_16x16x32_bf16 v[104:107], v[152:155], v[206:209], v[104:107]
	v_mfma_f32_16x16x32_bf16 v[92:95], v[48:51], v[214:217], v[92:95]
	v_mfma_f32_16x16x32_bf16 v[88:91], v[152:155], v[214:217], v[88:91]
	v_mfma_f32_16x16x32_bf16 v[44:47], v[52:55], v[194:197], v[44:47]
	v_mfma_f32_16x16x32_bf16 v[36:39], v[166:169], v[194:197], v[36:39]
	v_mfma_f32_16x16x32_bf16 v[124:127], v[52:55], v[202:205], v[124:127]
	v_mfma_f32_16x16x32_bf16 v[120:123], v[166:169], v[202:205], v[120:123]
	v_mfma_f32_16x16x32_bf16 v[108:111], v[52:55], v[210:213], v[108:111]
	v_mfma_f32_16x16x32_bf16 v[104:107], v[166:169], v[210:213], v[104:107]
	v_mfma_f32_16x16x32_bf16 v[92:95], v[52:55], v[218:221], v[92:95]
	v_mfma_f32_16x16x32_bf16 v[88:91], v[166:169], v[218:221], v[88:91]
	v_mfma_f32_16x16x32_bf16 v[132:135], v[170:173], v[190:193], v[132:135]
	v_mfma_f32_16x16x32_bf16 v[128:131], v[182:185], v[190:193], v[128:131]
	v_mfma_f32_16x16x32_bf16 v[116:119], v[170:173], v[198:201], v[116:119]
	v_mfma_f32_16x16x32_bf16 v[112:115], v[182:185], v[198:201], v[112:115]
	v_mfma_f32_16x16x32_bf16 v[100:103], v[170:173], v[206:209], v[100:103]
	v_mfma_f32_16x16x32_bf16 v[96:99], v[182:185], v[206:209], v[96:99]
	v_mfma_f32_16x16x32_bf16 v[84:87], v[170:173], v[214:217], v[84:87]
	v_mfma_f32_16x16x32_bf16 v[80:83], v[182:185], v[214:217], v[80:83]
	v_mfma_f32_16x16x32_bf16 v[132:135], v[178:181], v[194:197], v[132:135]
	v_mfma_f32_16x16x32_bf16 v[128:131], v[186:189], v[194:197], v[128:131]
	v_mfma_f32_16x16x32_bf16 v[116:119], v[178:181], v[202:205], v[116:119]
	v_mfma_f32_16x16x32_bf16 v[112:115], v[186:189], v[202:205], v[112:115]
	v_mfma_f32_16x16x32_bf16 v[100:103], v[178:181], v[210:213], v[100:103]
	v_mfma_f32_16x16x32_bf16 v[96:99], v[186:189], v[210:213], v[96:99]
	v_mfma_f32_16x16x32_bf16 v[84:87], v[178:181], v[218:221], v[84:87]
	v_mfma_f32_16x16x32_bf16 v[80:83], v[186:189], v[218:221], v[80:83]
	s_setprio 0
	s_barrier
	s_add_i32 s8, s80, s70
	v_lshl_add_u64 v[156:157], s[66:67], 0, v[138:139]
	s_mov_b32 m0, s8
	ds_read_b128 v[190:193], v164 offset:16384
	ds_read_b128 v[194:197], v164 offset:17408
	ds_read_b128 v[198:201], v164 offset:18432
	ds_read_b128 v[202:205], v164 offset:19456
	ds_read_b128 v[206:209], v164 offset:20480
	ds_read_b128 v[210:213], v164 offset:21504
	ds_read_b128 v[214:217], v164 offset:22528
	ds_read_b128 v[218:221], v164 offset:23552
	global_load_lds_dwordx4 v[156:157], off
	s_add_i32 m0, s8, 0x2000
	s_add_u32 s8, s66, 0x40000
	v_lshl_add_u64 v[174:175], s[66:67], 0, v[142:143]
	s_addc_u32 s9, s67, 0
	s_add_i32 s60, s81, s70
	global_load_lds_dwordx4 v[174:175], off
	v_lshl_add_u64 v[222:223], s[8:9], 0, v[138:139]
	s_mov_b32 m0, s60
	v_lshl_add_u64 v[224:225], s[68:69], 0, v[140:141]
	global_load_lds_dwordx4 v[222:223], off
	v_lshl_add_u64 v[222:223], s[8:9], 0, v[142:143]
	s_add_i32 m0, s60, 0x2000
	s_nop 0
	global_load_lds_dwordx4 v[222:223], off
	v_lshl_add_u64 v[222:223], s[68:69], 0, v[136:137]
	s_mov_b32 m0, s57
	s_nop 0
	global_load_lds_dwordx4 v[222:223], off
	s_mov_b32 m0, s71
	s_nop 0
	global_load_lds_dwordx4 v[224:225], off
	s_waitcnt vmcnt(8)
	s_waitcnt lgkmcnt(0)
	s_barrier
; #define PG8_STAGE(bufoff, gbase, voff) do { _Pragma("unroll") for (int _i = 0; _i < 2; ++_i) \
;         __builtin_amdgcn_global_load_lds((const unsigned*)((const char*)(gbase) + (voff)[_i]), (PG8_LAS unsigned*)(lds + (bufoff) + ldsw + _i * 8192), 16, 0, 0); } while (0)
; #define PG8_LDA(dst, b, h) do { _Pragma("unroll") for (int m = 0; m < 4; ++m) _Pragma("unroll") for (int k = 0; k < 2; ++k) dst[m][k] = *(const PG8_LAS bf16x8*)(lds + PG8_SA(b, h) + aoff + m * 2048 + k * 1024); } while (0)
; #define PG8_LDB(dst, b, h) do { _Pragma("unroll") for (int n = 0; n < 2; ++n) _Pragma("unroll") for (int k = 0; k < 2; ++k) dst[n][k] = *(const PG8_LAS bf16x8*)(lds + PG8_SB(b, h) + boff + n * 2048 + k * 1024); } while (0)
; #define PG8_MMA(ai, bj, At, Bt) do { __builtin_amdgcn_s_setprio(1); _Pragma("unroll") for (int m = 0; m < 4; ++m) _Pragma("unroll") for (int n = 0; n < 2; ++n) _Pragma("unroll") for (int k = 0; k < 2; ++k) \
;         acc[ai][bj][m][n] = __builtin_amdgcn_mfma_f32_16x16x32_bf16(Bt[n][k], At[m][k], acc[ai][bj][m][n], 0, 0, 0); __builtin_amdgcn_s_setprio(0); } while (0)
; #define PG8_WAIT_V(n) asm volatile("s_waitcnt vmcnt(" #n ")" ::: "memory")
; #define PG8_WAIT_L(n) asm volatile("s_waitcnt lgkmcnt(" #n ")" ::: "memory")
; #define PG8_BAR __builtin_amdgcn_s_barrier()
; #define PG8_SCHED __builtin_amdgcn_sched_barrier(0)
; template <class Epi, class Sched, bool ALIGN_EPI = false, bool SP2 = false>
; __device__ __forceinline__ void gemm_phase(PG8_LAS unsigned char* lds, const Gemm g, const Sched& S, const Epi& E) {
;     ...
;             PG8_WAIT_V(8); PG8_WAIT_L(0); PG8_BAR; PG8_MMA(1, 0, At, B0); PG8_MMA(1, 1, At, B1); PG8_BAR; PG8_SCHED;
;             PG8_LDB(B0, 1, 0); PG8_LDB(B1, 1, 1); PG8_SCHED; PG8_LDA(At, 1, 0); PG8_STAGE(PG8_SA(0, 1), a2 + hstep, voffA);
;             PG8_WAIT_V(8); PG8_WAIT_L(0); PG8_BAR; PG8_MMA(0, 0, At, B0); PG8_MMA(0, 1, At, B1); PG8_BAR; PG8_SCHED;
	s_setprio 1
	s_waitcnt lgkmcnt(0)
	v_mfma_f32_16x16x32_bf16 v[76:79], v[48:51], v[190:193], v[76:79]
	v_mfma_f32_16x16x32_bf16 v[72:75], v[152:155], v[190:193], v[72:75]
	v_mfma_f32_16x16x32_bf16 v[60:63], v[48:51], v[198:201], v[60:63]
	v_mfma_f32_16x16x32_bf16 v[56:59], v[152:155], v[198:201], v[56:59]
	v_mfma_f32_16x16x32_bf16 v[28:31], v[48:51], v[206:209], v[28:31]
	v_mfma_f32_16x16x32_bf16 v[24:27], v[152:155], v[206:209], v[24:27]
	v_mfma_f32_16x16x32_bf16 v[12:15], v[48:51], v[214:217], v[12:15]
	v_mfma_f32_16x16x32_bf16 v[8:11], v[152:155], v[214:217], v[8:11]
	v_mfma_f32_16x16x32_bf16 v[76:79], v[52:55], v[194:197], v[76:79]
	v_mfma_f32_16x16x32_bf16 v[72:75], v[166:169], v[194:197], v[72:75]
	v_mfma_f32_16x16x32_bf16 v[60:63], v[52:55], v[202:205], v[60:63]
	v_mfma_f32_16x16x32_bf16 v[56:59], v[166:169], v[202:205], v[56:59]
	v_mfma_f32_16x16x32_bf16 v[28:31], v[52:55], v[210:213], v[28:31]
	v_mfma_f32_16x16x32_bf16 v[24:27], v[166:169], v[210:213], v[24:27]
	v_mfma_f32_16x16x32_bf16 v[12:15], v[52:55], v[218:221], v[12:15]
	v_mfma_f32_16x16x32_bf16 v[8:11], v[166:169], v[218:221], v[8:11]
	v_mfma_f32_16x16x32_bf16 v[40:43], v[170:173], v[198:201], v[40:43]
	v_mfma_f32_16x16x32_bf16 v[32:35], v[182:185], v[198:201], v[32:35]
	v_mfma_f32_16x16x32_bf16 v[20:23], v[170:173], v[206:209], v[20:23]
	v_mfma_f32_16x16x32_bf16 v[16:19], v[182:185], v[206:209], v[16:19]
	v_mfma_f32_16x16x32_bf16 v[4:7], v[170:173], v[214:217], v[4:7]
	v_mfma_f32_16x16x32_bf16 v[0:3], v[182:185], v[214:217], v[0:3]
	v_mfma_f32_16x16x32_bf16 v[48:51], v[170:173], v[190:193], v[68:71]
	v_mfma_f32_16x16x32_bf16 v[52:55], v[182:185], v[190:193], v[64:67]
	v_mfma_f32_16x16x32_bf16 v[40:43], v[178:181], v[202:205], v[40:43]
	v_mfma_f32_16x16x32_bf16 v[32:35], v[186:189], v[202:205], v[32:35]
	v_mfma_f32_16x16x32_bf16 v[20:23], v[178:181], v[210:213], v[20:23]
	v_mfma_f32_16x16x32_bf16 v[16:19], v[186:189], v[210:213], v[16:19]
	v_mfma_f32_16x16x32_bf16 v[4:7], v[178:181], v[218:221], v[4:7]
	v_mfma_f32_16x16x32_bf16 v[0:3], v[186:189], v[218:221], v[0:3]
	v_mfma_f32_16x16x32_bf16 v[48:51], v[178:181], v[194:197], v[48:51]
	v_mfma_f32_16x16x32_bf16 v[52:55], v[186:189], v[194:197], v[52:55]
	s_setprio 0
	s_barrier
	s_add_i32 s60, 0, 0x18000
	s_add_i32 s61, 0, 0x1c000
	v_add_u32_e32 v166, s60, v159
	v_add_u32_e32 v177, s61, v159
	ds_read_b128 v[64:67], v166
	ds_read_b128 v[68:71], v166 offset:1024
	ds_read_b128 v[152:155], v166 offset:2048
	ds_read_b128 v[166:169], v166 offset:3072
	ds_read_b128 v[170:173], v177
	ds_read_b128 v[178:181], v177 offset:1024
	ds_read_b128 v[182:185], v177 offset:2048
	ds_read_b128 v[186:189], v177 offset:3072
	s_add_u32 s8, s68, 0x40000
	s_addc_u32 s9, s69, 0
	s_mov_b32 m0, s72
	v_lshl_add_u64 v[226:227], s[8:9], 0, v[136:137]
	ds_read_b128 v[190:193], v164 offset:32768
	ds_read_b128 v[194:197], v164 offset:33792
	ds_read_b128 v[198:201], v164 offset:34816
	ds_read_b128 v[202:205], v164 offset:35840
	ds_read_b128 v[206:209], v164 offset:36864
	ds_read_b128 v[210:213], v164 offset:37888
	ds_read_b128 v[214:217], v164 offset:38912
	ds_read_b128 v[218:221], v164 offset:39936
	global_load_lds_dwordx4 v[226:227], off
	v_lshl_add_u64 v[226:227], s[8:9], 0, v[140:141]
	s_mov_b32 m0, s73
	s_nop 0
	global_load_lds_dwordx4 v[226:227], off
	s_waitcnt vmcnt(8)
	s_waitcnt lgkmcnt(0)
	s_barrier
	s_setprio 1
	s_waitcnt lgkmcnt(0)
	v_mfma_f32_16x16x32_bf16 v[44:47], v[64:67], v[190:193], v[44:47]
	v_mfma_f32_16x16x32_bf16 v[36:39], v[152:155], v[190:193], v[36:39]
	v_mfma_f32_16x16x32_bf16 v[124:127], v[64:67], v[198:201], v[124:127]
	v_mfma_f32_16x16x32_bf16 v[120:123], v[152:155], v[198:201], v[120:123]
	v_mfma_f32_16x16x32_bf16 v[108:111], v[64:67], v[206:209], v[108:111]
	v_mfma_f32_16x16x32_bf16 v[104:107], v[152:155], v[206:209], v[104:107]
	v_mfma_f32_16x16x32_bf16 v[92:95], v[64:67], v[214:217], v[92:95]
	v_mfma_f32_16x16x32_bf16 v[88:91], v[152:155], v[214:217], v[88:91]
	v_mfma_f32_16x16x32_bf16 v[44:47], v[68:71], v[194:197], v[44:47]
	v_mfma_f32_16x16x32_bf16 v[36:39], v[166:169], v[194:197], v[36:39]
	v_mfma_f32_16x16x32_bf16 v[124:127], v[68:71], v[202:205], v[124:127]
	v_mfma_f32_16x16x32_bf16 v[120:123], v[166:169], v[202:205], v[120:123]
	v_mfma_f32_16x16x32_bf16 v[108:111], v[68:71], v[210:213], v[108:111]
	v_mfma_f32_16x16x32_bf16 v[104:107], v[166:169], v[210:213], v[104:107]
	v_mfma_f32_16x16x32_bf16 v[92:95], v[68:71], v[218:221], v[92:95]
	v_mfma_f32_16x16x32_bf16 v[88:91], v[166:169], v[218:221], v[88:91]
	v_mfma_f32_16x16x32_bf16 v[132:135], v[170:173], v[190:193], v[132:135]
	v_mfma_f32_16x16x32_bf16 v[128:131], v[182:185], v[190:193], v[128:131]
	v_mfma_f32_16x16x32_bf16 v[116:119], v[170:173], v[198:201], v[116:119]
	v_mfma_f32_16x16x32_bf16 v[112:115], v[182:185], v[198:201], v[112:115]
	v_mfma_f32_16x16x32_bf16 v[100:103], v[170:173], v[206:209], v[100:103]
	v_mfma_f32_16x16x32_bf16 v[96:99], v[182:185], v[206:209], v[96:99]
	v_mfma_f32_16x16x32_bf16 v[84:87], v[170:173], v[214:217], v[84:87]
	v_mfma_f32_16x16x32_bf16 v[80:83], v[182:185], v[214:217], v[80:83]
	v_mfma_f32_16x16x32_bf16 v[132:135], v[178:181], v[194:197], v[132:135]
	v_mfma_f32_16x16x32_bf16 v[128:131], v[186:189], v[194:197], v[128:131]
	v_mfma_f32_16x16x32_bf16 v[116:119], v[178:181], v[202:205], v[116:119]
	v_mfma_f32_16x16x32_bf16 v[112:115], v[186:189], v[202:205], v[112:115]
	v_mfma_f32_16x16x32_bf16 v[100:103], v[178:181], v[210:213], v[100:103]
	v_mfma_f32_16x16x32_bf16 v[96:99], v[186:189], v[210:213], v[96:99]
	v_mfma_f32_16x16x32_bf16 v[84:87], v[178:181], v[218:221], v[84:87]
	v_mfma_f32_16x16x32_bf16 v[80:83], v[186:189], v[218:221], v[80:83]
	s_setprio 0
	s_barrier
; #define PG8_STAGE(bufoff, gbase, voff) do { _Pragma("unroll") for (int _i = 0; _i < 2; ++_i) \
;         __builtin_amdgcn_global_load_lds((const unsigned*)((const char*)(gbase) + (voff)[_i]), (PG8_LAS unsigned*)(lds + (bufoff) + ldsw + _i * 8192), 16, 0, 0); } while (0)
; #define PG8_LDA(dst, b, h) do { _Pragma("unroll") for (int m = 0; m < 4; ++m) _Pragma("unroll") for (int k = 0; k < 2; ++k) dst[m][k] = *(const PG8_LAS bf16x8*)(lds + PG8_SA(b, h) + aoff + m * 2048 + k * 1024); } while (0)
; #define PG8_MMA(ai, bj, At, Bt) do { __builtin_amdgcn_s_setprio(1); _Pragma("unroll") for (int m = 0; m < 4; ++m) _Pragma("unroll") for (int n = 0; n < 2; ++n) _Pragma("unroll") for (int k = 0; k < 2; ++k) \
;         acc[ai][bj][m][n] = __builtin_amdgcn_mfma_f32_16x16x32_bf16(Bt[n][k], At[m][k], acc[ai][bj][m][n], 0, 0, 0); __builtin_amdgcn_s_setprio(0); } while (0)
; #define PG8_WAIT_V(n) asm volatile("s_waitcnt vmcnt(" #n ")" ::: "memory")
; #define PG8_WAIT_L(n) asm volatile("s_waitcnt lgkmcnt(" #n ")" ::: "memory")
; #define PG8_BAR __builtin_amdgcn_s_barrier()
; #define PG8_SCHED __builtin_amdgcn_sched_barrier(0)
; template <class Epi, class Sched, bool ALIGN_EPI = false, bool SP2 = false>
; __device__ __forceinline__ void gemm_phase(PG8_LAS unsigned char* lds, const Gemm g, const Sched& S, const Epi& E) {
;     ...
;             PG8_LDA(At, 1, 1); PG8_STAGE(PG8_SB(1, 0), b3, voffB); PG8_STAGE(PG8_SB(1, 1), b3 + hstep, voffB); PG8_STAGE(PG8_SA(1, 0), a3, voffA);
;             PG8_WAIT_V(8); PG8_WAIT_L(0); PG8_BAR; PG8_MMA(1, 0, At, B0); PG8_MMA(1, 1, At, B1); PG8_BAR; PG8_SCHED;
;     ...
;         if constexpr (ALIGN_EPI) { if (wr == 0) PG8_BAR; }
	s_add_i32 s8, s60, s70
	v_lshl_add_u64 v[156:157], v[156:157], 0, s[20:21]
	s_mov_b32 m0, s8
	ds_read_b128 v[190:193], v164 offset:49152
	ds_read_b128 v[194:197], v164 offset:50176
	ds_read_b128 v[198:201], v164 offset:51200
	ds_read_b128 v[202:205], v164 offset:52224
	ds_read_b128 v[206:209], v164 offset:53248
	ds_read_b128 v[210:213], v164 offset:54272
	ds_read_b128 v[214:217], v164 offset:55296
	ds_read_b128 v[218:221], v164 offset:56320
	global_load_lds_dwordx4 v[156:157], off
	s_add_i32 m0, s8, 0x2000
	s_add_u32 s8, s66, 0x40080
	v_lshl_add_u64 v[156:157], v[174:175], 0, s[20:21]
	s_addc_u32 s9, s67, 0
	s_add_i32 s60, s61, s70
	global_load_lds_dwordx4 v[156:157], off
	v_lshl_add_u64 v[156:157], s[8:9], 0, v[138:139]
	s_mov_b32 m0, s60
	s_nop 0
	global_load_lds_dwordx4 v[156:157], off
	v_lshl_add_u64 v[156:157], s[8:9], 0, v[142:143]
	s_add_i32 m0, s60, 0x2000
	s_nop 0
	global_load_lds_dwordx4 v[156:157], off
	v_lshl_add_u64 v[156:157], v[222:223], 0, s[20:21]
	s_mov_b32 m0, s75
	s_nop 0
	global_load_lds_dwordx4 v[156:157], off
	v_lshl_add_u64 v[156:157], v[224:225], 0, s[20:21]
	s_mov_b32 m0, s76
	s_nop 0
	global_load_lds_dwordx4 v[156:157], off
	s_waitcnt vmcnt(8)
	s_waitcnt lgkmcnt(0)
	s_barrier
	s_setprio 1
	s_waitcnt lgkmcnt(0)
	v_mfma_f32_16x16x32_bf16 v[76:79], v[64:67], v[190:193], v[76:79]
	v_mfma_f32_16x16x32_bf16 v[72:75], v[152:155], v[190:193], v[72:75]
	v_mfma_f32_16x16x32_bf16 v[60:63], v[64:67], v[198:201], v[60:63]
	v_mfma_f32_16x16x32_bf16 v[56:59], v[152:155], v[198:201], v[56:59]
	v_mfma_f32_16x16x32_bf16 v[28:31], v[64:67], v[206:209], v[28:31]
	v_mfma_f32_16x16x32_bf16 v[24:27], v[152:155], v[206:209], v[24:27]
	v_mfma_f32_16x16x32_bf16 v[12:15], v[64:67], v[214:217], v[12:15]
	v_mfma_f32_16x16x32_bf16 v[8:11], v[152:155], v[214:217], v[8:11]
	v_mfma_f32_16x16x32_bf16 v[76:79], v[68:71], v[194:197], v[76:79]
	v_mfma_f32_16x16x32_bf16 v[72:75], v[166:169], v[194:197], v[72:75]
	v_mfma_f32_16x16x32_bf16 v[60:63], v[68:71], v[202:205], v[60:63]
	v_mfma_f32_16x16x32_bf16 v[56:59], v[166:169], v[202:205], v[56:59]
	v_mfma_f32_16x16x32_bf16 v[28:31], v[68:71], v[210:213], v[28:31]
	v_mfma_f32_16x16x32_bf16 v[24:27], v[166:169], v[210:213], v[24:27]
	v_mfma_f32_16x16x32_bf16 v[12:15], v[68:71], v[218:221], v[12:15]
	v_mfma_f32_16x16x32_bf16 v[8:11], v[166:169], v[218:221], v[8:11]
	v_mfma_f32_16x16x32_bf16 v[48:51], v[170:173], v[190:193], v[48:51]
	v_mfma_f32_16x16x32_bf16 v[68:71], v[178:181], v[194:197], v[48:51]
	v_mfma_f32_16x16x32_bf16 v[48:51], v[182:185], v[190:193], v[52:55]
	v_mfma_f32_16x16x32_bf16 v[40:43], v[170:173], v[198:201], v[40:43]
	v_mfma_f32_16x16x32_bf16 v[32:35], v[182:185], v[198:201], v[32:35]
	v_mfma_f32_16x16x32_bf16 v[20:23], v[170:173], v[206:209], v[20:23]
	v_mfma_f32_16x16x32_bf16 v[16:19], v[182:185], v[206:209], v[16:19]
	v_mfma_f32_16x16x32_bf16 v[4:7], v[170:173], v[214:217], v[4:7]
	v_mfma_f32_16x16x32_bf16 v[0:3], v[182:185], v[214:217], v[0:3]
	v_mfma_f32_16x16x32_bf16 v[64:67], v[186:189], v[194:197], v[48:51]
	v_mfma_f32_16x16x32_bf16 v[40:43], v[178:181], v[202:205], v[40:43]
	v_mfma_f32_16x16x32_bf16 v[32:35], v[186:189], v[202:205], v[32:35]
	v_mfma_f32_16x16x32_bf16 v[20:23], v[178:181], v[210:213], v[20:23]
	v_mfma_f32_16x16x32_bf16 v[16:19], v[186:189], v[210:213], v[16:19]
	v_mfma_f32_16x16x32_bf16 v[4:7], v[178:181], v[218:221], v[4:7]
	v_mfma_f32_16x16x32_bf16 v[0:3], v[186:189], v[218:221], v[0:3]
	s_setprio 0
	s_add_i32 s87, s87, 2
	s_add_u32 s64, s64, 0x100
	s_addc_u32 s65, s65, 0
	s_add_u32 s83, s83, 0x100
	s_addc_u32 s86, s86, 0
	s_cmp_gt_u32 s87, 13
	s_barrier
	s_cbranch_scc0 .LBB0_836
	s_and_b64 vcc, exec, s[38:39]
	s_cbranch_vccz .LBB0_839
	s_barrier

; #define PG8_STAGE(bufoff, gbase, voff) do { _Pragma("unroll") for (int _i = 0; _i < 2; ++_i) \
;         __builtin_amdgcn_global_load_lds((const unsigned*)((const char*)(gbase) + (voff)[_i]), (PG8_LAS unsigned*)(lds + (bufoff) + ldsw + _i * 8192), 16, 0, 0); } while (0)
; #define PG8_LDA(dst, b, h) do { _Pragma("unroll") for (int m = 0; m < 4; ++m) _Pragma("unroll") for (int k = 0; k < 2; ++k) dst[m][k] = *(const PG8_LAS bf16x8*)(lds + PG8_SA(b, h) + aoff + m * 2048 + k * 1024); } while (0)
; #define PG8_LDB(dst, b, h) do { _Pragma("unroll") for (int n = 0; n < 2; ++n) _Pragma("unroll") for (int k = 0; k < 2; ++k) dst[n][k] = *(const PG8_LAS bf16x8*)(lds + PG8_SB(b, h) + boff + n * 2048 + k * 1024); } while (0)
; #define PG8_MMA(ai, bj, At, Bt) do { __builtin_amdgcn_s_setprio(1); _Pragma("unroll") for (int m = 0; m < 4; ++m) _Pragma("unroll") for (int n = 0; n < 2; ++n) _Pragma("unroll") for (int k = 0; k < 2; ++k) \
;         acc[ai][bj][m][n] = __builtin_amdgcn_mfma_f32_16x16x32_bf16(Bt[n][k], At[m][k], acc[ai][bj][m][n], 0, 0, 0); __builtin_amdgcn_s_setprio(0); } while (0)
; #define PG8_WAIT_V(n) asm volatile("s_waitcnt vmcnt(" #n ")" ::: "memory")
; template <class Epi, class Sched, bool ALIGN_EPI = false, bool SP2 = false>
; __device__ __forceinline__ void gemm_phase(PG8_LAS unsigned char* lds, const Gemm g, const Sched& S, const Epi& E) {
;     ...
;         const char* nA = has_next ? (const char*)g.A + (size_t)nxt.pm * tstep : cA; const char* nB = has_next ? (const char*)g.Bt + (size_t)nxt.pn * tstep : cB;
;         for (int t = 0; t < nt; t += 2) {
;             const bool last = (t == nt - 2);
;             const char* a1 = cA + (size_t)(t + 1) * kstep;
;             const char* a2 = last ? nA : cA + (size_t)(t + 2) * kstep; const char* b2 = last ? nB : cB + (size_t)(t + 2) * kstep;
;             const char* a3 = a2 + kstep; const char* b3 = b2 + kstep;
;             if (last && has_next) S.a_ready(nxt);
;             if constexpr (SP2) {
;             PG8_LDB(B0, 0, 0); PG8_LDB(B1, 0, 1); PG8_SCHED; PG8_LDA(At, 0, 0); PG8_STAGE(PG8_SA(1, 1), a1 + hstep, voffA);
;             PG8_WAIT_V(8); PG8_WAIT_L(0); PG8_BAR; PG8_MMA(0, 0, At, B0); PG8_MMA(0, 1, At, B1); PG8_BAR; PG8_SCHED;
;             PG8_LDA(At, 0, 1); PG8_STAGE(PG8_SB(0, 0), b2, voffB); PG8_STAGE(PG8_SB(0, 1), b2 + hstep, voffB); PG8_STAGE(PG8_SA(0, 0), a2, voffA);
.LBB0_934:
	ds_read_b128 v[144:147], v155
	ds_read_b128 v[148:151], v155 offset:1024
	ds_read_b128 v[162:165], v155 offset:2048
	ds_read_b128 v[166:169], v155 offset:3072
	ds_read_b128 v[170:173], v156
	ds_read_b128 v[178:181], v156 offset:1024
	ds_read_b128 v[182:185], v156 offset:2048
	ds_read_b128 v[186:189], v156 offset:3072
	s_add_u32 s8, s64, 0xfffc0080
	s_addc_u32 s9, s65, -1
	s_cmp_eq_u32 s96, 12
	s_cselect_b32 s69, s53, s9
	s_cselect_b32 s68, s92, s8
	s_cselect_b32 s67, s51, s95
	s_cselect_b32 s66, s93, s94
	v_lshl_add_u64 v[174:175], s[64:65], 0, v[136:137]
	s_add_i32 m0, s74, 0xc000
	ds_read_b128 v[190:193], v157
	ds_read_b128 v[194:197], v157 offset:1024
	ds_read_b128 v[198:201], v157 offset:2048
	ds_read_b128 v[202:205], v157 offset:3072
	ds_read_b128 v[206:209], v157 offset:4096
	ds_read_b128 v[210:213], v157 offset:5120
	ds_read_b128 v[214:217], v157 offset:6144
	ds_read_b128 v[218:221], v157 offset:7168
	global_load_lds_dwordx4 v[174:175], off
	v_lshl_add_u64 v[174:175], s[64:65], 0, v[138:139]
	s_add_i32 m0, s74, 0xe000
	s_nop 0
	global_load_lds_dwordx4 v[174:175], off
	s_waitcnt vmcnt(8)
	s_waitcnt lgkmcnt(0)
	s_barrier
	s_setprio 1
	s_waitcnt lgkmcnt(0)
	v_mfma_f32_16x16x32_bf16 v[124:127], v[144:147], v[190:193], v[124:127]
	v_mfma_f32_16x16x32_bf16 v[120:123], v[162:165], v[190:193], v[120:123]
	v_mfma_f32_16x16x32_bf16 v[108:111], v[144:147], v[198:201], v[108:111]
	v_mfma_f32_16x16x32_bf16 v[104:107], v[162:165], v[198:201], v[104:107]
	v_mfma_f32_16x16x32_bf16 v[92:95], v[144:147], v[206:209], v[92:95]
	v_mfma_f32_16x16x32_bf16 v[88:91], v[162:165], v[206:209], v[88:91]
	v_mfma_f32_16x16x32_bf16 v[76:79], v[144:147], v[214:217], v[76:79]
	v_mfma_f32_16x16x32_bf16 v[72:75], v[162:165], v[214:217], v[72:75]
	v_mfma_f32_16x16x32_bf16 v[124:127], v[148:151], v[194:197], v[124:127]
	v_mfma_f32_16x16x32_bf16 v[120:123], v[166:169], v[194:197], v[120:123]
	v_mfma_f32_16x16x32_bf16 v[108:111], v[148:151], v[202:205], v[108:111]
	v_mfma_f32_16x16x32_bf16 v[104:107], v[166:169], v[202:205], v[104:107]
	v_mfma_f32_16x16x32_bf16 v[92:95], v[148:151], v[210:213], v[92:95]
	v_mfma_f32_16x16x32_bf16 v[88:91], v[166:169], v[210:213], v[88:91]
	v_mfma_f32_16x16x32_bf16 v[76:79], v[148:151], v[218:221], v[76:79]
	v_mfma_f32_16x16x32_bf16 v[72:75], v[166:169], v[218:221], v[72:75]
	v_mfma_f32_16x16x32_bf16 v[116:119], v[170:173], v[190:193], v[116:119]
	v_mfma_f32_16x16x32_bf16 v[112:115], v[182:185], v[190:193], v[112:115]
	v_mfma_f32_16x16x32_bf16 v[100:103], v[170:173], v[198:201], v[100:103]
	v_mfma_f32_16x16x32_bf16 v[96:99], v[182:185], v[198:201], v[96:99]
	v_mfma_f32_16x16x32_bf16 v[84:87], v[170:173], v[206:209], v[84:87]
	v_mfma_f32_16x16x32_bf16 v[80:83], v[182:185], v[206:209], v[80:83]
	v_mfma_f32_16x16x32_bf16 v[68:71], v[170:173], v[214:217], v[68:71]
	v_mfma_f32_16x16x32_bf16 v[64:67], v[182:185], v[214:217], v[64:67]
	v_mfma_f32_16x16x32_bf16 v[116:119], v[178:181], v[194:197], v[116:119]
	v_mfma_f32_16x16x32_bf16 v[112:115], v[186:189], v[194:197], v[112:115]
	v_mfma_f32_16x16x32_bf16 v[100:103], v[178:181], v[202:205], v[100:103]
	v_mfma_f32_16x16x32_bf16 v[96:99], v[186:189], v[202:205], v[96:99]
	v_mfma_f32_16x16x32_bf16 v[84:87], v[178:181], v[210:213], v[84:87]
	v_mfma_f32_16x16x32_bf16 v[80:83], v[186:189], v[210:213], v[80:83]
	v_mfma_f32_16x16x32_bf16 v[68:71], v[178:181], v[218:221], v[68:71]
	v_mfma_f32_16x16x32_bf16 v[64:67], v[186:189], v[218:221], v[64:67]
	s_setprio 0
	s_barrier
	s_add_i32 s8, s83, s73
	v_lshl_add_u64 v[174:175], s[66:67], 0, v[130:131]
	s_mov_b32 m0, s8
	ds_read_b128 v[190:193], v157 offset:16384
	ds_read_b128 v[194:197], v157 offset:17408
	ds_read_b128 v[198:201], v157 offset:18432
	ds_read_b128 v[202:205], v157 offset:19456
	ds_read_b128 v[206:209], v157 offset:20480
	ds_read_b128 v[210:213], v157 offset:21504
	ds_read_b128 v[214:217], v157 offset:22528
	ds_read_b128 v[218:221], v157 offset:23552
	global_load_lds_dwordx4 v[174:175], off
	s_add_i32 m0, s8, 0x2000
	s_add_u32 s8, s66, 0x40000
	v_lshl_add_u64 v[222:223], s[66:67], 0, v[134:135]
	s_addc_u32 s9, s67, 0
	s_add_i32 s60, s86, s73
	global_load_lds_dwordx4 v[222:223], off
	v_lshl_add_u64 v[224:225], s[8:9], 0, v[130:131]
	s_mov_b32 m0, s60
	v_lshl_add_u64 v[226:227], s[68:69], 0, v[132:133]
	global_load_lds_dwordx4 v[224:225], off
	v_lshl_add_u64 v[224:225], s[8:9], 0, v[134:135]
	s_add_i32 m0, s60, 0x2000
	s_nop 0
	global_load_lds_dwordx4 v[224:225], off
	v_lshl_add_u64 v[224:225], s[68:69], 0, v[128:129]
	s_mov_b32 m0, s74
	s_nop 0
	global_load_lds_dwordx4 v[224:225], off
	s_mov_b32 m0, s75
	s_nop 0
	global_load_lds_dwordx4 v[226:227], off
	s_waitcnt vmcnt(8)
	s_waitcnt lgkmcnt(0)
	s_barrier
; #define PG8_STAGE(bufoff, gbase, voff) do { _Pragma("unroll") for (int _i = 0; _i < 2; ++_i) \
;         __builtin_amdgcn_global_load_lds((const unsigned*)((const char*)(gbase) + (voff)[_i]), (PG8_LAS unsigned*)(lds + (bufoff) + ldsw + _i * 8192), 16, 0, 0); } while (0)
; #define PG8_LDA(dst, b, h) do { _Pragma("unroll") for (int m = 0; m < 4; ++m) _Pragma("unroll") for (int k = 0; k < 2; ++k) dst[m][k] = *(const PG8_LAS bf16x8*)(lds + PG8_SA(b, h) + aoff + m * 2048 + k * 1024); } while (0)
; #define PG8_LDB(dst, b, h) do { _Pragma("unroll") for (int n = 0; n < 2; ++n) _Pragma("unroll") for (int k = 0; k < 2; ++k) dst[n][k] = *(const PG8_LAS bf16x8*)(lds + PG8_SB(b, h) + boff + n * 2048 + k * 1024); } while (0)
; #define PG8_MMA(ai, bj, At, Bt) do { __builtin_amdgcn_s_setprio(1); _Pragma("unroll") for (int m = 0; m < 4; ++m) _Pragma("unroll") for (int n = 0; n < 2; ++n) _Pragma("unroll") for (int k = 0; k < 2; ++k) \
;         acc[ai][bj][m][n] = __builtin_amdgcn_mfma_f32_16x16x32_bf16(Bt[n][k], At[m][k], acc[ai][bj][m][n], 0, 0, 0); __builtin_amdgcn_s_setprio(0); } while (0)
; #define PG8_WAIT_V(n) asm volatile("s_waitcnt vmcnt(" #n ")" ::: "memory")
; #define PG8_WAIT_L(n) asm volatile("s_waitcnt lgkmcnt(" #n ")" ::: "memory")
; #define PG8_BAR __builtin_amdgcn_s_barrier()
; #define PG8_SCHED __builtin_amdgcn_sched_barrier(0)
; template <class Epi, class Sched, bool ALIGN_EPI = false, bool SP2 = false>
; __device__ __forceinline__ void gemm_phase(PG8_LAS unsigned char* lds, const Gemm g, const Sched& S, const Epi& E) {
;     ...
;             PG8_WAIT_V(8); PG8_WAIT_L(0); PG8_BAR; PG8_MMA(1, 0, At, B0); PG8_MMA(1, 1, At, B1); PG8_BAR; PG8_SCHED;
;             PG8_LDB(B0, 1, 0); PG8_LDB(B1, 1, 1); PG8_SCHED; PG8_LDA(At, 1, 0); PG8_STAGE(PG8_SA(0, 1), a2 + hstep, voffA);
;             PG8_WAIT_V(8); PG8_WAIT_L(0); PG8_BAR; PG8_MMA(0, 0, At, B0); PG8_MMA(0, 1, At, B1); PG8_BAR; PG8_SCHED;
	s_setprio 1
	s_waitcnt lgkmcnt(0)
	v_mfma_f32_16x16x32_bf16 v[60:63], v[144:147], v[190:193], v[60:63]
	v_mfma_f32_16x16x32_bf16 v[56:59], v[162:165], v[190:193], v[56:59]
	v_mfma_f32_16x16x32_bf16 v[44:47], v[144:147], v[198:201], v[44:47]
	v_mfma_f32_16x16x32_bf16 v[40:43], v[162:165], v[198:201], v[40:43]
	v_mfma_f32_16x16x32_bf16 v[28:31], v[144:147], v[206:209], v[28:31]
	v_mfma_f32_16x16x32_bf16 v[24:27], v[162:165], v[206:209], v[24:27]
	v_mfma_f32_16x16x32_bf16 v[12:15], v[144:147], v[214:217], v[12:15]
	v_mfma_f32_16x16x32_bf16 v[8:11], v[162:165], v[214:217], v[8:11]
	v_mfma_f32_16x16x32_bf16 v[60:63], v[148:151], v[194:197], v[60:63]
	v_mfma_f32_16x16x32_bf16 v[56:59], v[166:169], v[194:197], v[56:59]
	v_mfma_f32_16x16x32_bf16 v[44:47], v[148:151], v[202:205], v[44:47]
	v_mfma_f32_16x16x32_bf16 v[40:43], v[166:169], v[202:205], v[40:43]
	v_mfma_f32_16x16x32_bf16 v[28:31], v[148:151], v[210:213], v[28:31]
	v_mfma_f32_16x16x32_bf16 v[24:27], v[166:169], v[210:213], v[24:27]
	v_mfma_f32_16x16x32_bf16 v[12:15], v[148:151], v[218:221], v[12:15]
	v_mfma_f32_16x16x32_bf16 v[8:11], v[166:169], v[218:221], v[8:11]
	v_mfma_f32_16x16x32_bf16 v[52:55], v[170:173], v[190:193], v[52:55]
	v_mfma_f32_16x16x32_bf16 v[48:51], v[182:185], v[190:193], v[48:51]
	v_mfma_f32_16x16x32_bf16 v[36:39], v[170:173], v[198:201], v[36:39]
	v_mfma_f32_16x16x32_bf16 v[32:35], v[182:185], v[198:201], v[32:35]
	v_mfma_f32_16x16x32_bf16 v[20:23], v[170:173], v[206:209], v[20:23]
	v_mfma_f32_16x16x32_bf16 v[16:19], v[182:185], v[206:209], v[16:19]
	v_mfma_f32_16x16x32_bf16 v[4:7], v[170:173], v[214:217], v[4:7]
	v_mfma_f32_16x16x32_bf16 v[0:3], v[182:185], v[214:217], v[0:3]
	v_mfma_f32_16x16x32_bf16 v[52:55], v[178:181], v[194:197], v[52:55]
	v_mfma_f32_16x16x32_bf16 v[48:51], v[186:189], v[194:197], v[48:51]
	v_mfma_f32_16x16x32_bf16 v[36:39], v[178:181], v[202:205], v[36:39]
	v_mfma_f32_16x16x32_bf16 v[32:35], v[186:189], v[202:205], v[32:35]
	v_mfma_f32_16x16x32_bf16 v[20:23], v[178:181], v[210:213], v[20:23]
	v_mfma_f32_16x16x32_bf16 v[16:19], v[186:189], v[210:213], v[16:19]
	v_mfma_f32_16x16x32_bf16 v[4:7], v[178:181], v[218:221], v[4:7]
	v_mfma_f32_16x16x32_bf16 v[0:3], v[186:189], v[218:221], v[0:3]
	s_setprio 0
	s_barrier
	s_add_i32 s60, 0, 0x18000
	v_add_u32_e32 v161, s60, v153
	s_add_i32 s61, 0, 0x1c000
	ds_read_b128 v[144:147], v161
	ds_read_b128 v[148:151], v161 offset:1024
	ds_read_b128 v[162:165], v161 offset:2048
	ds_read_b128 v[166:169], v161 offset:3072
	v_add_u32_e32 v161, s61, v153
	ds_read_b128 v[170:173], v161
	ds_read_b128 v[178:181], v161 offset:1024
	ds_read_b128 v[182:185], v161 offset:2048
	ds_read_b128 v[186:189], v161 offset:3072
	s_add_u32 s8, s68, 0x40000
	s_addc_u32 s9, s69, 0
	s_mov_b32 m0, s76
	v_lshl_add_u64 v[228:229], s[8:9], 0, v[128:129]
	ds_read_b128 v[190:193], v157 offset:32768
	ds_read_b128 v[194:197], v157 offset:33792
	ds_read_b128 v[198:201], v157 offset:34816
	ds_read_b128 v[202:205], v157 offset:35840
	ds_read_b128 v[206:209], v157 offset:36864
	ds_read_b128 v[210:213], v157 offset:37888
	ds_read_b128 v[214:217], v157 offset:38912
	ds_read_b128 v[218:221], v157 offset:39936
	global_load_lds_dwordx4 v[228:229], off
	v_lshl_add_u64 v[228:229], s[8:9], 0, v[132:133]
	s_mov_b32 m0, s77
	s_nop 0
	global_load_lds_dwordx4 v[228:229], off
	s_waitcnt vmcnt(8)
	s_waitcnt lgkmcnt(0)
	s_barrier
	s_setprio 1
	s_waitcnt lgkmcnt(0)
	v_mfma_f32_16x16x32_bf16 v[124:127], v[144:147], v[190:193], v[124:127]
	v_mfma_f32_16x16x32_bf16 v[120:123], v[162:165], v[190:193], v[120:123]
	v_mfma_f32_16x16x32_bf16 v[108:111], v[144:147], v[198:201], v[108:111]
	v_mfma_f32_16x16x32_bf16 v[104:107], v[162:165], v[198:201], v[104:107]
	v_mfma_f32_16x16x32_bf16 v[92:95], v[144:147], v[206:209], v[92:95]
	v_mfma_f32_16x16x32_bf16 v[88:91], v[162:165], v[206:209], v[88:91]
	v_mfma_f32_16x16x32_bf16 v[76:79], v[144:147], v[214:217], v[76:79]
	v_mfma_f32_16x16x32_bf16 v[72:75], v[162:165], v[214:217], v[72:75]
	v_mfma_f32_16x16x32_bf16 v[124:127], v[148:151], v[194:197], v[124:127]
	v_mfma_f32_16x16x32_bf16 v[120:123], v[166:169], v[194:197], v[120:123]
	v_mfma_f32_16x16x32_bf16 v[108:111], v[148:151], v[202:205], v[108:111]
	v_mfma_f32_16x16x32_bf16 v[104:107], v[166:169], v[202:205], v[104:107]
	v_mfma_f32_16x16x32_bf16 v[92:95], v[148:151], v[210:213], v[92:95]
	v_mfma_f32_16x16x32_bf16 v[88:91], v[166:169], v[210:213], v[88:91]
	v_mfma_f32_16x16x32_bf16 v[76:79], v[148:151], v[218:221], v[76:79]
	v_mfma_f32_16x16x32_bf16 v[72:75], v[166:169], v[218:221], v[72:75]
	v_mfma_f32_16x16x32_bf16 v[116:119], v[170:173], v[190:193], v[116:119]
	v_mfma_f32_16x16x32_bf16 v[112:115], v[182:185], v[190:193], v[112:115]
	v_mfma_f32_16x16x32_bf16 v[100:103], v[170:173], v[198:201], v[100:103]
	v_mfma_f32_16x16x32_bf16 v[96:99], v[182:185], v[198:201], v[96:99]
	v_mfma_f32_16x16x32_bf16 v[84:87], v[170:173], v[206:209], v[84:87]
	v_mfma_f32_16x16x32_bf16 v[80:83], v[182:185], v[206:209], v[80:83]
	v_mfma_f32_16x16x32_bf16 v[68:71], v[170:173], v[214:217], v[68:71]
	v_mfma_f32_16x16x32_bf16 v[64:67], v[182:185], v[214:217], v[64:67]
	v_mfma_f32_16x16x32_bf16 v[116:119], v[178:181], v[194:197], v[116:119]
	v_mfma_f32_16x16x32_bf16 v[112:115], v[186:189], v[194:197], v[112:115]
	v_mfma_f32_16x16x32_bf16 v[100:103], v[178:181], v[202:205], v[100:103]
	v_mfma_f32_16x16x32_bf16 v[96:99], v[186:189], v[202:205], v[96:99]
	v_mfma_f32_16x16x32_bf16 v[84:87], v[178:181], v[210:213], v[84:87]
	v_mfma_f32_16x16x32_bf16 v[80:83], v[186:189], v[210:213], v[80:83]
	v_mfma_f32_16x16x32_bf16 v[68:71], v[178:181], v[218:221], v[68:71]
	v_mfma_f32_16x16x32_bf16 v[64:67], v[186:189], v[218:221], v[64:67]
	s_setprio 0
	s_barrier
; #define PG8_STAGE(bufoff, gbase, voff) do { _Pragma("unroll") for (int _i = 0; _i < 2; ++_i) \
;         __builtin_amdgcn_global_load_lds((const unsigned*)((const char*)(gbase) + (voff)[_i]), (PG8_LAS unsigned*)(lds + (bufoff) + ldsw + _i * 8192), 16, 0, 0); } while (0)
; #define PG8_LDA(dst, b, h) do { _Pragma("unroll") for (int m = 0; m < 4; ++m) _Pragma("unroll") for (int k = 0; k < 2; ++k) dst[m][k] = *(const PG8_LAS bf16x8*)(lds + PG8_SA(b, h) + aoff + m * 2048 + k * 1024); } while (0)
; #define PG8_MMA(ai, bj, At, Bt) do { __builtin_amdgcn_s_setprio(1); _Pragma("unroll") for (int m = 0; m < 4; ++m) _Pragma("unroll") for (int n = 0; n < 2; ++n) _Pragma("unroll") for (int k = 0; k < 2; ++k) \
;         acc[ai][bj][m][n] = __builtin_amdgcn_mfma_f32_16x16x32_bf16(Bt[n][k], At[m][k], acc[ai][bj][m][n], 0, 0, 0); __builtin_amdgcn_s_setprio(0); } while (0)
; #define PG8_WAIT_V(n) asm volatile("s_waitcnt vmcnt(" #n ")" ::: "memory")
; #define PG8_WAIT_L(n) asm volatile("s_waitcnt lgkmcnt(" #n ")" ::: "memory")
; #define PG8_BAR __builtin_amdgcn_s_barrier()
; #define PG8_SCHED __builtin_amdgcn_sched_barrier(0)
; template <class Epi, class Sched, bool ALIGN_EPI = false, bool SP2 = false>
; __device__ __forceinline__ void gemm_phase(PG8_LAS unsigned char* lds, const Gemm g, const Sched& S, const Epi& E) {
;     ...
;             PG8_LDA(At, 1, 1); PG8_STAGE(PG8_SB(1, 0), b3, voffB); PG8_STAGE(PG8_SB(1, 1), b3 + hstep, voffB); PG8_STAGE(PG8_SA(1, 0), a3, voffA);
;             PG8_WAIT_V(8); PG8_WAIT_L(0); PG8_BAR; PG8_MMA(1, 0, At, B0); PG8_MMA(1, 1, At, B1); PG8_BAR; PG8_SCHED;
;     ...
;         if constexpr (ALIGN_EPI) { if (wr == 0) PG8_BAR; }
	s_add_i32 s8, s60, s73
	v_lshl_add_u64 v[174:175], v[174:175], 0, s[14:15]
	s_mov_b32 m0, s8
	ds_read_b128 v[190:193], v157 offset:49152
	ds_read_b128 v[194:197], v157 offset:50176
	ds_read_b128 v[198:201], v157 offset:51200
	ds_read_b128 v[202:205], v157 offset:52224
	ds_read_b128 v[206:209], v157 offset:53248
	ds_read_b128 v[210:213], v157 offset:54272
	ds_read_b128 v[214:217], v157 offset:55296
	ds_read_b128 v[218:221], v157 offset:56320
	global_load_lds_dwordx4 v[174:175], off
	s_add_i32 m0, s8, 0x2000
	s_add_u32 s8, s66, 0x40080
	v_lshl_add_u64 v[174:175], v[222:223], 0, s[14:15]
	s_addc_u32 s9, s67, 0
	s_add_i32 s60, s61, s73
	global_load_lds_dwordx4 v[174:175], off
	v_lshl_add_u64 v[174:175], s[8:9], 0, v[130:131]
	s_mov_b32 m0, s60
	s_nop 0
	global_load_lds_dwordx4 v[174:175], off
	v_lshl_add_u64 v[174:175], s[8:9], 0, v[134:135]
	s_add_i32 m0, s60, 0x2000
	s_nop 0
	global_load_lds_dwordx4 v[174:175], off
	v_lshl_add_u64 v[174:175], v[224:225], 0, s[14:15]
	s_mov_b32 m0, s79
	s_nop 0
	global_load_lds_dwordx4 v[174:175], off
	v_lshl_add_u64 v[174:175], v[226:227], 0, s[14:15]
	s_mov_b32 m0, s80
	s_nop 0
	global_load_lds_dwordx4 v[174:175], off
	s_waitcnt vmcnt(8)
	s_waitcnt lgkmcnt(0)
	s_barrier
	s_setprio 1
	s_waitcnt lgkmcnt(0)
	v_mfma_f32_16x16x32_bf16 v[60:63], v[144:147], v[190:193], v[60:63]
	v_mfma_f32_16x16x32_bf16 v[56:59], v[162:165], v[190:193], v[56:59]
	v_mfma_f32_16x16x32_bf16 v[44:47], v[144:147], v[198:201], v[44:47]
	v_mfma_f32_16x16x32_bf16 v[40:43], v[162:165], v[198:201], v[40:43]
	v_mfma_f32_16x16x32_bf16 v[28:31], v[144:147], v[206:209], v[28:31]
	v_mfma_f32_16x16x32_bf16 v[24:27], v[162:165], v[206:209], v[24:27]
	v_mfma_f32_16x16x32_bf16 v[12:15], v[144:147], v[214:217], v[12:15]
	v_mfma_f32_16x16x32_bf16 v[8:11], v[162:165], v[214:217], v[8:11]
	v_mfma_f32_16x16x32_bf16 v[60:63], v[148:151], v[194:197], v[60:63]
	v_mfma_f32_16x16x32_bf16 v[56:59], v[166:169], v[194:197], v[56:59]
	v_mfma_f32_16x16x32_bf16 v[44:47], v[148:151], v[202:205], v[44:47]
	v_mfma_f32_16x16x32_bf16 v[40:43], v[166:169], v[202:205], v[40:43]
	v_mfma_f32_16x16x32_bf16 v[28:31], v[148:151], v[210:213], v[28:31]
	v_mfma_f32_16x16x32_bf16 v[24:27], v[166:169], v[210:213], v[24:27]
	v_mfma_f32_16x16x32_bf16 v[12:15], v[148:151], v[218:221], v[12:15]
	v_mfma_f32_16x16x32_bf16 v[8:11], v[166:169], v[218:221], v[8:11]
	v_mfma_f32_16x16x32_bf16 v[52:55], v[170:173], v[190:193], v[52:55]
	v_mfma_f32_16x16x32_bf16 v[48:51], v[182:185], v[190:193], v[48:51]
	v_mfma_f32_16x16x32_bf16 v[36:39], v[170:173], v[198:201], v[36:39]
	v_mfma_f32_16x16x32_bf16 v[32:35], v[182:185], v[198:201], v[32:35]
	v_mfma_f32_16x16x32_bf16 v[20:23], v[170:173], v[206:209], v[20:23]
	v_mfma_f32_16x16x32_bf16 v[16:19], v[182:185], v[206:209], v[16:19]
	v_mfma_f32_16x16x32_bf16 v[4:7], v[170:173], v[214:217], v[4:7]
	v_mfma_f32_16x16x32_bf16 v[0:3], v[182:185], v[214:217], v[0:3]
	v_mfma_f32_16x16x32_bf16 v[52:55], v[178:181], v[194:197], v[52:55]
	v_mfma_f32_16x16x32_bf16 v[48:51], v[186:189], v[194:197], v[48:51]
	v_mfma_f32_16x16x32_bf16 v[36:39], v[178:181], v[202:205], v[36:39]
	v_mfma_f32_16x16x32_bf16 v[32:35], v[186:189], v[202:205], v[32:35]
	v_mfma_f32_16x16x32_bf16 v[20:23], v[178:181], v[210:213], v[20:23]
	v_mfma_f32_16x16x32_bf16 v[16:19], v[186:189], v[210:213], v[16:19]
	v_mfma_f32_16x16x32_bf16 v[4:7], v[178:181], v[218:221], v[4:7]
	v_mfma_f32_16x16x32_bf16 v[0:3], v[186:189], v[218:221], v[0:3]
	s_setprio 0
	s_add_i32 s96, s96, 2
	s_add_u32 s64, s64, 0x100
	s_addc_u32 s65, s65, 0
	s_add_u32 s94, s94, 0x100
	s_addc_u32 s95, s95, 0
	s_cmp_gt_u32 s96, 13
	s_barrier
	s_cbranch_scc0 .LBB0_934
	s_and_b64 vcc, exec, s[18:19]
	s_cbranch_vccz .LBB0_937
	s_barrier

; #define PG8_STAGE(bufoff, gbase, voff) do { _Pragma("unroll") for (int _i = 0; _i < 2; ++_i) \
;         __builtin_amdgcn_global_load_lds((const unsigned*)((const char*)(gbase) + (voff)[_i]), (PG8_LAS unsigned*)(lds + (bufoff) + ldsw + _i * 8192), 16, 0, 0); } while (0)
; #define PG8_LDA(dst, b, h) do { _Pragma("unroll") for (int m = 0; m < 4; ++m) _Pragma("unroll") for (int k = 0; k < 2; ++k) dst[m][k] = *(const PG8_LAS bf16x8*)(lds + PG8_SA(b, h) + aoff + m * 2048 + k * 1024); } while (0)
; #define PG8_LDB(dst, b, h) do { _Pragma("unroll") for (int n = 0; n < 2; ++n) _Pragma("unroll") for (int k = 0; k < 2; ++k) dst[n][k] = *(const PG8_LAS bf16x8*)(lds + PG8_SB(b, h) + boff + n * 2048 + k * 1024); } while (0)
; #define PG8_MMA(ai, bj, At, Bt) do { __builtin_amdgcn_s_setprio(1); _Pragma("unroll") for (int m = 0; m < 4; ++m) _Pragma("unroll") for (int n = 0; n < 2; ++n) _Pragma("unroll") for (int k = 0; k < 2; ++k) \
;         acc[ai][bj][m][n] = __builtin_amdgcn_mfma_f32_16x16x32_bf16(Bt[n][k], At[m][k], acc[ai][bj][m][n], 0, 0, 0); __builtin_amdgcn_s_setprio(0); } while (0)
; #define PG8_WAIT_V(n) asm volatile("s_waitcnt vmcnt(" #n ")" ::: "memory")
; template <class Epi, class Sched, bool ALIGN_EPI = false, bool SP2 = false>
; __device__ __forceinline__ void gemm_phase(PG8_LAS unsigned char* lds, const Gemm g, const Sched& S, const Epi& E) {
;     ...
;         const char* nA = has_next ? (const char*)g.A + (size_t)nxt.pm * tstep : cA; const char* nB = has_next ? (const char*)g.Bt + (size_t)nxt.pn * tstep : cB;
;         for (int t = 0; t < nt; t += 2) {
;             const bool last = (t == nt - 2);
;             const char* a1 = cA + (size_t)(t + 1) * kstep;
;             const char* a2 = last ? nA : cA + (size_t)(t + 2) * kstep; const char* b2 = last ? nB : cB + (size_t)(t + 2) * kstep;
;             const char* a3 = a2 + kstep; const char* b3 = b2 + kstep;
;             if (last && has_next) S.a_ready(nxt);
;             if constexpr (SP2) {
;             PG8_LDB(B0, 0, 0); PG8_LDB(B1, 0, 1); PG8_SCHED; PG8_LDA(At, 0, 0); PG8_STAGE(PG8_SA(1, 1), a1 + hstep, voffA);
;             PG8_WAIT_V(8); PG8_WAIT_L(0); PG8_BAR; PG8_MMA(0, 0, At, B0); PG8_MMA(0, 1, At, B1); PG8_BAR; PG8_SCHED;
;             PG8_LDA(At, 0, 1); PG8_STAGE(PG8_SB(0, 0), b2, voffB); PG8_STAGE(PG8_SB(0, 1), b2 + hstep, voffB); PG8_STAGE(PG8_SA(0, 0), a2, voffA);
.LBB0_1172:
	ds_read_b128 v[154:157], v150
	ds_read_b128 v[162:165], v150 offset:1024
	ds_read_b128 v[166:169], v150 offset:2048
	ds_read_b128 v[170:173], v150 offset:3072
	ds_read_b128 v[178:181], v151
	ds_read_b128 v[182:185], v151 offset:1024
	ds_read_b128 v[186:189], v151 offset:2048
	ds_read_b128 v[190:193], v151 offset:3072
	s_add_u32 s8, s52, 0xfffc0080
	s_addc_u32 s9, s53, -1
	s_cmp_eq_u32 s87, 12
	s_cselect_b32 s57, s45, s9
	s_cselect_b32 s56, s81, s8
	s_cselect_b32 s55, s43, s86
	s_cselect_b32 s54, s82, s83
	v_lshl_add_u64 v[146:147], s[52:53], 0, v[136:137]
	s_add_i32 m0, s51, 0xc000
	ds_read_b128 v[194:197], v152
	ds_read_b128 v[198:201], v152 offset:1024
	ds_read_b128 v[202:205], v152 offset:2048
	ds_read_b128 v[206:209], v152 offset:3072
	ds_read_b128 v[210:213], v152 offset:4096
	ds_read_b128 v[214:217], v152 offset:5120
	ds_read_b128 v[218:221], v152 offset:6144
	ds_read_b128 v[222:225], v152 offset:7168
	global_load_lds_dwordx4 v[146:147], off
	v_lshl_add_u64 v[146:147], s[52:53], 0, v[138:139]
	s_add_i32 m0, s51, 0xe000
	s_nop 0
	global_load_lds_dwordx4 v[146:147], off
	s_waitcnt vmcnt(8)
	s_waitcnt lgkmcnt(0)
	s_barrier
	s_setprio 1
	s_waitcnt lgkmcnt(0)
	v_mfma_f32_16x16x32_bf16 v[124:127], v[154:157], v[194:197], v[124:127]
	v_mfma_f32_16x16x32_bf16 v[120:123], v[166:169], v[194:197], v[120:123]
	v_mfma_f32_16x16x32_bf16 v[112:115], v[154:157], v[202:205], v[112:115]
	v_mfma_f32_16x16x32_bf16 v[104:107], v[166:169], v[202:205], v[104:107]
	v_mfma_f32_16x16x32_bf16 v[96:99], v[154:157], v[210:213], v[96:99]
	v_mfma_f32_16x16x32_bf16 v[88:91], v[166:169], v[210:213], v[88:91]
	v_mfma_f32_16x16x32_bf16 v[80:83], v[154:157], v[218:221], v[80:83]
	v_mfma_f32_16x16x32_bf16 v[72:75], v[166:169], v[218:221], v[72:75]
	v_mfma_f32_16x16x32_bf16 v[124:127], v[162:165], v[198:201], v[124:127]
	v_mfma_f32_16x16x32_bf16 v[120:123], v[170:173], v[198:201], v[120:123]
	v_mfma_f32_16x16x32_bf16 v[112:115], v[162:165], v[206:209], v[112:115]
	v_mfma_f32_16x16x32_bf16 v[104:107], v[170:173], v[206:209], v[104:107]
	v_mfma_f32_16x16x32_bf16 v[96:99], v[162:165], v[214:217], v[96:99]
	v_mfma_f32_16x16x32_bf16 v[88:91], v[170:173], v[214:217], v[88:91]
	v_mfma_f32_16x16x32_bf16 v[80:83], v[162:165], v[222:225], v[80:83]
	v_mfma_f32_16x16x32_bf16 v[72:75], v[170:173], v[222:225], v[72:75]
	v_mfma_f32_16x16x32_bf16 v[116:119], v[178:181], v[194:197], v[116:119]
	v_mfma_f32_16x16x32_bf16 v[108:111], v[186:189], v[194:197], v[108:111]
	v_mfma_f32_16x16x32_bf16 v[100:103], v[178:181], v[202:205], v[100:103]
	v_mfma_f32_16x16x32_bf16 v[92:95], v[186:189], v[202:205], v[92:95]
	v_mfma_f32_16x16x32_bf16 v[84:87], v[178:181], v[210:213], v[84:87]
	v_mfma_f32_16x16x32_bf16 v[76:79], v[186:189], v[210:213], v[76:79]
	v_mfma_f32_16x16x32_bf16 v[68:71], v[178:181], v[218:221], v[68:71]
	v_mfma_f32_16x16x32_bf16 v[64:67], v[186:189], v[218:221], v[64:67]
	v_mfma_f32_16x16x32_bf16 v[116:119], v[182:185], v[198:201], v[116:119]
	v_mfma_f32_16x16x32_bf16 v[108:111], v[190:193], v[198:201], v[108:111]
	v_mfma_f32_16x16x32_bf16 v[100:103], v[182:185], v[206:209], v[100:103]
	v_mfma_f32_16x16x32_bf16 v[92:95], v[190:193], v[206:209], v[92:95]
	v_mfma_f32_16x16x32_bf16 v[84:87], v[182:185], v[214:217], v[84:87]
	v_mfma_f32_16x16x32_bf16 v[76:79], v[190:193], v[214:217], v[76:79]
	v_mfma_f32_16x16x32_bf16 v[68:71], v[182:185], v[222:225], v[68:71]
	v_mfma_f32_16x16x32_bf16 v[64:67], v[190:193], v[222:225], v[64:67]
	s_setprio 0
	s_barrier
	s_add_i32 s8, s74, s65
	v_lshl_add_u64 v[146:147], s[54:55], 0, v[130:131]
	s_mov_b32 m0, s8
	ds_read_b128 v[194:197], v152 offset:16384
	ds_read_b128 v[198:201], v152 offset:17408
	ds_read_b128 v[202:205], v152 offset:18432
	ds_read_b128 v[206:209], v152 offset:19456
	ds_read_b128 v[210:213], v152 offset:20480
	ds_read_b128 v[214:217], v152 offset:21504
	ds_read_b128 v[218:221], v152 offset:22528
	ds_read_b128 v[222:225], v152 offset:23552
	global_load_lds_dwordx4 v[146:147], off
	s_add_i32 m0, s8, 0x2000
	s_add_u32 s8, s54, 0x40000
	v_lshl_add_u64 v[158:159], s[54:55], 0, v[134:135]
	s_addc_u32 s9, s55, 0
	s_add_i32 s60, s75, s65
	global_load_lds_dwordx4 v[158:159], off
	v_lshl_add_u64 v[174:175], s[8:9], 0, v[130:131]
	s_mov_b32 m0, s60
	v_lshl_add_u64 v[226:227], s[56:57], 0, v[132:133]
	global_load_lds_dwordx4 v[174:175], off
	v_lshl_add_u64 v[174:175], s[8:9], 0, v[134:135]
	s_add_i32 m0, s60, 0x2000
	s_nop 0
	global_load_lds_dwordx4 v[174:175], off
	v_lshl_add_u64 v[174:175], s[56:57], 0, v[128:129]
	s_mov_b32 m0, s51
	s_nop 0
	global_load_lds_dwordx4 v[174:175], off
	s_mov_b32 m0, s66
	s_nop 0
	global_load_lds_dwordx4 v[226:227], off
	s_waitcnt vmcnt(8)
	s_waitcnt lgkmcnt(0)
	s_barrier
; #define PG8_STAGE(bufoff, gbase, voff) do { _Pragma("unroll") for (int _i = 0; _i < 2; ++_i) \
;         __builtin_amdgcn_global_load_lds((const unsigned*)((const char*)(gbase) + (voff)[_i]), (PG8_LAS unsigned*)(lds + (bufoff) + ldsw + _i * 8192), 16, 0, 0); } while (0)
; #define PG8_LDA(dst, b, h) do { _Pragma("unroll") for (int m = 0; m < 4; ++m) _Pragma("unroll") for (int k = 0; k < 2; ++k) dst[m][k] = *(const PG8_LAS bf16x8*)(lds + PG8_SA(b, h) + aoff + m * 2048 + k * 1024); } while (0)
; #define PG8_LDB(dst, b, h) do { _Pragma("unroll") for (int n = 0; n < 2; ++n) _Pragma("unroll") for (int k = 0; k < 2; ++k) dst[n][k] = *(const PG8_LAS bf16x8*)(lds + PG8_SB(b, h) + boff + n * 2048 + k * 1024); } while (0)
; #define PG8_MMA(ai, bj, At, Bt) do { __builtin_amdgcn_s_setprio(1); _Pragma("unroll") for (int m = 0; m < 4; ++m) _Pragma("unroll") for (int n = 0; n < 2; ++n) _Pragma("unroll") for (int k = 0; k < 2; ++k) \
;         acc[ai][bj][m][n] = __builtin_amdgcn_mfma_f32_16x16x32_bf16(Bt[n][k], At[m][k], acc[ai][bj][m][n], 0, 0, 0); __builtin_amdgcn_s_setprio(0); } while (0)
; #define PG8_WAIT_V(n) asm volatile("s_waitcnt vmcnt(" #n ")" ::: "memory")
; #define PG8_WAIT_L(n) asm volatile("s_waitcnt lgkmcnt(" #n ")" ::: "memory")
; #define PG8_BAR __builtin_amdgcn_s_barrier()
; #define PG8_SCHED __builtin_amdgcn_sched_barrier(0)
; template <class Epi, class Sched, bool ALIGN_EPI = false, bool SP2 = false>
; __device__ __forceinline__ void gemm_phase(PG8_LAS unsigned char* lds, const Gemm g, const Sched& S, const Epi& E) {
;     ...
;             PG8_WAIT_V(8); PG8_WAIT_L(0); PG8_BAR; PG8_MMA(1, 0, At, B0); PG8_MMA(1, 1, At, B1); PG8_BAR; PG8_SCHED;
;             PG8_LDB(B0, 1, 0); PG8_LDB(B1, 1, 1); PG8_SCHED; PG8_LDA(At, 1, 0); PG8_STAGE(PG8_SA(0, 1), a2 + hstep, voffA);
;             PG8_WAIT_V(8); PG8_WAIT_L(0); PG8_BAR; PG8_MMA(0, 0, At, B0); PG8_MMA(0, 1, At, B1); PG8_BAR; PG8_SCHED;
	s_setprio 1
	s_waitcnt lgkmcnt(0)
	v_mfma_f32_16x16x32_bf16 v[60:63], v[154:157], v[194:197], v[60:63]
	v_mfma_f32_16x16x32_bf16 v[56:59], v[166:169], v[194:197], v[56:59]
	v_mfma_f32_16x16x32_bf16 v[48:51], v[154:157], v[202:205], v[48:51]
	v_mfma_f32_16x16x32_bf16 v[40:43], v[166:169], v[202:205], v[40:43]
	v_mfma_f32_16x16x32_bf16 v[32:35], v[154:157], v[210:213], v[32:35]
	v_mfma_f32_16x16x32_bf16 v[24:27], v[166:169], v[210:213], v[24:27]
	v_mfma_f32_16x16x32_bf16 v[16:19], v[154:157], v[218:221], v[16:19]
	v_mfma_f32_16x16x32_bf16 v[8:11], v[166:169], v[218:221], v[8:11]
	v_mfma_f32_16x16x32_bf16 v[60:63], v[162:165], v[198:201], v[60:63]
	v_mfma_f32_16x16x32_bf16 v[56:59], v[170:173], v[198:201], v[56:59]
	v_mfma_f32_16x16x32_bf16 v[48:51], v[162:165], v[206:209], v[48:51]
	v_mfma_f32_16x16x32_bf16 v[40:43], v[170:173], v[206:209], v[40:43]
	v_mfma_f32_16x16x32_bf16 v[32:35], v[162:165], v[214:217], v[32:35]
	v_mfma_f32_16x16x32_bf16 v[24:27], v[170:173], v[214:217], v[24:27]
	v_mfma_f32_16x16x32_bf16 v[16:19], v[162:165], v[222:225], v[16:19]
	v_mfma_f32_16x16x32_bf16 v[8:11], v[170:173], v[222:225], v[8:11]
	v_mfma_f32_16x16x32_bf16 v[52:55], v[178:181], v[194:197], v[52:55]
	v_mfma_f32_16x16x32_bf16 v[44:47], v[186:189], v[194:197], v[44:47]
	v_mfma_f32_16x16x32_bf16 v[36:39], v[178:181], v[202:205], v[36:39]
	v_mfma_f32_16x16x32_bf16 v[28:31], v[186:189], v[202:205], v[28:31]
	v_mfma_f32_16x16x32_bf16 v[20:23], v[178:181], v[210:213], v[20:23]
	v_mfma_f32_16x16x32_bf16 v[12:15], v[186:189], v[210:213], v[12:15]
	v_mfma_f32_16x16x32_bf16 v[4:7], v[178:181], v[218:221], v[4:7]
	v_mfma_f32_16x16x32_bf16 v[0:3], v[186:189], v[218:221], v[0:3]
	v_mfma_f32_16x16x32_bf16 v[52:55], v[182:185], v[198:201], v[52:55]
	v_mfma_f32_16x16x32_bf16 v[44:47], v[190:193], v[198:201], v[44:47]
	v_mfma_f32_16x16x32_bf16 v[36:39], v[182:185], v[206:209], v[36:39]
	v_mfma_f32_16x16x32_bf16 v[28:31], v[190:193], v[206:209], v[28:31]
	v_mfma_f32_16x16x32_bf16 v[20:23], v[182:185], v[214:217], v[20:23]
	v_mfma_f32_16x16x32_bf16 v[12:15], v[190:193], v[214:217], v[12:15]
	v_mfma_f32_16x16x32_bf16 v[4:7], v[182:185], v[222:225], v[4:7]
	v_mfma_f32_16x16x32_bf16 v[0:3], v[190:193], v[222:225], v[0:3]
	s_setprio 0
	s_barrier
	s_add_i32 s60, 0, 0x18000
	v_add_u32_e32 v144, s60, v148
	s_add_i32 s61, 0, 0x1c000
	ds_read_b128 v[154:157], v144
	ds_read_b128 v[162:165], v144 offset:1024
	ds_read_b128 v[166:169], v144 offset:2048
	ds_read_b128 v[170:173], v144 offset:3072
	v_add_u32_e32 v144, s61, v148
	ds_read_b128 v[178:181], v144
	ds_read_b128 v[182:185], v144 offset:1024
	ds_read_b128 v[186:189], v144 offset:2048
	ds_read_b128 v[190:193], v144 offset:3072
	s_add_u32 s8, s56, 0x40000
	s_addc_u32 s9, s57, 0
	s_mov_b32 m0, s67
	v_lshl_add_u64 v[228:229], s[8:9], 0, v[128:129]
	ds_read_b128 v[194:197], v152 offset:32768
	ds_read_b128 v[198:201], v152 offset:33792
	ds_read_b128 v[202:205], v152 offset:34816
	ds_read_b128 v[206:209], v152 offset:35840
	ds_read_b128 v[210:213], v152 offset:36864
	ds_read_b128 v[214:217], v152 offset:37888
	ds_read_b128 v[218:221], v152 offset:38912
	ds_read_b128 v[222:225], v152 offset:39936
	global_load_lds_dwordx4 v[228:229], off
	v_lshl_add_u64 v[228:229], s[8:9], 0, v[132:133]
	s_mov_b32 m0, s68
	s_nop 0
	global_load_lds_dwordx4 v[228:229], off
	s_waitcnt vmcnt(8)
	s_waitcnt lgkmcnt(0)
	s_barrier
	s_setprio 1
	s_waitcnt lgkmcnt(0)
	v_mfma_f32_16x16x32_bf16 v[124:127], v[154:157], v[194:197], v[124:127]
	v_mfma_f32_16x16x32_bf16 v[120:123], v[166:169], v[194:197], v[120:123]
	v_mfma_f32_16x16x32_bf16 v[112:115], v[154:157], v[202:205], v[112:115]
	v_mfma_f32_16x16x32_bf16 v[104:107], v[166:169], v[202:205], v[104:107]
	v_mfma_f32_16x16x32_bf16 v[96:99], v[154:157], v[210:213], v[96:99]
	v_mfma_f32_16x16x32_bf16 v[88:91], v[166:169], v[210:213], v[88:91]
	v_mfma_f32_16x16x32_bf16 v[80:83], v[154:157], v[218:221], v[80:83]
	v_mfma_f32_16x16x32_bf16 v[72:75], v[166:169], v[218:221], v[72:75]
	v_mfma_f32_16x16x32_bf16 v[124:127], v[162:165], v[198:201], v[124:127]
	v_mfma_f32_16x16x32_bf16 v[120:123], v[170:173], v[198:201], v[120:123]
	v_mfma_f32_16x16x32_bf16 v[112:115], v[162:165], v[206:209], v[112:115]
	v_mfma_f32_16x16x32_bf16 v[104:107], v[170:173], v[206:209], v[104:107]
	v_mfma_f32_16x16x32_bf16 v[96:99], v[162:165], v[214:217], v[96:99]
	v_mfma_f32_16x16x32_bf16 v[88:91], v[170:173], v[214:217], v[88:91]
	v_mfma_f32_16x16x32_bf16 v[80:83], v[162:165], v[222:225], v[80:83]
	v_mfma_f32_16x16x32_bf16 v[72:75], v[170:173], v[222:225], v[72:75]
	v_mfma_f32_16x16x32_bf16 v[116:119], v[178:181], v[194:197], v[116:119]
	v_mfma_f32_16x16x32_bf16 v[108:111], v[186:189], v[194:197], v[108:111]
	v_mfma_f32_16x16x32_bf16 v[100:103], v[178:181], v[202:205], v[100:103]
	v_mfma_f32_16x16x32_bf16 v[92:95], v[186:189], v[202:205], v[92:95]
	v_mfma_f32_16x16x32_bf16 v[84:87], v[178:181], v[210:213], v[84:87]
	v_mfma_f32_16x16x32_bf16 v[76:79], v[186:189], v[210:213], v[76:79]
	v_mfma_f32_16x16x32_bf16 v[68:71], v[178:181], v[218:221], v[68:71]
	v_mfma_f32_16x16x32_bf16 v[64:67], v[186:189], v[218:221], v[64:67]
	v_mfma_f32_16x16x32_bf16 v[116:119], v[182:185], v[198:201], v[116:119]
	v_mfma_f32_16x16x32_bf16 v[108:111], v[190:193], v[198:201], v[108:111]
	v_mfma_f32_16x16x32_bf16 v[100:103], v[182:185], v[206:209], v[100:103]
	v_mfma_f32_16x16x32_bf16 v[92:95], v[190:193], v[206:209], v[92:95]
	v_mfma_f32_16x16x32_bf16 v[84:87], v[182:185], v[214:217], v[84:87]
	v_mfma_f32_16x16x32_bf16 v[76:79], v[190:193], v[214:217], v[76:79]
	v_mfma_f32_16x16x32_bf16 v[68:71], v[182:185], v[222:225], v[68:71]
	v_mfma_f32_16x16x32_bf16 v[64:67], v[190:193], v[222:225], v[64:67]
	s_setprio 0
	s_barrier
; #define PG8_STAGE(bufoff, gbase, voff) do { _Pragma("unroll") for (int _i = 0; _i < 2; ++_i) \
;         __builtin_amdgcn_global_load_lds((const unsigned*)((const char*)(gbase) + (voff)[_i]), (PG8_LAS unsigned*)(lds + (bufoff) + ldsw + _i * 8192), 16, 0, 0); } while (0)
; #define PG8_LDA(dst, b, h) do { _Pragma("unroll") for (int m = 0; m < 4; ++m) _Pragma("unroll") for (int k = 0; k < 2; ++k) dst[m][k] = *(const PG8_LAS bf16x8*)(lds + PG8_SA(b, h) + aoff + m * 2048 + k * 1024); } while (0)
; #define PG8_MMA(ai, bj, At, Bt) do { __builtin_amdgcn_s_setprio(1); _Pragma("unroll") for (int m = 0; m < 4; ++m) _Pragma("unroll") for (int n = 0; n < 2; ++n) _Pragma("unroll") for (int k = 0; k < 2; ++k) \
;         acc[ai][bj][m][n] = __builtin_amdgcn_mfma_f32_16x16x32_bf16(Bt[n][k], At[m][k], acc[ai][bj][m][n], 0, 0, 0); __builtin_amdgcn_s_setprio(0); } while (0)
; #define PG8_WAIT_V(n) asm volatile("s_waitcnt vmcnt(" #n ")" ::: "memory")
; #define PG8_WAIT_L(n) asm volatile("s_waitcnt lgkmcnt(" #n ")" ::: "memory")
; #define PG8_BAR __builtin_amdgcn_s_barrier()
; #define PG8_SCHED __builtin_amdgcn_sched_barrier(0)
; template <class Epi, class Sched, bool ALIGN_EPI = false, bool SP2 = false>
; __device__ __forceinline__ void gemm_phase(PG8_LAS unsigned char* lds, const Gemm g, const Sched& S, const Epi& E) {
;     ...
;             PG8_LDA(At, 1, 1); PG8_STAGE(PG8_SB(1, 0), b3, voffB); PG8_STAGE(PG8_SB(1, 1), b3 + hstep, voffB); PG8_STAGE(PG8_SA(1, 0), a3, voffA);
;             PG8_WAIT_V(8); PG8_WAIT_L(0); PG8_BAR; PG8_MMA(1, 0, At, B0); PG8_MMA(1, 1, At, B1); PG8_BAR; PG8_SCHED;
;     ...
;         if constexpr (ALIGN_EPI) { if (wr == 0) PG8_BAR; }
	s_add_i32 s8, s60, s65
	v_lshl_add_u64 v[146:147], v[146:147], 0, s[12:13]
	s_mov_b32 m0, s8
	ds_read_b128 v[194:197], v152 offset:49152
	ds_read_b128 v[198:201], v152 offset:50176
	ds_read_b128 v[202:205], v152 offset:51200
	ds_read_b128 v[206:209], v152 offset:52224
	ds_read_b128 v[210:213], v152 offset:53248
	ds_read_b128 v[214:217], v152 offset:54272
	ds_read_b128 v[218:221], v152 offset:55296
	ds_read_b128 v[222:225], v152 offset:56320
	global_load_lds_dwordx4 v[146:147], off
	s_add_i32 m0, s8, 0x2000
	s_add_u32 s8, s54, 0x40080
	v_lshl_add_u64 v[146:147], v[158:159], 0, s[12:13]
	s_addc_u32 s9, s55, 0
	s_add_i32 s54, s61, s65
	global_load_lds_dwordx4 v[146:147], off
	v_lshl_add_u64 v[146:147], s[8:9], 0, v[130:131]
	s_mov_b32 m0, s54
	s_nop 0
	global_load_lds_dwordx4 v[146:147], off
	v_lshl_add_u64 v[146:147], s[8:9], 0, v[134:135]
	s_add_i32 m0, s54, 0x2000
	s_nop 0
	global_load_lds_dwordx4 v[146:147], off
	v_lshl_add_u64 v[146:147], v[174:175], 0, s[12:13]
	s_mov_b32 m0, s70
	s_nop 0
	global_load_lds_dwordx4 v[146:147], off
	v_lshl_add_u64 v[146:147], v[226:227], 0, s[12:13]
	s_mov_b32 m0, s71
	s_nop 0
	global_load_lds_dwordx4 v[146:147], off
	s_waitcnt vmcnt(8)
	s_waitcnt lgkmcnt(0)
	s_barrier
	s_setprio 1
	s_waitcnt lgkmcnt(0)
	v_mfma_f32_16x16x32_bf16 v[60:63], v[154:157], v[194:197], v[60:63]
	v_mfma_f32_16x16x32_bf16 v[56:59], v[166:169], v[194:197], v[56:59]
	v_mfma_f32_16x16x32_bf16 v[48:51], v[154:157], v[202:205], v[48:51]
	v_mfma_f32_16x16x32_bf16 v[40:43], v[166:169], v[202:205], v[40:43]
	v_mfma_f32_16x16x32_bf16 v[32:35], v[154:157], v[210:213], v[32:35]
	v_mfma_f32_16x16x32_bf16 v[24:27], v[166:169], v[210:213], v[24:27]
	v_mfma_f32_16x16x32_bf16 v[16:19], v[154:157], v[218:221], v[16:19]
	v_mfma_f32_16x16x32_bf16 v[8:11], v[166:169], v[218:221], v[8:11]
	v_mfma_f32_16x16x32_bf16 v[60:63], v[162:165], v[198:201], v[60:63]
	v_mfma_f32_16x16x32_bf16 v[56:59], v[170:173], v[198:201], v[56:59]
	v_mfma_f32_16x16x32_bf16 v[48:51], v[162:165], v[206:209], v[48:51]
	v_mfma_f32_16x16x32_bf16 v[40:43], v[170:173], v[206:209], v[40:43]
	v_mfma_f32_16x16x32_bf16 v[32:35], v[162:165], v[214:217], v[32:35]
	v_mfma_f32_16x16x32_bf16 v[24:27], v[170:173], v[214:217], v[24:27]
	v_mfma_f32_16x16x32_bf16 v[16:19], v[162:165], v[222:225], v[16:19]
	v_mfma_f32_16x16x32_bf16 v[8:11], v[170:173], v[222:225], v[8:11]
	v_mfma_f32_16x16x32_bf16 v[52:55], v[178:181], v[194:197], v[52:55]
	v_mfma_f32_16x16x32_bf16 v[44:47], v[186:189], v[194:197], v[44:47]
	v_mfma_f32_16x16x32_bf16 v[36:39], v[178:181], v[202:205], v[36:39]
	v_mfma_f32_16x16x32_bf16 v[28:31], v[186:189], v[202:205], v[28:31]
	v_mfma_f32_16x16x32_bf16 v[20:23], v[178:181], v[210:213], v[20:23]
	v_mfma_f32_16x16x32_bf16 v[12:15], v[186:189], v[210:213], v[12:15]
	v_mfma_f32_16x16x32_bf16 v[4:7], v[178:181], v[218:221], v[4:7]
	v_mfma_f32_16x16x32_bf16 v[0:3], v[186:189], v[218:221], v[0:3]
	v_mfma_f32_16x16x32_bf16 v[52:55], v[182:185], v[198:201], v[52:55]
	v_mfma_f32_16x16x32_bf16 v[44:47], v[190:193], v[198:201], v[44:47]
	v_mfma_f32_16x16x32_bf16 v[36:39], v[182:185], v[206:209], v[36:39]
	v_mfma_f32_16x16x32_bf16 v[28:31], v[190:193], v[206:209], v[28:31]
	v_mfma_f32_16x16x32_bf16 v[20:23], v[182:185], v[214:217], v[20:23]
	v_mfma_f32_16x16x32_bf16 v[12:15], v[190:193], v[214:217], v[12:15]
	v_mfma_f32_16x16x32_bf16 v[4:7], v[182:185], v[222:225], v[4:7]
	v_mfma_f32_16x16x32_bf16 v[0:3], v[190:193], v[222:225], v[0:3]
	s_setprio 0
	s_add_i32 s87, s87, 2
	s_add_u32 s52, s52, 0x100
	s_addc_u32 s53, s53, 0
	s_add_u32 s83, s83, 0x100
	s_addc_u32 s86, s86, 0
	s_cmp_gt_u32 s87, 13
	s_barrier
	s_cbranch_scc0 .LBB0_1172
	s_and_b64 vcc, exec, s[14:15]
	s_cbranch_vccz .LBB0_1175
	s_barrier

; #define PG8_STAGE(bufoff, gbase, voff) do { _Pragma("unroll") for (int _i = 0; _i < 2; ++_i) \
;         __builtin_amdgcn_global_load_lds((const unsigned*)((const char*)(gbase) + (voff)[_i]), (PG8_LAS unsigned*)(lds + (bufoff) + ldsw + _i * 8192), 16, 0, 0); } while (0)
; #define PG8_LDA(dst, b, h) do { _Pragma("unroll") for (int m = 0; m < 4; ++m) _Pragma("unroll") for (int k = 0; k < 2; ++k) dst[m][k] = *(const PG8_LAS bf16x8*)(lds + PG8_SA(b, h) + aoff + m * 2048 + k * 1024); } while (0)
; #define PG8_LDB(dst, b, h) do { _Pragma("unroll") for (int n = 0; n < 2; ++n) _Pragma("unroll") for (int k = 0; k < 2; ++k) dst[n][k] = *(const PG8_LAS bf16x8*)(lds + PG8_SB(b, h) + boff + n * 2048 + k * 1024); } while (0)
; #define PG8_MMA(ai, bj, At, Bt) do { __builtin_amdgcn_s_setprio(1); _Pragma("unroll") for (int m = 0; m < 4; ++m) _Pragma("unroll") for (int n = 0; n < 2; ++n) _Pragma("unroll") for (int k = 0; k < 2; ++k) \
;         acc[ai][bj][m][n] = __builtin_amdgcn_mfma_f32_16x16x32_bf16(Bt[n][k], At[m][k], acc[ai][bj][m][n], 0, 0, 0); __builtin_amdgcn_s_setprio(0); } while (0)
; #define PG8_WAIT_V(n) asm volatile("s_waitcnt vmcnt(" #n ")" ::: "memory")
; template <class Epi, class Sched, bool ALIGN_EPI = false, bool SP2 = false>
; __device__ __forceinline__ void gemm_phase(PG8_LAS unsigned char* lds, const Gemm g, const Sched& S, const Epi& E) {
;     ...
;         const char* nA = has_next ? (const char*)g.A + (size_t)nxt.pm * tstep : cA; const char* nB = has_next ? (const char*)g.Bt + (size_t)nxt.pn * tstep : cB;
;         for (int t = 0; t < nt; t += 2) {
;             const bool last = (t == nt - 2);
;             const char* a1 = cA + (size_t)(t + 1) * kstep;
;             const char* a2 = last ? nA : cA + (size_t)(t + 2) * kstep; const char* b2 = last ? nB : cB + (size_t)(t + 2) * kstep;
;             const char* a3 = a2 + kstep; const char* b3 = b2 + kstep;
;             if (last && has_next) S.a_ready(nxt);
;             if constexpr (SP2) {
;             PG8_LDB(B0, 0, 0); PG8_LDB(B1, 0, 1); PG8_SCHED; PG8_LDA(At, 0, 0); PG8_STAGE(PG8_SA(1, 1), a1 + hstep, voffA);
;             PG8_WAIT_V(8); PG8_WAIT_L(0); PG8_BAR; PG8_MMA(0, 0, At, B0); PG8_MMA(0, 1, At, B1); PG8_BAR; PG8_SCHED;
;             PG8_LDA(At, 0, 1); PG8_STAGE(PG8_SB(0, 0), b2, voffB); PG8_STAGE(PG8_SB(0, 1), b2 + hstep, voffB); PG8_STAGE(PG8_SA(0, 0), a2, voffA);
.LBB0_1337:
	ds_read_b128 v[152:155], v149
	ds_read_b128 v[156:159], v149 offset:1024
	ds_read_b128 v[162:165], v149 offset:2048
	ds_read_b128 v[166:169], v149 offset:3072
	ds_read_b128 v[170:173], v150
	ds_read_b128 v[178:181], v150 offset:1024
	ds_read_b128 v[182:185], v150 offset:2048
	ds_read_b128 v[186:189], v150 offset:3072
	s_add_u32 s8, s38, 0xfffc0080
	s_addc_u32 s9, s39, -1
	s_cmp_eq_u32 s71, 12
	s_cselect_b32 s45, s19, s9
	s_cselect_b32 s44, s67, s8
	s_cselect_b32 s43, s15, s70
	s_cselect_b32 s42, s68, s69
	v_lshl_add_u64 v[144:145], s[38:39], 0, v[136:137]
	s_add_i32 m0, s25, 0xc000
	ds_read_b128 v[190:193], v151
	ds_read_b128 v[194:197], v151 offset:1024
	ds_read_b128 v[198:201], v151 offset:2048
	ds_read_b128 v[202:205], v151 offset:3072
	ds_read_b128 v[206:209], v151 offset:4096
	ds_read_b128 v[210:213], v151 offset:5120
	ds_read_b128 v[214:217], v151 offset:6144
	ds_read_b128 v[218:221], v151 offset:7168
	global_load_lds_dwordx4 v[144:145], off
	v_lshl_add_u64 v[144:145], s[38:39], 0, v[138:139]
	s_add_i32 m0, s25, 0xe000
	s_nop 0
	global_load_lds_dwordx4 v[144:145], off
	s_waitcnt vmcnt(8)
	s_waitcnt lgkmcnt(0)
	s_barrier
	s_setprio 1
	s_waitcnt lgkmcnt(0)
	v_mfma_f32_16x16x32_bf16 v[124:127], v[152:155], v[190:193], v[124:127]
	v_mfma_f32_16x16x32_bf16 v[120:123], v[162:165], v[190:193], v[120:123]
	v_mfma_f32_16x16x32_bf16 v[108:111], v[152:155], v[198:201], v[108:111]
	v_mfma_f32_16x16x32_bf16 v[104:107], v[162:165], v[198:201], v[104:107]
	v_mfma_f32_16x16x32_bf16 v[92:95], v[152:155], v[206:209], v[92:95]
	v_mfma_f32_16x16x32_bf16 v[88:91], v[162:165], v[206:209], v[88:91]
	v_mfma_f32_16x16x32_bf16 v[76:79], v[152:155], v[214:217], v[76:79]
	v_mfma_f32_16x16x32_bf16 v[72:75], v[162:165], v[214:217], v[72:75]
	v_mfma_f32_16x16x32_bf16 v[124:127], v[156:159], v[194:197], v[124:127]
	v_mfma_f32_16x16x32_bf16 v[120:123], v[166:169], v[194:197], v[120:123]
	v_mfma_f32_16x16x32_bf16 v[108:111], v[156:159], v[202:205], v[108:111]
	v_mfma_f32_16x16x32_bf16 v[104:107], v[166:169], v[202:205], v[104:107]
	v_mfma_f32_16x16x32_bf16 v[92:95], v[156:159], v[210:213], v[92:95]
	v_mfma_f32_16x16x32_bf16 v[88:91], v[166:169], v[210:213], v[88:91]
	v_mfma_f32_16x16x32_bf16 v[76:79], v[156:159], v[218:221], v[76:79]
	v_mfma_f32_16x16x32_bf16 v[72:75], v[166:169], v[218:221], v[72:75]
	v_mfma_f32_16x16x32_bf16 v[116:119], v[170:173], v[190:193], v[116:119]
	v_mfma_f32_16x16x32_bf16 v[112:115], v[182:185], v[190:193], v[112:115]
	v_mfma_f32_16x16x32_bf16 v[100:103], v[170:173], v[198:201], v[100:103]
	v_mfma_f32_16x16x32_bf16 v[96:99], v[182:185], v[198:201], v[96:99]
	v_mfma_f32_16x16x32_bf16 v[84:87], v[170:173], v[206:209], v[84:87]
	v_mfma_f32_16x16x32_bf16 v[80:83], v[182:185], v[206:209], v[80:83]
	v_mfma_f32_16x16x32_bf16 v[68:71], v[170:173], v[214:217], v[68:71]
	v_mfma_f32_16x16x32_bf16 v[64:67], v[182:185], v[214:217], v[64:67]
	v_mfma_f32_16x16x32_bf16 v[116:119], v[178:181], v[194:197], v[116:119]
	v_mfma_f32_16x16x32_bf16 v[112:115], v[186:189], v[194:197], v[112:115]
	v_mfma_f32_16x16x32_bf16 v[100:103], v[178:181], v[202:205], v[100:103]
	v_mfma_f32_16x16x32_bf16 v[96:99], v[186:189], v[202:205], v[96:99]
	v_mfma_f32_16x16x32_bf16 v[84:87], v[178:181], v[210:213], v[84:87]
	v_mfma_f32_16x16x32_bf16 v[80:83], v[186:189], v[210:213], v[80:83]
	v_mfma_f32_16x16x32_bf16 v[68:71], v[178:181], v[218:221], v[68:71]
	v_mfma_f32_16x16x32_bf16 v[64:67], v[186:189], v[218:221], v[64:67]
	s_setprio 0
	s_barrier
	s_add_i32 s8, s63, s47
	v_lshl_add_u64 v[144:145], s[42:43], 0, v[132:133]
	s_mov_b32 m0, s8
	ds_read_b128 v[190:193], v151 offset:16384
	ds_read_b128 v[194:197], v151 offset:17408
	ds_read_b128 v[198:201], v151 offset:18432
	ds_read_b128 v[202:205], v151 offset:19456
	ds_read_b128 v[206:209], v151 offset:20480
	ds_read_b128 v[210:213], v151 offset:21504
	ds_read_b128 v[214:217], v151 offset:22528
	ds_read_b128 v[218:221], v151 offset:23552
	global_load_lds_dwordx4 v[144:145], off
	s_add_i32 m0, s8, 0x2000
	s_add_u32 s8, s42, 0x40000
	v_lshl_add_u64 v[174:175], s[42:43], 0, v[128:129]
	s_addc_u32 s9, s43, 0
	s_add_i32 s60, s64, s47
	global_load_lds_dwordx4 v[174:175], off
	v_lshl_add_u64 v[222:223], s[8:9], 0, v[132:133]
	s_mov_b32 m0, s60
	v_lshl_add_u64 v[224:225], s[44:45], 0, v[130:131]
	global_load_lds_dwordx4 v[222:223], off
	v_lshl_add_u64 v[222:223], s[8:9], 0, v[128:129]
	s_add_i32 m0, s60, 0x2000
	s_nop 0
	global_load_lds_dwordx4 v[222:223], off
	v_lshl_add_u64 v[222:223], s[44:45], 0, v[134:135]
	s_mov_b32 m0, s25
	s_nop 0
	global_load_lds_dwordx4 v[222:223], off
	s_mov_b32 m0, s50
	s_nop 0
	global_load_lds_dwordx4 v[224:225], off
	s_waitcnt vmcnt(8)
	s_waitcnt lgkmcnt(0)
	s_barrier
; #define PG8_STAGE(bufoff, gbase, voff) do { _Pragma("unroll") for (int _i = 0; _i < 2; ++_i) \
;         __builtin_amdgcn_global_load_lds((const unsigned*)((const char*)(gbase) + (voff)[_i]), (PG8_LAS unsigned*)(lds + (bufoff) + ldsw + _i * 8192), 16, 0, 0); } while (0)
; #define PG8_LDA(dst, b, h) do { _Pragma("unroll") for (int m = 0; m < 4; ++m) _Pragma("unroll") for (int k = 0; k < 2; ++k) dst[m][k] = *(const PG8_LAS bf16x8*)(lds + PG8_SA(b, h) + aoff + m * 2048 + k * 1024); } while (0)
; #define PG8_LDB(dst, b, h) do { _Pragma("unroll") for (int n = 0; n < 2; ++n) _Pragma("unroll") for (int k = 0; k < 2; ++k) dst[n][k] = *(const PG8_LAS bf16x8*)(lds + PG8_SB(b, h) + boff + n * 2048 + k * 1024); } while (0)
; #define PG8_MMA(ai, bj, At, Bt) do { __builtin_amdgcn_s_setprio(1); _Pragma("unroll") for (int m = 0; m < 4; ++m) _Pragma("unroll") for (int n = 0; n < 2; ++n) _Pragma("unroll") for (int k = 0; k < 2; ++k) \
;         acc[ai][bj][m][n] = __builtin_amdgcn_mfma_f32_16x16x32_bf16(Bt[n][k], At[m][k], acc[ai][bj][m][n], 0, 0, 0); __builtin_amdgcn_s_setprio(0); } while (0)
; #define PG8_WAIT_V(n) asm volatile("s_waitcnt vmcnt(" #n ")" ::: "memory")
; #define PG8_WAIT_L(n) asm volatile("s_waitcnt lgkmcnt(" #n ")" ::: "memory")
; #define PG8_BAR __builtin_amdgcn_s_barrier()
; #define PG8_SCHED __builtin_amdgcn_sched_barrier(0)
; template <class Epi, class Sched, bool ALIGN_EPI = false, bool SP2 = false>
; __device__ __forceinline__ void gemm_phase(PG8_LAS unsigned char* lds, const Gemm g, const Sched& S, const Epi& E) {
;     ...
;             PG8_WAIT_V(8); PG8_WAIT_L(0); PG8_BAR; PG8_MMA(1, 0, At, B0); PG8_MMA(1, 1, At, B1); PG8_BAR; PG8_SCHED;
;             PG8_LDB(B0, 1, 0); PG8_LDB(B1, 1, 1); PG8_SCHED; PG8_LDA(At, 1, 0); PG8_STAGE(PG8_SA(0, 1), a2 + hstep, voffA);
;             PG8_WAIT_V(8); PG8_WAIT_L(0); PG8_BAR; PG8_MMA(0, 0, At, B0); PG8_MMA(0, 1, At, B1); PG8_BAR; PG8_SCHED;
	s_setprio 1
	s_waitcnt lgkmcnt(0)
	v_mfma_f32_16x16x32_bf16 v[60:63], v[152:155], v[190:193], v[60:63]
	v_mfma_f32_16x16x32_bf16 v[56:59], v[162:165], v[190:193], v[56:59]
	v_mfma_f32_16x16x32_bf16 v[44:47], v[152:155], v[198:201], v[44:47]
	v_mfma_f32_16x16x32_bf16 v[40:43], v[162:165], v[198:201], v[40:43]
	v_mfma_f32_16x16x32_bf16 v[28:31], v[152:155], v[206:209], v[28:31]
	v_mfma_f32_16x16x32_bf16 v[24:27], v[162:165], v[206:209], v[24:27]
	v_mfma_f32_16x16x32_bf16 v[12:15], v[152:155], v[214:217], v[12:15]
	v_mfma_f32_16x16x32_bf16 v[8:11], v[162:165], v[214:217], v[8:11]
	v_mfma_f32_16x16x32_bf16 v[60:63], v[156:159], v[194:197], v[60:63]
	v_mfma_f32_16x16x32_bf16 v[56:59], v[166:169], v[194:197], v[56:59]
	v_mfma_f32_16x16x32_bf16 v[44:47], v[156:159], v[202:205], v[44:47]
	v_mfma_f32_16x16x32_bf16 v[40:43], v[166:169], v[202:205], v[40:43]
	v_mfma_f32_16x16x32_bf16 v[28:31], v[156:159], v[210:213], v[28:31]
	v_mfma_f32_16x16x32_bf16 v[24:27], v[166:169], v[210:213], v[24:27]
	v_mfma_f32_16x16x32_bf16 v[12:15], v[156:159], v[218:221], v[12:15]
	v_mfma_f32_16x16x32_bf16 v[8:11], v[166:169], v[218:221], v[8:11]
	v_mfma_f32_16x16x32_bf16 v[52:55], v[170:173], v[190:193], v[52:55]
	v_mfma_f32_16x16x32_bf16 v[48:51], v[182:185], v[190:193], v[48:51]
	v_mfma_f32_16x16x32_bf16 v[36:39], v[170:173], v[198:201], v[36:39]
	v_mfma_f32_16x16x32_bf16 v[32:35], v[182:185], v[198:201], v[32:35]
	v_mfma_f32_16x16x32_bf16 v[20:23], v[170:173], v[206:209], v[20:23]
	v_mfma_f32_16x16x32_bf16 v[16:19], v[182:185], v[206:209], v[16:19]
	v_mfma_f32_16x16x32_bf16 v[4:7], v[170:173], v[214:217], v[4:7]
	v_mfma_f32_16x16x32_bf16 v[0:3], v[182:185], v[214:217], v[0:3]
	v_mfma_f32_16x16x32_bf16 v[52:55], v[178:181], v[194:197], v[52:55]
	v_mfma_f32_16x16x32_bf16 v[48:51], v[186:189], v[194:197], v[48:51]
	v_mfma_f32_16x16x32_bf16 v[36:39], v[178:181], v[202:205], v[36:39]
	v_mfma_f32_16x16x32_bf16 v[32:35], v[186:189], v[202:205], v[32:35]
	v_mfma_f32_16x16x32_bf16 v[20:23], v[178:181], v[210:213], v[20:23]
	v_mfma_f32_16x16x32_bf16 v[16:19], v[186:189], v[210:213], v[16:19]
	v_mfma_f32_16x16x32_bf16 v[4:7], v[178:181], v[218:221], v[4:7]
	v_mfma_f32_16x16x32_bf16 v[0:3], v[186:189], v[218:221], v[0:3]
	s_setprio 0
	s_barrier
	s_add_i32 s60, 0, 0x18000
	v_add_u32_e32 v161, s60, v147
	s_add_i32 s61, 0, 0x1c000
	ds_read_b128 v[152:155], v161
	ds_read_b128 v[156:159], v161 offset:1024
	ds_read_b128 v[162:165], v161 offset:2048
	ds_read_b128 v[166:169], v161 offset:3072
	v_add_u32_e32 v161, s61, v147
	ds_read_b128 v[170:173], v161
	ds_read_b128 v[178:181], v161 offset:1024
	ds_read_b128 v[182:185], v161 offset:2048
	ds_read_b128 v[186:189], v161 offset:3072
	s_add_u32 s8, s44, 0x40000
	s_addc_u32 s9, s45, 0
	s_mov_b32 m0, s51
	v_lshl_add_u64 v[226:227], s[8:9], 0, v[134:135]
	ds_read_b128 v[190:193], v151 offset:32768
	ds_read_b128 v[194:197], v151 offset:33792
	ds_read_b128 v[198:201], v151 offset:34816
	ds_read_b128 v[202:205], v151 offset:35840
	ds_read_b128 v[206:209], v151 offset:36864
	ds_read_b128 v[210:213], v151 offset:37888
	ds_read_b128 v[214:217], v151 offset:38912
	ds_read_b128 v[218:221], v151 offset:39936
	global_load_lds_dwordx4 v[226:227], off
	v_lshl_add_u64 v[226:227], s[8:9], 0, v[130:131]
	s_mov_b32 m0, s52
	s_nop 0
	global_load_lds_dwordx4 v[226:227], off
	s_waitcnt vmcnt(8)
	s_waitcnt lgkmcnt(0)
	s_barrier
	s_setprio 1
	s_waitcnt lgkmcnt(0)
	v_mfma_f32_16x16x32_bf16 v[124:127], v[152:155], v[190:193], v[124:127]
	v_mfma_f32_16x16x32_bf16 v[120:123], v[162:165], v[190:193], v[120:123]
	v_mfma_f32_16x16x32_bf16 v[108:111], v[152:155], v[198:201], v[108:111]
	v_mfma_f32_16x16x32_bf16 v[104:107], v[162:165], v[198:201], v[104:107]
	v_mfma_f32_16x16x32_bf16 v[92:95], v[152:155], v[206:209], v[92:95]
	v_mfma_f32_16x16x32_bf16 v[88:91], v[162:165], v[206:209], v[88:91]
	v_mfma_f32_16x16x32_bf16 v[76:79], v[152:155], v[214:217], v[76:79]
	v_mfma_f32_16x16x32_bf16 v[72:75], v[162:165], v[214:217], v[72:75]
	v_mfma_f32_16x16x32_bf16 v[124:127], v[156:159], v[194:197], v[124:127]
	v_mfma_f32_16x16x32_bf16 v[120:123], v[166:169], v[194:197], v[120:123]
	v_mfma_f32_16x16x32_bf16 v[108:111], v[156:159], v[202:205], v[108:111]
	v_mfma_f32_16x16x32_bf16 v[104:107], v[166:169], v[202:205], v[104:107]
	v_mfma_f32_16x16x32_bf16 v[92:95], v[156:159], v[210:213], v[92:95]
	v_mfma_f32_16x16x32_bf16 v[88:91], v[166:169], v[210:213], v[88:91]
	v_mfma_f32_16x16x32_bf16 v[76:79], v[156:159], v[218:221], v[76:79]
	v_mfma_f32_16x16x32_bf16 v[72:75], v[166:169], v[218:221], v[72:75]
	v_mfma_f32_16x16x32_bf16 v[116:119], v[170:173], v[190:193], v[116:119]
	v_mfma_f32_16x16x32_bf16 v[112:115], v[182:185], v[190:193], v[112:115]
	v_mfma_f32_16x16x32_bf16 v[100:103], v[170:173], v[198:201], v[100:103]
	v_mfma_f32_16x16x32_bf16 v[96:99], v[182:185], v[198:201], v[96:99]
	v_mfma_f32_16x16x32_bf16 v[84:87], v[170:173], v[206:209], v[84:87]
	v_mfma_f32_16x16x32_bf16 v[80:83], v[182:185], v[206:209], v[80:83]
	v_mfma_f32_16x16x32_bf16 v[68:71], v[170:173], v[214:217], v[68:71]
	v_mfma_f32_16x16x32_bf16 v[64:67], v[182:185], v[214:217], v[64:67]
	v_mfma_f32_16x16x32_bf16 v[116:119], v[178:181], v[194:197], v[116:119]
	v_mfma_f32_16x16x32_bf16 v[112:115], v[186:189], v[194:197], v[112:115]
	v_mfma_f32_16x16x32_bf16 v[100:103], v[178:181], v[202:205], v[100:103]
	v_mfma_f32_16x16x32_bf16 v[96:99], v[186:189], v[202:205], v[96:99]
	v_mfma_f32_16x16x32_bf16 v[84:87], v[178:181], v[210:213], v[84:87]
	v_mfma_f32_16x16x32_bf16 v[80:83], v[186:189], v[210:213], v[80:83]
	v_mfma_f32_16x16x32_bf16 v[68:71], v[178:181], v[218:221], v[68:71]
	v_mfma_f32_16x16x32_bf16 v[64:67], v[186:189], v[218:221], v[64:67]
	s_setprio 0
	s_barrier
; #define PG8_STAGE(bufoff, gbase, voff) do { _Pragma("unroll") for (int _i = 0; _i < 2; ++_i) \
;         __builtin_amdgcn_global_load_lds((const unsigned*)((const char*)(gbase) + (voff)[_i]), (PG8_LAS unsigned*)(lds + (bufoff) + ldsw + _i * 8192), 16, 0, 0); } while (0)
; #define PG8_LDA(dst, b, h) do { _Pragma("unroll") for (int m = 0; m < 4; ++m) _Pragma("unroll") for (int k = 0; k < 2; ++k) dst[m][k] = *(const PG8_LAS bf16x8*)(lds + PG8_SA(b, h) + aoff + m * 2048 + k * 1024); } while (0)
; #define PG8_MMA(ai, bj, At, Bt) do { __builtin_amdgcn_s_setprio(1); _Pragma("unroll") for (int m = 0; m < 4; ++m) _Pragma("unroll") for (int n = 0; n < 2; ++n) _Pragma("unroll") for (int k = 0; k < 2; ++k) \
;         acc[ai][bj][m][n] = __builtin_amdgcn_mfma_f32_16x16x32_bf16(Bt[n][k], At[m][k], acc[ai][bj][m][n], 0, 0, 0); __builtin_amdgcn_s_setprio(0); } while (0)
; #define PG8_WAIT_V(n) asm volatile("s_waitcnt vmcnt(" #n ")" ::: "memory")
; #define PG8_WAIT_L(n) asm volatile("s_waitcnt lgkmcnt(" #n ")" ::: "memory")
; #define PG8_BAR __builtin_amdgcn_s_barrier()
; #define PG8_SCHED __builtin_amdgcn_sched_barrier(0)
; template <class Epi, class Sched, bool ALIGN_EPI = false, bool SP2 = false>
; __device__ __forceinline__ void gemm_phase(PG8_LAS unsigned char* lds, const Gemm g, const Sched& S, const Epi& E) {
;     ...
;             PG8_LDA(At, 1, 1); PG8_STAGE(PG8_SB(1, 0), b3, voffB); PG8_STAGE(PG8_SB(1, 1), b3 + hstep, voffB); PG8_STAGE(PG8_SA(1, 0), a3, voffA);
;             PG8_WAIT_V(8); PG8_WAIT_L(0); PG8_BAR; PG8_MMA(1, 0, At, B0); PG8_MMA(1, 1, At, B1); PG8_BAR; PG8_SCHED;
;     ...
;         if constexpr (ALIGN_EPI) { if (wr == 0) PG8_BAR; }
	s_add_i32 s8, s60, s47
	v_lshl_add_u64 v[144:145], v[144:145], 0, s[6:7]
	s_mov_b32 m0, s8
	ds_read_b128 v[190:193], v151 offset:49152
	ds_read_b128 v[194:197], v151 offset:50176
	ds_read_b128 v[198:201], v151 offset:51200
	ds_read_b128 v[202:205], v151 offset:52224
	ds_read_b128 v[206:209], v151 offset:53248
	ds_read_b128 v[210:213], v151 offset:54272
	ds_read_b128 v[214:217], v151 offset:55296
	ds_read_b128 v[218:221], v151 offset:56320
	global_load_lds_dwordx4 v[144:145], off
	s_add_i32 m0, s8, 0x2000
	s_add_u32 s8, s42, 0x40080
	v_lshl_add_u64 v[144:145], v[174:175], 0, s[6:7]
	s_addc_u32 s9, s43, 0
	s_add_i32 s42, s61, s47
	global_load_lds_dwordx4 v[144:145], off
	v_lshl_add_u64 v[144:145], s[8:9], 0, v[132:133]
	s_mov_b32 m0, s42
	s_nop 0
	global_load_lds_dwordx4 v[144:145], off
	v_lshl_add_u64 v[144:145], s[8:9], 0, v[128:129]
	s_add_i32 m0, s42, 0x2000
	s_nop 0
	global_load_lds_dwordx4 v[144:145], off
	v_lshl_add_u64 v[144:145], v[222:223], 0, s[6:7]
	s_mov_b32 m0, s54
	s_nop 0
	global_load_lds_dwordx4 v[144:145], off
	v_lshl_add_u64 v[144:145], v[224:225], 0, s[6:7]
	s_mov_b32 m0, s55
	s_nop 0
	global_load_lds_dwordx4 v[144:145], off
	s_waitcnt vmcnt(8)
	s_waitcnt lgkmcnt(0)
	s_barrier
	s_setprio 1
	s_waitcnt lgkmcnt(0)
	v_mfma_f32_16x16x32_bf16 v[60:63], v[152:155], v[190:193], v[60:63]
	v_mfma_f32_16x16x32_bf16 v[56:59], v[162:165], v[190:193], v[56:59]
	v_mfma_f32_16x16x32_bf16 v[44:47], v[152:155], v[198:201], v[44:47]
	v_mfma_f32_16x16x32_bf16 v[40:43], v[162:165], v[198:201], v[40:43]
	v_mfma_f32_16x16x32_bf16 v[28:31], v[152:155], v[206:209], v[28:31]
	v_mfma_f32_16x16x32_bf16 v[24:27], v[162:165], v[206:209], v[24:27]
	v_mfma_f32_16x16x32_bf16 v[12:15], v[152:155], v[214:217], v[12:15]
	v_mfma_f32_16x16x32_bf16 v[8:11], v[162:165], v[214:217], v[8:11]
	v_mfma_f32_16x16x32_bf16 v[60:63], v[156:159], v[194:197], v[60:63]
	v_mfma_f32_16x16x32_bf16 v[56:59], v[166:169], v[194:197], v[56:59]
	v_mfma_f32_16x16x32_bf16 v[44:47], v[156:159], v[202:205], v[44:47]
	v_mfma_f32_16x16x32_bf16 v[40:43], v[166:169], v[202:205], v[40:43]
	v_mfma_f32_16x16x32_bf16 v[28:31], v[156:159], v[210:213], v[28:31]
	v_mfma_f32_16x16x32_bf16 v[24:27], v[166:169], v[210:213], v[24:27]
	v_mfma_f32_16x16x32_bf16 v[12:15], v[156:159], v[218:221], v[12:15]
	v_mfma_f32_16x16x32_bf16 v[8:11], v[166:169], v[218:221], v[8:11]
	v_mfma_f32_16x16x32_bf16 v[52:55], v[170:173], v[190:193], v[52:55]
	v_mfma_f32_16x16x32_bf16 v[48:51], v[182:185], v[190:193], v[48:51]
	v_mfma_f32_16x16x32_bf16 v[36:39], v[170:173], v[198:201], v[36:39]
	v_mfma_f32_16x16x32_bf16 v[32:35], v[182:185], v[198:201], v[32:35]
	v_mfma_f32_16x16x32_bf16 v[20:23], v[170:173], v[206:209], v[20:23]
	v_mfma_f32_16x16x32_bf16 v[16:19], v[182:185], v[206:209], v[16:19]
	v_mfma_f32_16x16x32_bf16 v[4:7], v[170:173], v[214:217], v[4:7]
	v_mfma_f32_16x16x32_bf16 v[0:3], v[182:185], v[214:217], v[0:3]
	v_mfma_f32_16x16x32_bf16 v[52:55], v[178:181], v[194:197], v[52:55]
	v_mfma_f32_16x16x32_bf16 v[48:51], v[186:189], v[194:197], v[48:51]
	v_mfma_f32_16x16x32_bf16 v[36:39], v[178:181], v[202:205], v[36:39]
	v_mfma_f32_16x16x32_bf16 v[32:35], v[186:189], v[202:205], v[32:35]
	v_mfma_f32_16x16x32_bf16 v[20:23], v[178:181], v[210:213], v[20:23]
	v_mfma_f32_16x16x32_bf16 v[16:19], v[186:189], v[210:213], v[16:19]
	v_mfma_f32_16x16x32_bf16 v[4:7], v[178:181], v[218:221], v[4:7]
	v_mfma_f32_16x16x32_bf16 v[0:3], v[186:189], v[218:221], v[0:3]
	s_setprio 0
	s_add_i32 s71, s71, 2
	s_add_u32 s38, s38, 0x100
	s_addc_u32 s39, s39, 0
	s_add_u32 s69, s69, 0x100
	s_addc_u32 s70, s70, 0
	s_cmp_gt_u32 s71, 13
	s_barrier
	s_cbranch_scc0 .LBB0_1337
	s_and_b64 vcc, exec, s[12:13]
	s_cbranch_vccz .LBB0_1340
	s_barrier

; #define PG8_STAGE(bufoff, gbase, voff) do { _Pragma("unroll") for (int _i = 0; _i < 2; ++_i) \
;         __builtin_amdgcn_global_load_lds((const unsigned*)((const char*)(gbase) + (voff)[_i]), (PG8_LAS unsigned*)(lds + (bufoff) + ldsw + _i * 8192), 16, 0, 0); } while (0)
; #define PG8_LDA(dst, b, h) do { _Pragma("unroll") for (int m = 0; m < 4; ++m) _Pragma("unroll") for (int k = 0; k < 2; ++k) dst[m][k] = *(const PG8_LAS bf16x8*)(lds + PG8_SA(b, h) + aoff + m * 2048 + k * 1024); } while (0)
; #define PG8_LDB(dst, b, h) do { _Pragma("unroll") for (int n = 0; n < 2; ++n) _Pragma("unroll") for (int k = 0; k < 2; ++k) dst[n][k] = *(const PG8_LAS bf16x8*)(lds + PG8_SB(b, h) + boff + n * 2048 + k * 1024); } while (0)
; #define PG8_MMA(ai, bj, At, Bt) do { __builtin_amdgcn_s_setprio(1); _Pragma("unroll") for (int m = 0; m < 4; ++m) _Pragma("unroll") for (int n = 0; n < 2; ++n) _Pragma("unroll") for (int k = 0; k < 2; ++k) \
;         acc[ai][bj][m][n] = __builtin_amdgcn_mfma_f32_16x16x32_bf16(Bt[n][k], At[m][k], acc[ai][bj][m][n], 0, 0, 0); __builtin_amdgcn_s_setprio(0); } while (0)
; #define PG8_WAIT_V(n) asm volatile("s_waitcnt vmcnt(" #n ")" ::: "memory")
; template <class Epi, class Sched, bool ALIGN_EPI = false, bool SP2 = false>
; __device__ __forceinline__ void gemm_phase(PG8_LAS unsigned char* lds, const Gemm g, const Sched& S, const Epi& E) {
;     ...
;         const char* nA = has_next ? (const char*)g.A + (size_t)nxt.pm * tstep : cA; const char* nB = has_next ? (const char*)g.Bt + (size_t)nxt.pn * tstep : cB;
;         for (int t = 0; t < nt; t += 2) {
;             const bool last = (t == nt - 2);
;             const char* a1 = cA + (size_t)(t + 1) * kstep;
;             const char* a2 = last ? nA : cA + (size_t)(t + 2) * kstep; const char* b2 = last ? nB : cB + (size_t)(t + 2) * kstep;
;             const char* a3 = a2 + kstep; const char* b3 = b2 + kstep;
;             if (last && has_next) S.a_ready(nxt);
;             if constexpr (SP2) {
;             PG8_LDB(B0, 0, 0); PG8_LDB(B1, 0, 1); PG8_SCHED; PG8_LDA(At, 0, 0); PG8_STAGE(PG8_SA(1, 1), a1 + hstep, voffA);
;             PG8_WAIT_V(8); PG8_WAIT_L(0); PG8_BAR; PG8_MMA(0, 0, At, B0); PG8_MMA(0, 1, At, B1); PG8_BAR; PG8_SCHED;
;             PG8_LDA(At, 0, 1); PG8_STAGE(PG8_SB(0, 0), b2, voffB); PG8_STAGE(PG8_SB(0, 1), b2 + hstep, voffB); PG8_STAGE(PG8_SA(0, 0), a2, voffA);
.LBB0_1420:
	ds_read_b128 v[164:167], v159
	ds_read_b128 v[168:171], v159 offset:1024
	ds_read_b128 v[172:175], v159 offset:2048
	ds_read_b128 v[178:181], v159 offset:3072
	ds_read_b128 v[182:185], v161
	ds_read_b128 v[186:189], v161 offset:1024
	ds_read_b128 v[190:193], v161 offset:2048
	ds_read_b128 v[194:197], v161 offset:3072
	s_add_u32 s8, s44, 0xfff50080
	s_addc_u32 s9, s45, -1
	s_cmp_eq_u32 s79, 40
	s_cselect_b32 s49, s1, s9
	s_cselect_b32 s48, s0, s8
	s_cselect_b32 s47, s43, s78
	s_cselect_b32 s46, s42, s77
	v_lshl_add_u64 v[146:147], s[44:45], 0, v[136:137]
	s_add_i32 m0, s53, 0xc000
	ds_read_b128 v[198:201], v162
	ds_read_b128 v[202:205], v162 offset:1024
	ds_read_b128 v[206:209], v162 offset:2048
	ds_read_b128 v[210:213], v162 offset:3072
	ds_read_b128 v[214:217], v162 offset:4096
	ds_read_b128 v[218:221], v162 offset:5120
	ds_read_b128 v[222:225], v162 offset:6144
	ds_read_b128 v[226:229], v162 offset:7168
	global_load_lds_dwordx4 v[146:147], off
	v_lshl_add_u64 v[146:147], s[44:45], 0, v[138:139]
	s_add_i32 m0, s53, 0xe000
	s_nop 0
	global_load_lds_dwordx4 v[146:147], off
	s_waitcnt vmcnt(8)
	s_waitcnt lgkmcnt(0)
	s_barrier
	s_setprio 1
	s_waitcnt lgkmcnt(0)
	v_mfma_f32_16x16x32_bf16 v[124:127], v[164:167], v[198:201], v[124:127]
	v_mfma_f32_16x16x32_bf16 v[120:123], v[172:175], v[198:201], v[120:123]
	v_mfma_f32_16x16x32_bf16 v[112:115], v[164:167], v[206:209], v[112:115]
	v_mfma_f32_16x16x32_bf16 v[104:107], v[172:175], v[206:209], v[104:107]
	v_mfma_f32_16x16x32_bf16 v[96:99], v[164:167], v[214:217], v[96:99]
	v_mfma_f32_16x16x32_bf16 v[88:91], v[172:175], v[214:217], v[88:91]
	v_mfma_f32_16x16x32_bf16 v[80:83], v[164:167], v[222:225], v[80:83]
	v_mfma_f32_16x16x32_bf16 v[72:75], v[172:175], v[222:225], v[72:75]
	v_mfma_f32_16x16x32_bf16 v[124:127], v[168:171], v[202:205], v[124:127]
	v_mfma_f32_16x16x32_bf16 v[120:123], v[178:181], v[202:205], v[120:123]
	v_mfma_f32_16x16x32_bf16 v[112:115], v[168:171], v[210:213], v[112:115]
	v_mfma_f32_16x16x32_bf16 v[104:107], v[178:181], v[210:213], v[104:107]
	v_mfma_f32_16x16x32_bf16 v[96:99], v[168:171], v[218:221], v[96:99]
	v_mfma_f32_16x16x32_bf16 v[88:91], v[178:181], v[218:221], v[88:91]
	v_mfma_f32_16x16x32_bf16 v[80:83], v[168:171], v[226:229], v[80:83]
	v_mfma_f32_16x16x32_bf16 v[72:75], v[178:181], v[226:229], v[72:75]
	v_mfma_f32_16x16x32_bf16 v[116:119], v[182:185], v[198:201], v[116:119]
	v_mfma_f32_16x16x32_bf16 v[108:111], v[190:193], v[198:201], v[108:111]
	v_mfma_f32_16x16x32_bf16 v[100:103], v[182:185], v[206:209], v[100:103]
	v_mfma_f32_16x16x32_bf16 v[92:95], v[190:193], v[206:209], v[92:95]
	v_mfma_f32_16x16x32_bf16 v[84:87], v[182:185], v[214:217], v[84:87]
	v_mfma_f32_16x16x32_bf16 v[76:79], v[190:193], v[214:217], v[76:79]
	v_mfma_f32_16x16x32_bf16 v[68:71], v[182:185], v[222:225], v[68:71]
	v_mfma_f32_16x16x32_bf16 v[64:67], v[190:193], v[222:225], v[64:67]
	v_mfma_f32_16x16x32_bf16 v[116:119], v[186:189], v[202:205], v[116:119]
	v_mfma_f32_16x16x32_bf16 v[108:111], v[194:197], v[202:205], v[108:111]
	v_mfma_f32_16x16x32_bf16 v[100:103], v[186:189], v[210:213], v[100:103]
	v_mfma_f32_16x16x32_bf16 v[92:95], v[194:197], v[210:213], v[92:95]
	v_mfma_f32_16x16x32_bf16 v[84:87], v[186:189], v[218:221], v[84:87]
	v_mfma_f32_16x16x32_bf16 v[76:79], v[194:197], v[218:221], v[76:79]
	v_mfma_f32_16x16x32_bf16 v[68:71], v[186:189], v[226:229], v[68:71]
	v_mfma_f32_16x16x32_bf16 v[64:67], v[194:197], v[226:229], v[64:67]
	s_setprio 0
	s_barrier
	s_add_i32 s8, s67, s52
	v_lshl_add_u64 v[146:147], s[46:47], 0, v[130:131]
	s_mov_b32 m0, s8
	ds_read_b128 v[198:201], v162 offset:16384
	ds_read_b128 v[202:205], v162 offset:17408
	ds_read_b128 v[206:209], v162 offset:18432
	ds_read_b128 v[210:213], v162 offset:19456
	ds_read_b128 v[214:217], v162 offset:20480
	ds_read_b128 v[218:221], v162 offset:21504
	ds_read_b128 v[222:225], v162 offset:22528
	ds_read_b128 v[226:229], v162 offset:23552
	global_load_lds_dwordx4 v[146:147], off
	s_add_i32 m0, s8, 0x2000
	s_add_u32 s8, s46, 0xb0000
	v_lshl_add_u64 v[230:231], s[46:47], 0, v[134:135]
	s_addc_u32 s9, s47, 0
	s_add_i32 s60, s68, s52
	global_load_lds_dwordx4 v[230:231], off
	v_lshl_add_u64 v[232:233], s[8:9], 0, v[130:131]
	s_mov_b32 m0, s60
	v_lshl_add_u64 v[234:235], s[48:49], 0, v[132:133]
	global_load_lds_dwordx4 v[232:233], off
	v_lshl_add_u64 v[232:233], s[8:9], 0, v[134:135]
	s_add_i32 m0, s60, 0x2000
	s_nop 0
	global_load_lds_dwordx4 v[232:233], off
	v_lshl_add_u64 v[232:233], s[48:49], 0, v[128:129]
	s_mov_b32 m0, s53
	s_nop 0
	global_load_lds_dwordx4 v[232:233], off
	s_mov_b32 m0, s54
	s_nop 0
	global_load_lds_dwordx4 v[234:235], off
	s_waitcnt vmcnt(8)
	s_waitcnt lgkmcnt(0)
	s_barrier
; #define PG8_STAGE(bufoff, gbase, voff) do { _Pragma("unroll") for (int _i = 0; _i < 2; ++_i) \
;         __builtin_amdgcn_global_load_lds((const unsigned*)((const char*)(gbase) + (voff)[_i]), (PG8_LAS unsigned*)(lds + (bufoff) + ldsw + _i * 8192), 16, 0, 0); } while (0)
; #define PG8_LDA(dst, b, h) do { _Pragma("unroll") for (int m = 0; m < 4; ++m) _Pragma("unroll") for (int k = 0; k < 2; ++k) dst[m][k] = *(const PG8_LAS bf16x8*)(lds + PG8_SA(b, h) + aoff + m * 2048 + k * 1024); } while (0)
; #define PG8_LDB(dst, b, h) do { _Pragma("unroll") for (int n = 0; n < 2; ++n) _Pragma("unroll") for (int k = 0; k < 2; ++k) dst[n][k] = *(const PG8_LAS bf16x8*)(lds + PG8_SB(b, h) + boff + n * 2048 + k * 1024); } while (0)
; #define PG8_MMA(ai, bj, At, Bt) do { __builtin_amdgcn_s_setprio(1); _Pragma("unroll") for (int m = 0; m < 4; ++m) _Pragma("unroll") for (int n = 0; n < 2; ++n) _Pragma("unroll") for (int k = 0; k < 2; ++k) \
;         acc[ai][bj][m][n] = __builtin_amdgcn_mfma_f32_16x16x32_bf16(Bt[n][k], At[m][k], acc[ai][bj][m][n], 0, 0, 0); __builtin_amdgcn_s_setprio(0); } while (0)
; #define PG8_WAIT_V(n) asm volatile("s_waitcnt vmcnt(" #n ")" ::: "memory")
; #define PG8_WAIT_L(n) asm volatile("s_waitcnt lgkmcnt(" #n ")" ::: "memory")
; #define PG8_BAR __builtin_amdgcn_s_barrier()
; #define PG8_SCHED __builtin_amdgcn_sched_barrier(0)
; template <class Epi, class Sched, bool ALIGN_EPI = false, bool SP2 = false>
; __device__ __forceinline__ void gemm_phase(PG8_LAS unsigned char* lds, const Gemm g, const Sched& S, const Epi& E) {
;     ...
;             PG8_WAIT_V(8); PG8_WAIT_L(0); PG8_BAR; PG8_MMA(1, 0, At, B0); PG8_MMA(1, 1, At, B1); PG8_BAR; PG8_SCHED;
;             PG8_LDB(B0, 1, 0); PG8_LDB(B1, 1, 1); PG8_SCHED; PG8_LDA(At, 1, 0); PG8_STAGE(PG8_SA(0, 1), a2 + hstep, voffA);
;             PG8_WAIT_V(8); PG8_WAIT_L(0); PG8_BAR; PG8_MMA(0, 0, At, B0); PG8_MMA(0, 1, At, B1); PG8_BAR; PG8_SCHED;
	s_setprio 1
	s_waitcnt lgkmcnt(0)
	v_mfma_f32_16x16x32_bf16 v[60:63], v[164:167], v[198:201], v[60:63]
	v_mfma_f32_16x16x32_bf16 v[56:59], v[172:175], v[198:201], v[56:59]
	v_mfma_f32_16x16x32_bf16 v[48:51], v[164:167], v[206:209], v[48:51]
	v_mfma_f32_16x16x32_bf16 v[40:43], v[172:175], v[206:209], v[40:43]
	v_mfma_f32_16x16x32_bf16 v[32:35], v[164:167], v[214:217], v[32:35]
	v_mfma_f32_16x16x32_bf16 v[24:27], v[172:175], v[214:217], v[24:27]
	v_mfma_f32_16x16x32_bf16 v[16:19], v[164:167], v[222:225], v[16:19]
	v_mfma_f32_16x16x32_bf16 v[8:11], v[172:175], v[222:225], v[8:11]
	v_mfma_f32_16x16x32_bf16 v[60:63], v[168:171], v[202:205], v[60:63]
	v_mfma_f32_16x16x32_bf16 v[56:59], v[178:181], v[202:205], v[56:59]
	v_mfma_f32_16x16x32_bf16 v[48:51], v[168:171], v[210:213], v[48:51]
	v_mfma_f32_16x16x32_bf16 v[40:43], v[178:181], v[210:213], v[40:43]
	v_mfma_f32_16x16x32_bf16 v[32:35], v[168:171], v[218:221], v[32:35]
	v_mfma_f32_16x16x32_bf16 v[24:27], v[178:181], v[218:221], v[24:27]
	v_mfma_f32_16x16x32_bf16 v[16:19], v[168:171], v[226:229], v[16:19]
	v_mfma_f32_16x16x32_bf16 v[8:11], v[178:181], v[226:229], v[8:11]
	v_mfma_f32_16x16x32_bf16 v[52:55], v[182:185], v[198:201], v[52:55]
	v_mfma_f32_16x16x32_bf16 v[44:47], v[190:193], v[198:201], v[44:47]
	v_mfma_f32_16x16x32_bf16 v[36:39], v[182:185], v[206:209], v[36:39]
	v_mfma_f32_16x16x32_bf16 v[28:31], v[190:193], v[206:209], v[28:31]
	v_mfma_f32_16x16x32_bf16 v[20:23], v[182:185], v[214:217], v[20:23]
	v_mfma_f32_16x16x32_bf16 v[12:15], v[190:193], v[214:217], v[12:15]
	v_mfma_f32_16x16x32_bf16 v[4:7], v[182:185], v[222:225], v[4:7]
	v_mfma_f32_16x16x32_bf16 v[0:3], v[190:193], v[222:225], v[0:3]
	v_mfma_f32_16x16x32_bf16 v[52:55], v[186:189], v[202:205], v[52:55]
	v_mfma_f32_16x16x32_bf16 v[44:47], v[194:197], v[202:205], v[44:47]
	v_mfma_f32_16x16x32_bf16 v[36:39], v[186:189], v[210:213], v[36:39]
	v_mfma_f32_16x16x32_bf16 v[28:31], v[194:197], v[210:213], v[28:31]
	v_mfma_f32_16x16x32_bf16 v[20:23], v[186:189], v[218:221], v[20:23]
	v_mfma_f32_16x16x32_bf16 v[12:15], v[194:197], v[218:221], v[12:15]
	v_mfma_f32_16x16x32_bf16 v[4:7], v[186:189], v[226:229], v[4:7]
	v_mfma_f32_16x16x32_bf16 v[0:3], v[194:197], v[226:229], v[0:3]
	s_setprio 0
	s_barrier
	s_add_i32 s60, 0, 0x18000
	v_add_u32_e32 v144, s60, v157
	s_add_i32 s61, 0, 0x1c000
	ds_read_b128 v[164:167], v144
	ds_read_b128 v[168:171], v144 offset:1024
	ds_read_b128 v[172:175], v144 offset:2048
	ds_read_b128 v[178:181], v144 offset:3072
	v_add_u32_e32 v144, s61, v157
	ds_read_b128 v[182:185], v144
	ds_read_b128 v[186:189], v144 offset:1024
	ds_read_b128 v[190:193], v144 offset:2048
	ds_read_b128 v[194:197], v144 offset:3072
	s_add_u32 s8, s48, 0xb0000
	s_addc_u32 s9, s49, 0
	s_mov_b32 m0, s55
	v_lshl_add_u64 v[236:237], s[8:9], 0, v[128:129]
	ds_read_b128 v[198:201], v162 offset:32768
	ds_read_b128 v[202:205], v162 offset:33792
	ds_read_b128 v[206:209], v162 offset:34816
	ds_read_b128 v[210:213], v162 offset:35840
	ds_read_b128 v[214:217], v162 offset:36864
	ds_read_b128 v[218:221], v162 offset:37888
	ds_read_b128 v[222:225], v162 offset:38912
	ds_read_b128 v[226:229], v162 offset:39936
	global_load_lds_dwordx4 v[236:237], off
	v_lshl_add_u64 v[236:237], s[8:9], 0, v[132:133]
	s_mov_b32 m0, s56
	s_nop 0
	global_load_lds_dwordx4 v[236:237], off
	s_waitcnt vmcnt(8)
	s_waitcnt lgkmcnt(0)
	s_barrier
	s_setprio 1
	s_waitcnt lgkmcnt(0)
	v_mfma_f32_16x16x32_bf16 v[124:127], v[164:167], v[198:201], v[124:127]
	v_mfma_f32_16x16x32_bf16 v[120:123], v[172:175], v[198:201], v[120:123]
	v_mfma_f32_16x16x32_bf16 v[112:115], v[164:167], v[206:209], v[112:115]
	v_mfma_f32_16x16x32_bf16 v[104:107], v[172:175], v[206:209], v[104:107]
	v_mfma_f32_16x16x32_bf16 v[96:99], v[164:167], v[214:217], v[96:99]
	v_mfma_f32_16x16x32_bf16 v[88:91], v[172:175], v[214:217], v[88:91]
	v_mfma_f32_16x16x32_bf16 v[80:83], v[164:167], v[222:225], v[80:83]
	v_mfma_f32_16x16x32_bf16 v[72:75], v[172:175], v[222:225], v[72:75]
	v_mfma_f32_16x16x32_bf16 v[124:127], v[168:171], v[202:205], v[124:127]
	v_mfma_f32_16x16x32_bf16 v[120:123], v[178:181], v[202:205], v[120:123]
	v_mfma_f32_16x16x32_bf16 v[112:115], v[168:171], v[210:213], v[112:115]
	v_mfma_f32_16x16x32_bf16 v[104:107], v[178:181], v[210:213], v[104:107]
	v_mfma_f32_16x16x32_bf16 v[96:99], v[168:171], v[218:221], v[96:99]
	v_mfma_f32_16x16x32_bf16 v[88:91], v[178:181], v[218:221], v[88:91]
	v_mfma_f32_16x16x32_bf16 v[80:83], v[168:171], v[226:229], v[80:83]
	v_mfma_f32_16x16x32_bf16 v[72:75], v[178:181], v[226:229], v[72:75]
	v_mfma_f32_16x16x32_bf16 v[116:119], v[182:185], v[198:201], v[116:119]
	v_mfma_f32_16x16x32_bf16 v[108:111], v[190:193], v[198:201], v[108:111]
	v_mfma_f32_16x16x32_bf16 v[100:103], v[182:185], v[206:209], v[100:103]
	v_mfma_f32_16x16x32_bf16 v[92:95], v[190:193], v[206:209], v[92:95]
	v_mfma_f32_16x16x32_bf16 v[84:87], v[182:185], v[214:217], v[84:87]
	v_mfma_f32_16x16x32_bf16 v[76:79], v[190:193], v[214:217], v[76:79]
	v_mfma_f32_16x16x32_bf16 v[68:71], v[182:185], v[222:225], v[68:71]
	v_mfma_f32_16x16x32_bf16 v[64:67], v[190:193], v[222:225], v[64:67]
	v_mfma_f32_16x16x32_bf16 v[116:119], v[186:189], v[202:205], v[116:119]
	v_mfma_f32_16x16x32_bf16 v[108:111], v[194:197], v[202:205], v[108:111]
	v_mfma_f32_16x16x32_bf16 v[100:103], v[186:189], v[210:213], v[100:103]
	v_mfma_f32_16x16x32_bf16 v[92:95], v[194:197], v[210:213], v[92:95]
	v_mfma_f32_16x16x32_bf16 v[84:87], v[186:189], v[218:221], v[84:87]
	v_mfma_f32_16x16x32_bf16 v[76:79], v[194:197], v[218:221], v[76:79]
	v_mfma_f32_16x16x32_bf16 v[68:71], v[186:189], v[226:229], v[68:71]
	v_mfma_f32_16x16x32_bf16 v[64:67], v[194:197], v[226:229], v[64:67]
	s_setprio 0
	s_barrier
; #define PG8_STAGE(bufoff, gbase, voff) do { _Pragma("unroll") for (int _i = 0; _i < 2; ++_i) \
;         __builtin_amdgcn_global_load_lds((const unsigned*)((const char*)(gbase) + (voff)[_i]), (PG8_LAS unsigned*)(lds + (bufoff) + ldsw + _i * 8192), 16, 0, 0); } while (0)
; #define PG8_LDA(dst, b, h) do { _Pragma("unroll") for (int m = 0; m < 4; ++m) _Pragma("unroll") for (int k = 0; k < 2; ++k) dst[m][k] = *(const PG8_LAS bf16x8*)(lds + PG8_SA(b, h) + aoff + m * 2048 + k * 1024); } while (0)
; #define PG8_MMA(ai, bj, At, Bt) do { __builtin_amdgcn_s_setprio(1); _Pragma("unroll") for (int m = 0; m < 4; ++m) _Pragma("unroll") for (int n = 0; n < 2; ++n) _Pragma("unroll") for (int k = 0; k < 2; ++k) \
;         acc[ai][bj][m][n] = __builtin_amdgcn_mfma_f32_16x16x32_bf16(Bt[n][k], At[m][k], acc[ai][bj][m][n], 0, 0, 0); __builtin_amdgcn_s_setprio(0); } while (0)
; #define PG8_WAIT_V(n) asm volatile("s_waitcnt vmcnt(" #n ")" ::: "memory")
; #define PG8_WAIT_L(n) asm volatile("s_waitcnt lgkmcnt(" #n ")" ::: "memory")
; #define PG8_BAR __builtin_amdgcn_s_barrier()
; #define PG8_SCHED __builtin_amdgcn_sched_barrier(0)
; template <class Epi, class Sched, bool ALIGN_EPI = false, bool SP2 = false>
; __device__ __forceinline__ void gemm_phase(PG8_LAS unsigned char* lds, const Gemm g, const Sched& S, const Epi& E) {
;     ...
;             PG8_LDA(At, 1, 1); PG8_STAGE(PG8_SB(1, 0), b3, voffB); PG8_STAGE(PG8_SB(1, 1), b3 + hstep, voffB); PG8_STAGE(PG8_SA(1, 0), a3, voffA);
;             PG8_WAIT_V(8); PG8_WAIT_L(0); PG8_BAR; PG8_MMA(1, 0, At, B0); PG8_MMA(1, 1, At, B1); PG8_BAR; PG8_SCHED;
;     ...
;         if constexpr (ALIGN_EPI) { if (wr == 0) PG8_BAR; }
	s_add_i32 s8, s60, s52
	v_lshl_add_u64 v[146:147], v[146:147], 0, s[14:15]
	s_mov_b32 m0, s8
	ds_read_b128 v[198:201], v162 offset:49152
	ds_read_b128 v[202:205], v162 offset:50176
	ds_read_b128 v[206:209], v162 offset:51200
	ds_read_b128 v[210:213], v162 offset:52224
	ds_read_b128 v[214:217], v162 offset:53248
	ds_read_b128 v[218:221], v162 offset:54272
	ds_read_b128 v[222:225], v162 offset:55296
	ds_read_b128 v[226:229], v162 offset:56320
	global_load_lds_dwordx4 v[146:147], off
	s_add_i32 m0, s8, 0x2000
	s_add_u32 s8, s46, 0xb0080
	v_lshl_add_u64 v[146:147], v[230:231], 0, s[14:15]
	s_addc_u32 s9, s47, 0
	s_add_i32 s46, s61, s52
	global_load_lds_dwordx4 v[146:147], off
	v_lshl_add_u64 v[146:147], s[8:9], 0, v[130:131]
	s_mov_b32 m0, s46
	s_nop 0
	global_load_lds_dwordx4 v[146:147], off
	v_lshl_add_u64 v[146:147], s[8:9], 0, v[134:135]
	s_add_i32 m0, s46, 0x2000
	s_nop 0
	global_load_lds_dwordx4 v[146:147], off
	v_lshl_add_u64 v[146:147], v[232:233], 0, s[14:15]
	s_mov_b32 m0, s63
	s_nop 0
	global_load_lds_dwordx4 v[146:147], off
	v_lshl_add_u64 v[146:147], v[234:235], 0, s[14:15]
	s_mov_b32 m0, s64
	s_nop 0
	global_load_lds_dwordx4 v[146:147], off
	s_waitcnt vmcnt(8)
	s_waitcnt lgkmcnt(0)
	s_barrier
	s_setprio 1
	s_waitcnt lgkmcnt(0)
	v_mfma_f32_16x16x32_bf16 v[60:63], v[164:167], v[198:201], v[60:63]
	v_mfma_f32_16x16x32_bf16 v[56:59], v[172:175], v[198:201], v[56:59]
	v_mfma_f32_16x16x32_bf16 v[48:51], v[164:167], v[206:209], v[48:51]
	v_mfma_f32_16x16x32_bf16 v[40:43], v[172:175], v[206:209], v[40:43]
	v_mfma_f32_16x16x32_bf16 v[32:35], v[164:167], v[214:217], v[32:35]
	v_mfma_f32_16x16x32_bf16 v[24:27], v[172:175], v[214:217], v[24:27]
	v_mfma_f32_16x16x32_bf16 v[16:19], v[164:167], v[222:225], v[16:19]
	v_mfma_f32_16x16x32_bf16 v[8:11], v[172:175], v[222:225], v[8:11]
	v_mfma_f32_16x16x32_bf16 v[60:63], v[168:171], v[202:205], v[60:63]
	v_mfma_f32_16x16x32_bf16 v[56:59], v[178:181], v[202:205], v[56:59]
	v_mfma_f32_16x16x32_bf16 v[48:51], v[168:171], v[210:213], v[48:51]
	v_mfma_f32_16x16x32_bf16 v[40:43], v[178:181], v[210:213], v[40:43]
	v_mfma_f32_16x16x32_bf16 v[32:35], v[168:171], v[218:221], v[32:35]
	v_mfma_f32_16x16x32_bf16 v[24:27], v[178:181], v[218:221], v[24:27]
	v_mfma_f32_16x16x32_bf16 v[16:19], v[168:171], v[226:229], v[16:19]
	v_mfma_f32_16x16x32_bf16 v[8:11], v[178:181], v[226:229], v[8:11]
	v_mfma_f32_16x16x32_bf16 v[52:55], v[182:185], v[198:201], v[52:55]
	v_mfma_f32_16x16x32_bf16 v[44:47], v[190:193], v[198:201], v[44:47]
	v_mfma_f32_16x16x32_bf16 v[36:39], v[182:185], v[206:209], v[36:39]
	v_mfma_f32_16x16x32_bf16 v[28:31], v[190:193], v[206:209], v[28:31]
	v_mfma_f32_16x16x32_bf16 v[20:23], v[182:185], v[214:217], v[20:23]
	v_mfma_f32_16x16x32_bf16 v[12:15], v[190:193], v[214:217], v[12:15]
	v_mfma_f32_16x16x32_bf16 v[4:7], v[182:185], v[222:225], v[4:7]
	v_mfma_f32_16x16x32_bf16 v[0:3], v[190:193], v[222:225], v[0:3]
	v_mfma_f32_16x16x32_bf16 v[52:55], v[186:189], v[202:205], v[52:55]
	v_mfma_f32_16x16x32_bf16 v[44:47], v[194:197], v[202:205], v[44:47]
	v_mfma_f32_16x16x32_bf16 v[36:39], v[186:189], v[210:213], v[36:39]
	v_mfma_f32_16x16x32_bf16 v[28:31], v[194:197], v[210:213], v[28:31]
	v_mfma_f32_16x16x32_bf16 v[20:23], v[186:189], v[218:221], v[20:23]
	v_mfma_f32_16x16x32_bf16 v[12:15], v[194:197], v[218:221], v[12:15]
	v_mfma_f32_16x16x32_bf16 v[4:7], v[186:189], v[226:229], v[4:7]
	v_mfma_f32_16x16x32_bf16 v[0:3], v[194:197], v[226:229], v[0:3]
	s_setprio 0
	s_add_i32 s79, s79, 2
	s_add_u32 s44, s44, 0x100
	s_addc_u32 s45, s45, 0
	s_add_u32 s77, s77, 0x100
	s_addc_u32 s78, s78, 0
	s_cmp_gt_u32 s79, 41
	s_barrier
	s_cbranch_scc0 .LBB0_1420
	s_and_b64 vcc, exec, s[18:19]
	s_cbranch_vccz .LBB0_1423
	s_barrier

; #define PG8_STAGE(bufoff, gbase, voff) do { _Pragma("unroll") for (int _i = 0; _i < 2; ++_i) \
;         __builtin_amdgcn_global_load_lds((const unsigned*)((const char*)(gbase) + (voff)[_i]), (PG8_LAS unsigned*)(lds + (bufoff) + ldsw + _i * 8192), 16, 0, 0); } while (0)
; #define PG8_LDA(dst, b, h) do { _Pragma("unroll") for (int m = 0; m < 4; ++m) _Pragma("unroll") for (int k = 0; k < 2; ++k) dst[m][k] = *(const PG8_LAS bf16x8*)(lds + PG8_SA(b, h) + aoff + m * 2048 + k * 1024); } while (0)
; #define PG8_LDB(dst, b, h) do { _Pragma("unroll") for (int n = 0; n < 2; ++n) _Pragma("unroll") for (int k = 0; k < 2; ++k) dst[n][k] = *(const PG8_LAS bf16x8*)(lds + PG8_SB(b, h) + boff + n * 2048 + k * 1024); } while (0)
; #define PG8_MMA(ai, bj, At, Bt) do { __builtin_amdgcn_s_setprio(1); _Pragma("unroll") for (int m = 0; m < 4; ++m) _Pragma("unroll") for (int n = 0; n < 2; ++n) _Pragma("unroll") for (int k = 0; k < 2; ++k) \
;         acc[ai][bj][m][n] = __builtin_amdgcn_mfma_f32_16x16x32_bf16(Bt[n][k], At[m][k], acc[ai][bj][m][n], 0, 0, 0); __builtin_amdgcn_s_setprio(0); } while (0)
; #define PG8_WAIT_V(n) asm volatile("s_waitcnt vmcnt(" #n ")" ::: "memory")
; template <class Epi, class Sched, bool ALIGN_EPI = false, bool SP2 = false>
; __device__ __forceinline__ void gemm_phase(PG8_LAS unsigned char* lds, const Gemm g, const Sched& S, const Epi& E) {
;     ...
;         const char* nA = has_next ? (const char*)g.A + (size_t)nxt.pm * tstep : cA; const char* nB = has_next ? (const char*)g.Bt + (size_t)nxt.pn * tstep : cB;
;         for (int t = 0; t < nt; t += 2) {
;             const bool last = (t == nt - 2);
;             const char* a1 = cA + (size_t)(t + 1) * kstep;
;             const char* a2 = last ? nA : cA + (size_t)(t + 2) * kstep; const char* b2 = last ? nB : cB + (size_t)(t + 2) * kstep;
;             const char* a3 = a2 + kstep; const char* b3 = b2 + kstep;
;             if (last && has_next) S.a_ready(nxt);
;             if constexpr (SP2) {
;             PG8_LDB(B0, 0, 0); PG8_LDB(B1, 0, 1); PG8_SCHED; PG8_LDA(At, 0, 0); PG8_STAGE(PG8_SA(1, 1), a1 + hstep, voffA);
;             PG8_WAIT_V(8); PG8_WAIT_L(0); PG8_BAR; PG8_MMA(0, 0, At, B0); PG8_MMA(0, 1, At, B1); PG8_BAR; PG8_SCHED;
;             PG8_LDA(At, 0, 1); PG8_STAGE(PG8_SB(0, 0), b2, voffB); PG8_STAGE(PG8_SB(0, 1), b2 + hstep, voffB); PG8_STAGE(PG8_SA(0, 0), a2, voffA);
.LBB0_1444:
	s_add_u32 s53, s46, s52
	s_addc_u32 s60, s47, 0
	s_add_u32 s54, s53, 0x100
	s_addc_u32 s55, s60, 0
	s_and_b64 s[8:9], s[50:51], exec
	s_cselect_b32 s55, s25, s55
	s_cselect_b32 s54, s89, s54
	s_add_u32 s8, s44, s52
	s_addc_u32 s9, s45, 0
	s_add_u32 s52, s8, 0x100
	s_addc_u32 s56, s9, 0
	s_and_b64 s[8:9], s[50:51], exec
	s_cselect_b32 s57, s23, s56
	s_cselect_b32 s56, s90, s52
	s_add_u32 s66, s53, 0x10080
	ds_read_b128 v[150:153], v146
	ds_read_b128 v[154:157], v146 offset:1024
	ds_read_b128 v[162:165], v146 offset:2048
	ds_read_b128 v[166:169], v146 offset:3072
	ds_read_b128 v[170:173], v147
	ds_read_b128 v[178:181], v147 offset:1024
	ds_read_b128 v[182:185], v147 offset:2048
	ds_read_b128 v[186:189], v147 offset:3072
	s_addc_u32 s67, s60, 0
	s_add_i32 s9, s80, s71
	s_add_i32 m0, s43, 0xc000
	s_add_i32 s60, s43, 0xe000
	s_add_i32 s84, s9, 0x2000
	s_add_u32 s64, s56, 0x10000
	s_addc_u32 s65, s57, 0
	s_add_i32 s8, s81, s71
	s_add_i32 s97, s8, 0x2000
	s_add_i32 s96, 0, 0x18000
	s_add_i32 s95, 0, 0x1c000
	s_add_u32 s52, s54, 0x10000
	s_addc_u32 s53, s55, 0
	s_add_i32 s94, s96, s71
	s_add_i32 s92, s94, 0x2000
	s_add_u32 s50, s56, 0x10080
	s_addc_u32 s51, s57, 0
	s_add_i32 s93, s95, s71
	s_add_i32 s91, s93, 0x2000
	v_lshl_add_u64 v[142:143], s[66:67], 0, v[128:129]
	ds_read_b128 v[190:193], v148
	ds_read_b128 v[194:197], v148 offset:1024
	ds_read_b128 v[198:201], v148 offset:2048
	ds_read_b128 v[202:205], v148 offset:3072
	ds_read_b128 v[206:209], v148 offset:4096
	ds_read_b128 v[210:213], v148 offset:5120
	ds_read_b128 v[214:217], v148 offset:6144
	ds_read_b128 v[218:221], v148 offset:7168
	global_load_lds_dwordx4 v[142:143], off
	v_lshl_add_u64 v[142:143], s[66:67], 0, v[132:133]
	s_mov_b32 m0, s60
	s_nop 0
	global_load_lds_dwordx4 v[142:143], off
	s_waitcnt vmcnt(8)
	s_waitcnt lgkmcnt(0)
	s_barrier
	s_setprio 1
	s_waitcnt lgkmcnt(0)
	v_mfma_f32_16x16x32_bf16 v[124:127], v[150:153], v[190:193], v[124:127]
	v_mfma_f32_16x16x32_bf16 v[120:123], v[162:165], v[190:193], v[120:123]
	v_mfma_f32_16x16x32_bf16 v[112:115], v[150:153], v[198:201], v[112:115]
	v_mfma_f32_16x16x32_bf16 v[104:107], v[162:165], v[198:201], v[104:107]
	v_mfma_f32_16x16x32_bf16 v[96:99], v[150:153], v[206:209], v[96:99]
	v_mfma_f32_16x16x32_bf16 v[88:91], v[162:165], v[206:209], v[88:91]
	v_mfma_f32_16x16x32_bf16 v[80:83], v[150:153], v[214:217], v[80:83]
	v_mfma_f32_16x16x32_bf16 v[72:75], v[162:165], v[214:217], v[72:75]
	v_mfma_f32_16x16x32_bf16 v[124:127], v[154:157], v[194:197], v[124:127]
	v_mfma_f32_16x16x32_bf16 v[120:123], v[166:169], v[194:197], v[120:123]
	v_mfma_f32_16x16x32_bf16 v[112:115], v[154:157], v[202:205], v[112:115]
	v_mfma_f32_16x16x32_bf16 v[104:107], v[166:169], v[202:205], v[104:107]
	v_mfma_f32_16x16x32_bf16 v[96:99], v[154:157], v[210:213], v[96:99]
	v_mfma_f32_16x16x32_bf16 v[88:91], v[166:169], v[210:213], v[88:91]
	v_mfma_f32_16x16x32_bf16 v[80:83], v[154:157], v[218:221], v[80:83]
	v_mfma_f32_16x16x32_bf16 v[72:75], v[166:169], v[218:221], v[72:75]
	v_mfma_f32_16x16x32_bf16 v[116:119], v[170:173], v[190:193], v[116:119]
	v_mfma_f32_16x16x32_bf16 v[108:111], v[182:185], v[190:193], v[108:111]
	v_mfma_f32_16x16x32_bf16 v[100:103], v[170:173], v[198:201], v[100:103]
	v_mfma_f32_16x16x32_bf16 v[92:95], v[182:185], v[198:201], v[92:95]
	v_mfma_f32_16x16x32_bf16 v[84:87], v[170:173], v[206:209], v[84:87]
	v_mfma_f32_16x16x32_bf16 v[76:79], v[182:185], v[206:209], v[76:79]
	v_mfma_f32_16x16x32_bf16 v[68:71], v[170:173], v[214:217], v[68:71]
	v_mfma_f32_16x16x32_bf16 v[64:67], v[182:185], v[214:217], v[64:67]
	v_mfma_f32_16x16x32_bf16 v[116:119], v[178:181], v[194:197], v[116:119]
	v_mfma_f32_16x16x32_bf16 v[108:111], v[186:189], v[194:197], v[108:111]
	v_mfma_f32_16x16x32_bf16 v[100:103], v[178:181], v[202:205], v[100:103]
	v_mfma_f32_16x16x32_bf16 v[92:95], v[186:189], v[202:205], v[92:95]
	v_mfma_f32_16x16x32_bf16 v[84:87], v[178:181], v[210:213], v[84:87]
	v_mfma_f32_16x16x32_bf16 v[76:79], v[186:189], v[210:213], v[76:79]
	v_mfma_f32_16x16x32_bf16 v[68:71], v[178:181], v[218:221], v[68:71]
	v_mfma_f32_16x16x32_bf16 v[64:67], v[186:189], v[218:221], v[64:67]
	s_setprio 0
	s_barrier
	s_mov_b32 m0, s9
	v_lshl_add_u64 v[142:143], s[56:57], 0, v[130:131]
	ds_read_b128 v[190:193], v148 offset:16384
	ds_read_b128 v[194:197], v148 offset:17408
	ds_read_b128 v[198:201], v148 offset:18432
	ds_read_b128 v[202:205], v148 offset:19456
	ds_read_b128 v[206:209], v148 offset:20480
	ds_read_b128 v[210:213], v148 offset:21504
	ds_read_b128 v[214:217], v148 offset:22528
	ds_read_b128 v[218:221], v148 offset:23552
	global_load_lds_dwordx4 v[142:143], off
	v_lshl_add_u64 v[158:159], s[56:57], 0, v[134:135]
	s_mov_b32 m0, s84
	v_lshl_add_u64 v[174:175], s[64:65], 0, v[130:131]
	global_load_lds_dwordx4 v[158:159], off
	s_mov_b32 m0, s8
	v_lshl_add_u64 v[222:223], s[54:55], 0, v[132:133]
	global_load_lds_dwordx4 v[174:175], off
	v_lshl_add_u64 v[174:175], s[64:65], 0, v[134:135]
	s_mov_b32 m0, s97
	s_nop 0
	global_load_lds_dwordx4 v[174:175], off
	v_lshl_add_u64 v[174:175], s[54:55], 0, v[128:129]
	s_mov_b32 m0, s43
	s_nop 0
	global_load_lds_dwordx4 v[174:175], off
	s_mov_b32 m0, s72
	s_nop 0
	global_load_lds_dwordx4 v[222:223], off
	s_waitcnt vmcnt(8)
	s_waitcnt lgkmcnt(0)
	s_barrier
; #define PG8_STAGE(bufoff, gbase, voff) do { _Pragma("unroll") for (int _i = 0; _i < 2; ++_i) \
;         __builtin_amdgcn_global_load_lds((const unsigned*)((const char*)(gbase) + (voff)[_i]), (PG8_LAS unsigned*)(lds + (bufoff) + ldsw + _i * 8192), 16, 0, 0); } while (0)
; #define PG8_LDA(dst, b, h) do { _Pragma("unroll") for (int m = 0; m < 4; ++m) _Pragma("unroll") for (int k = 0; k < 2; ++k) dst[m][k] = *(const PG8_LAS bf16x8*)(lds + PG8_SA(b, h) + aoff + m * 2048 + k * 1024); } while (0)
; #define PG8_LDB(dst, b, h) do { _Pragma("unroll") for (int n = 0; n < 2; ++n) _Pragma("unroll") for (int k = 0; k < 2; ++k) dst[n][k] = *(const PG8_LAS bf16x8*)(lds + PG8_SB(b, h) + boff + n * 2048 + k * 1024); } while (0)
; #define PG8_MMA(ai, bj, At, Bt) do { __builtin_amdgcn_s_setprio(1); _Pragma("unroll") for (int m = 0; m < 4; ++m) _Pragma("unroll") for (int n = 0; n < 2; ++n) _Pragma("unroll") for (int k = 0; k < 2; ++k) \
;         acc[ai][bj][m][n] = __builtin_amdgcn_mfma_f32_16x16x32_bf16(Bt[n][k], At[m][k], acc[ai][bj][m][n], 0, 0, 0); __builtin_amdgcn_s_setprio(0); } while (0)
; #define PG8_WAIT_V(n) asm volatile("s_waitcnt vmcnt(" #n ")" ::: "memory")
; template <class Epi, class Sched, bool ALIGN_EPI = false, bool SP2 = false>
; __device__ __forceinline__ void gemm_phase(PG8_LAS unsigned char* lds, const Gemm g, const Sched& S, const Epi& E) {
;     ...
;             PG8_LDB(B0, 0, 0); PG8_LDB(B1, 0, 1); PG8_SCHED; PG8_LDA(At, 0, 0); PG8_STAGE(PG8_SA(1, 1), a1 + hstep, voffA);
;             PG8_WAIT_V(8); PG8_WAIT_L(0); PG8_BAR; PG8_MMA(0, 0, At, B0); PG8_MMA(0, 1, At, B1); PG8_BAR; PG8_SCHED;
;             PG8_LDA(At, 0, 1); PG8_STAGE(PG8_SB(0, 0), b2, voffB); PG8_STAGE(PG8_SB(0, 1), b2 + hstep, voffB); PG8_STAGE(PG8_SA(0, 0), a2, voffA);
;             PG8_WAIT_V(8); PG8_WAIT_L(0); PG8_BAR; PG8_MMA(1, 0, At, B0); PG8_MMA(1, 1, At, B1); PG8_BAR; PG8_SCHED;
;             PG8_LDB(B0, 1, 0); PG8_LDB(B1, 1, 1); PG8_SCHED; PG8_LDA(At, 1, 0); PG8_STAGE(PG8_SA(0, 1), a2 + hstep, voffA);
;             PG8_WAIT_V(8); PG8_WAIT_L(0); PG8_BAR; PG8_MMA(0, 0, At, B0); PG8_MMA(0, 1, At, B1); PG8_BAR; PG8_SCHED;
;             PG8_LDA(At, 1, 1); PG8_STAGE(PG8_SB(1, 0), b3, voffB); PG8_STAGE(PG8_SB(1, 1), b3 + hstep, voffB); PG8_STAGE(PG8_SA(1, 0), a3, voffA);
;             PG8_WAIT_V(8); PG8_WAIT_L(0); PG8_BAR; PG8_MMA(1, 0, At, B0); PG8_MMA(1, 1, At, B1); PG8_BAR; PG8_SCHED;
	s_setprio 1
	s_waitcnt lgkmcnt(0)
	v_mfma_f32_16x16x32_bf16 v[60:63], v[150:153], v[190:193], v[60:63]
	v_mfma_f32_16x16x32_bf16 v[56:59], v[162:165], v[190:193], v[56:59]
	v_mfma_f32_16x16x32_bf16 v[48:51], v[150:153], v[198:201], v[48:51]
	v_mfma_f32_16x16x32_bf16 v[40:43], v[162:165], v[198:201], v[40:43]
	v_mfma_f32_16x16x32_bf16 v[32:35], v[150:153], v[206:209], v[32:35]
	v_mfma_f32_16x16x32_bf16 v[24:27], v[162:165], v[206:209], v[24:27]
	v_mfma_f32_16x16x32_bf16 v[16:19], v[150:153], v[214:217], v[16:19]
	v_mfma_f32_16x16x32_bf16 v[8:11], v[162:165], v[214:217], v[8:11]
	v_mfma_f32_16x16x32_bf16 v[60:63], v[154:157], v[194:197], v[60:63]
	v_mfma_f32_16x16x32_bf16 v[56:59], v[166:169], v[194:197], v[56:59]
	v_mfma_f32_16x16x32_bf16 v[48:51], v[154:157], v[202:205], v[48:51]
	v_mfma_f32_16x16x32_bf16 v[40:43], v[166:169], v[202:205], v[40:43]
	v_mfma_f32_16x16x32_bf16 v[32:35], v[154:157], v[210:213], v[32:35]
	v_mfma_f32_16x16x32_bf16 v[24:27], v[166:169], v[210:213], v[24:27]
	v_mfma_f32_16x16x32_bf16 v[16:19], v[154:157], v[218:221], v[16:19]
	v_mfma_f32_16x16x32_bf16 v[8:11], v[166:169], v[218:221], v[8:11]
	v_mfma_f32_16x16x32_bf16 v[52:55], v[170:173], v[190:193], v[52:55]
	v_mfma_f32_16x16x32_bf16 v[44:47], v[182:185], v[190:193], v[44:47]
	v_mfma_f32_16x16x32_bf16 v[36:39], v[170:173], v[198:201], v[36:39]
	v_mfma_f32_16x16x32_bf16 v[28:31], v[182:185], v[198:201], v[28:31]
	v_mfma_f32_16x16x32_bf16 v[20:23], v[170:173], v[206:209], v[20:23]
	v_mfma_f32_16x16x32_bf16 v[12:15], v[182:185], v[206:209], v[12:15]
	v_mfma_f32_16x16x32_bf16 v[4:7], v[170:173], v[214:217], v[4:7]
	v_mfma_f32_16x16x32_bf16 v[0:3], v[182:185], v[214:217], v[0:3]
	v_mfma_f32_16x16x32_bf16 v[52:55], v[178:181], v[194:197], v[52:55]
	v_mfma_f32_16x16x32_bf16 v[44:47], v[186:189], v[194:197], v[44:47]
	v_mfma_f32_16x16x32_bf16 v[36:39], v[178:181], v[202:205], v[36:39]
	v_mfma_f32_16x16x32_bf16 v[28:31], v[186:189], v[202:205], v[28:31]
	v_mfma_f32_16x16x32_bf16 v[20:23], v[178:181], v[210:213], v[20:23]
	v_mfma_f32_16x16x32_bf16 v[12:15], v[186:189], v[210:213], v[12:15]
	v_mfma_f32_16x16x32_bf16 v[4:7], v[178:181], v[218:221], v[4:7]
	v_mfma_f32_16x16x32_bf16 v[0:3], v[186:189], v[218:221], v[0:3]
	s_setprio 0
	s_barrier
	v_add_u32_e32 v140, s96, v144
	ds_read_b128 v[150:153], v140
	ds_read_b128 v[154:157], v140 offset:1024
	ds_read_b128 v[162:165], v140 offset:2048
	ds_read_b128 v[166:169], v140 offset:3072
	v_add_u32_e32 v140, s95, v144
	ds_read_b128 v[170:173], v140
	ds_read_b128 v[178:181], v140 offset:1024
	ds_read_b128 v[182:185], v140 offset:2048
	ds_read_b128 v[186:189], v140 offset:3072
	s_mov_b32 m0, s73
	v_lshl_add_u64 v[224:225], s[52:53], 0, v[128:129]
	ds_read_b128 v[190:193], v148 offset:32768
	ds_read_b128 v[194:197], v148 offset:33792
	ds_read_b128 v[198:201], v148 offset:34816
	ds_read_b128 v[202:205], v148 offset:35840
	ds_read_b128 v[206:209], v148 offset:36864
	ds_read_b128 v[210:213], v148 offset:37888
	ds_read_b128 v[214:217], v148 offset:38912
	ds_read_b128 v[218:221], v148 offset:39936
	global_load_lds_dwordx4 v[224:225], off
	v_lshl_add_u64 v[224:225], s[52:53], 0, v[132:133]
	s_mov_b32 m0, s74
	s_nop 0
	global_load_lds_dwordx4 v[224:225], off
	s_waitcnt vmcnt(8)
	s_waitcnt lgkmcnt(0)
	s_barrier
	s_setprio 1
	s_waitcnt lgkmcnt(0)
	v_mfma_f32_16x16x32_bf16 v[124:127], v[150:153], v[190:193], v[124:127]
	v_mfma_f32_16x16x32_bf16 v[120:123], v[162:165], v[190:193], v[120:123]
	v_mfma_f32_16x16x32_bf16 v[112:115], v[150:153], v[198:201], v[112:115]
	v_mfma_f32_16x16x32_bf16 v[104:107], v[162:165], v[198:201], v[104:107]
	v_mfma_f32_16x16x32_bf16 v[96:99], v[150:153], v[206:209], v[96:99]
	v_mfma_f32_16x16x32_bf16 v[88:91], v[162:165], v[206:209], v[88:91]
	v_mfma_f32_16x16x32_bf16 v[80:83], v[150:153], v[214:217], v[80:83]
	v_mfma_f32_16x16x32_bf16 v[72:75], v[162:165], v[214:217], v[72:75]
	v_mfma_f32_16x16x32_bf16 v[124:127], v[154:157], v[194:197], v[124:127]
	v_mfma_f32_16x16x32_bf16 v[120:123], v[166:169], v[194:197], v[120:123]
	v_mfma_f32_16x16x32_bf16 v[112:115], v[154:157], v[202:205], v[112:115]
	v_mfma_f32_16x16x32_bf16 v[104:107], v[166:169], v[202:205], v[104:107]
	v_mfma_f32_16x16x32_bf16 v[96:99], v[154:157], v[210:213], v[96:99]
	v_mfma_f32_16x16x32_bf16 v[88:91], v[166:169], v[210:213], v[88:91]
	v_mfma_f32_16x16x32_bf16 v[80:83], v[154:157], v[218:221], v[80:83]
	v_mfma_f32_16x16x32_bf16 v[72:75], v[166:169], v[218:221], v[72:75]
	v_mfma_f32_16x16x32_bf16 v[116:119], v[170:173], v[190:193], v[116:119]
	v_mfma_f32_16x16x32_bf16 v[108:111], v[182:185], v[190:193], v[108:111]
	v_mfma_f32_16x16x32_bf16 v[100:103], v[170:173], v[198:201], v[100:103]
	v_mfma_f32_16x16x32_bf16 v[92:95], v[182:185], v[198:201], v[92:95]
	v_mfma_f32_16x16x32_bf16 v[84:87], v[170:173], v[206:209], v[84:87]
	v_mfma_f32_16x16x32_bf16 v[76:79], v[182:185], v[206:209], v[76:79]
	v_mfma_f32_16x16x32_bf16 v[68:71], v[170:173], v[214:217], v[68:71]
	v_mfma_f32_16x16x32_bf16 v[64:67], v[182:185], v[214:217], v[64:67]
	v_mfma_f32_16x16x32_bf16 v[116:119], v[178:181], v[194:197], v[116:119]
	v_mfma_f32_16x16x32_bf16 v[108:111], v[186:189], v[194:197], v[108:111]
	v_mfma_f32_16x16x32_bf16 v[100:103], v[178:181], v[202:205], v[100:103]
	v_mfma_f32_16x16x32_bf16 v[92:95], v[186:189], v[202:205], v[92:95]
	v_mfma_f32_16x16x32_bf16 v[84:87], v[178:181], v[210:213], v[84:87]
	v_mfma_f32_16x16x32_bf16 v[76:79], v[186:189], v[210:213], v[76:79]
	v_mfma_f32_16x16x32_bf16 v[68:71], v[178:181], v[218:221], v[68:71]
	v_mfma_f32_16x16x32_bf16 v[64:67], v[186:189], v[218:221], v[64:67]
	s_setprio 0
	s_barrier
; #define PG8_STAGE(bufoff, gbase, voff) do { _Pragma("unroll") for (int _i = 0; _i < 2; ++_i) \
;         __builtin_amdgcn_global_load_lds((const unsigned*)((const char*)(gbase) + (voff)[_i]), (PG8_LAS unsigned*)(lds + (bufoff) + ldsw + _i * 8192), 16, 0, 0); } while (0)
; #define PG8_LDA(dst, b, h) do { _Pragma("unroll") for (int m = 0; m < 4; ++m) _Pragma("unroll") for (int k = 0; k < 2; ++k) dst[m][k] = *(const PG8_LAS bf16x8*)(lds + PG8_SA(b, h) + aoff + m * 2048 + k * 1024); } while (0)
; #define PG8_MMA(ai, bj, At, Bt) do { __builtin_amdgcn_s_setprio(1); _Pragma("unroll") for (int m = 0; m < 4; ++m) _Pragma("unroll") for (int n = 0; n < 2; ++n) _Pragma("unroll") for (int k = 0; k < 2; ++k) \
;         acc[ai][bj][m][n] = __builtin_amdgcn_mfma_f32_16x16x32_bf16(Bt[n][k], At[m][k], acc[ai][bj][m][n], 0, 0, 0); __builtin_amdgcn_s_setprio(0); } while (0)
; #define PG8_WAIT_V(n) asm volatile("s_waitcnt vmcnt(" #n ")" ::: "memory")
; #define PG8_WAIT_L(n) asm volatile("s_waitcnt lgkmcnt(" #n ")" ::: "memory")
; #define PG8_BAR __builtin_amdgcn_s_barrier()
; #define PG8_SCHED __builtin_amdgcn_sched_barrier(0)
; template <class Epi, class Sched, bool ALIGN_EPI = false, bool SP2 = false>
; __device__ __forceinline__ void gemm_phase(PG8_LAS unsigned char* lds, const Gemm g, const Sched& S, const Epi& E) {
;     ...
;             PG8_LDA(At, 1, 1); PG8_STAGE(PG8_SB(1, 0), b3, voffB); PG8_STAGE(PG8_SB(1, 1), b3 + hstep, voffB); PG8_STAGE(PG8_SA(1, 0), a3, voffA);
;             PG8_WAIT_V(8); PG8_WAIT_L(0); PG8_BAR; PG8_MMA(1, 0, At, B0); PG8_MMA(1, 1, At, B1); PG8_BAR; PG8_SCHED;
;     ...
;         if constexpr (ALIGN_EPI) { if (wr == 0) PG8_BAR; }
	s_mov_b32 m0, s94
	v_lshl_add_u64 v[142:143], v[142:143], 0, s[6:7]
	ds_read_b128 v[190:193], v148 offset:49152
	ds_read_b128 v[194:197], v148 offset:50176
	ds_read_b128 v[198:201], v148 offset:51200
	ds_read_b128 v[202:205], v148 offset:52224
	ds_read_b128 v[206:209], v148 offset:53248
	ds_read_b128 v[210:213], v148 offset:54272
	ds_read_b128 v[214:217], v148 offset:55296
	ds_read_b128 v[218:221], v148 offset:56320
	global_load_lds_dwordx4 v[142:143], off
	v_lshl_add_u64 v[142:143], v[158:159], 0, s[6:7]
	s_mov_b32 m0, s92
	s_nop 0
	global_load_lds_dwordx4 v[142:143], off
	v_lshl_add_u64 v[142:143], s[50:51], 0, v[130:131]
	s_mov_b32 m0, s93
	s_nop 0
	global_load_lds_dwordx4 v[142:143], off
	v_lshl_add_u64 v[142:143], s[50:51], 0, v[134:135]
	s_mov_b32 m0, s91
	s_nop 0
	global_load_lds_dwordx4 v[142:143], off
	v_lshl_add_u64 v[142:143], v[174:175], 0, s[6:7]
	s_mov_b32 m0, s76
	s_nop 0
	global_load_lds_dwordx4 v[142:143], off
	v_lshl_add_u64 v[142:143], v[222:223], 0, s[6:7]
	s_mov_b32 m0, s77
	s_nop 0
	global_load_lds_dwordx4 v[142:143], off
	s_waitcnt vmcnt(8)
	s_waitcnt lgkmcnt(0)
	s_barrier
	s_setprio 1
	s_waitcnt lgkmcnt(0)
	v_mfma_f32_16x16x32_bf16 v[60:63], v[150:153], v[190:193], v[60:63]
	v_mfma_f32_16x16x32_bf16 v[56:59], v[162:165], v[190:193], v[56:59]
	v_mfma_f32_16x16x32_bf16 v[48:51], v[150:153], v[198:201], v[48:51]
	v_mfma_f32_16x16x32_bf16 v[40:43], v[162:165], v[198:201], v[40:43]
	v_mfma_f32_16x16x32_bf16 v[32:35], v[150:153], v[206:209], v[32:35]
	v_mfma_f32_16x16x32_bf16 v[24:27], v[162:165], v[206:209], v[24:27]
	v_mfma_f32_16x16x32_bf16 v[16:19], v[150:153], v[214:217], v[16:19]
	v_mfma_f32_16x16x32_bf16 v[8:11], v[162:165], v[214:217], v[8:11]
	v_mfma_f32_16x16x32_bf16 v[60:63], v[154:157], v[194:197], v[60:63]
	v_mfma_f32_16x16x32_bf16 v[56:59], v[166:169], v[194:197], v[56:59]
	v_mfma_f32_16x16x32_bf16 v[48:51], v[154:157], v[202:205], v[48:51]
	v_mfma_f32_16x16x32_bf16 v[40:43], v[166:169], v[202:205], v[40:43]
	v_mfma_f32_16x16x32_bf16 v[32:35], v[154:157], v[210:213], v[32:35]
	v_mfma_f32_16x16x32_bf16 v[24:27], v[166:169], v[210:213], v[24:27]
	v_mfma_f32_16x16x32_bf16 v[16:19], v[154:157], v[218:221], v[16:19]
	v_mfma_f32_16x16x32_bf16 v[8:11], v[166:169], v[218:221], v[8:11]
	v_mfma_f32_16x16x32_bf16 v[52:55], v[170:173], v[190:193], v[52:55]
	v_mfma_f32_16x16x32_bf16 v[44:47], v[182:185], v[190:193], v[44:47]
	v_mfma_f32_16x16x32_bf16 v[36:39], v[170:173], v[198:201], v[36:39]
	v_mfma_f32_16x16x32_bf16 v[28:31], v[182:185], v[198:201], v[28:31]
	v_mfma_f32_16x16x32_bf16 v[20:23], v[170:173], v[206:209], v[20:23]
	v_mfma_f32_16x16x32_bf16 v[12:15], v[182:185], v[206:209], v[12:15]
	v_mfma_f32_16x16x32_bf16 v[4:7], v[170:173], v[214:217], v[4:7]
	v_mfma_f32_16x16x32_bf16 v[0:3], v[182:185], v[214:217], v[0:3]
	v_mfma_f32_16x16x32_bf16 v[52:55], v[178:181], v[194:197], v[52:55]
	v_mfma_f32_16x16x32_bf16 v[44:47], v[186:189], v[194:197], v[44:47]
	v_mfma_f32_16x16x32_bf16 v[36:39], v[178:181], v[202:205], v[36:39]
	v_mfma_f32_16x16x32_bf16 v[28:31], v[186:189], v[202:205], v[28:31]
	v_mfma_f32_16x16x32_bf16 v[20:23], v[178:181], v[210:213], v[20:23]
	v_mfma_f32_16x16x32_bf16 v[12:15], v[186:189], v[210:213], v[12:15]
	v_mfma_f32_16x16x32_bf16 v[4:7], v[178:181], v[218:221], v[4:7]
	v_mfma_f32_16x16x32_bf16 v[0:3], v[186:189], v[218:221], v[0:3]
	s_setprio 0
	s_barrier
	s_movk_i32 s52, 0x100
	s_andn2_b64 vcc, exec, s[48:49]
	s_mov_b64 s[50:51], -1
	s_mov_b64 s[48:49], 0
	s_cbranch_vccz .LBB0_1444
	s_and_b64 vcc, exec, s[12:13]
	s_cbranch_vccz .LBB0_1447
	s_barrier

; #define PG8_STAGE(bufoff, gbase, voff) do { _Pragma("unroll") for (int _i = 0; _i < 2; ++_i) \
;         __builtin_amdgcn_global_load_lds((const unsigned*)((const char*)(gbase) + (voff)[_i]), (PG8_LAS unsigned*)(lds + (bufoff) + ldsw + _i * 8192), 16, 0, 0); } while (0)
; #define PG8_LDA(dst, b, h) do { _Pragma("unroll") for (int m = 0; m < 4; ++m) _Pragma("unroll") for (int k = 0; k < 2; ++k) dst[m][k] = *(const PG8_LAS bf16x8*)(lds + PG8_SA(b, h) + aoff + m * 2048 + k * 1024); } while (0)
; #define PG8_LDB(dst, b, h) do { _Pragma("unroll") for (int n = 0; n < 2; ++n) _Pragma("unroll") for (int k = 0; k < 2; ++k) dst[n][k] = *(const PG8_LAS bf16x8*)(lds + PG8_SB(b, h) + boff + n * 2048 + k * 1024); } while (0)
; #define PG8_MMA(ai, bj, At, Bt) do { __builtin_amdgcn_s_setprio(1); _Pragma("unroll") for (int m = 0; m < 4; ++m) _Pragma("unroll") for (int n = 0; n < 2; ++n) _Pragma("unroll") for (int k = 0; k < 2; ++k) \
;         acc[ai][bj][m][n] = __builtin_amdgcn_mfma_f32_16x16x32_bf16(Bt[n][k], At[m][k], acc[ai][bj][m][n], 0, 0, 0); __builtin_amdgcn_s_setprio(0); } while (0)
; #define PG8_WAIT_V(n) asm volatile("s_waitcnt vmcnt(" #n ")" ::: "memory")
; #define PG8_WAIT_L(n) asm volatile("s_waitcnt lgkmcnt(" #n ")" ::: "memory")
; template <class Epi, class Sched, bool ALIGN_EPI = false, bool SP2 = false>
; __device__ __forceinline__ void gemm_phase(PG8_LAS unsigned char* lds, const Gemm g, const Sched& S, const Epi& E) {
;     ...
;             const bool last = (t == nt - 2);
;             const char* a1 = cA + (size_t)(t + 1) * kstep;
;             const char* a2 = last ? nA : cA + (size_t)(t + 2) * kstep; const char* b2 = last ? nB : cB + (size_t)(t + 2) * kstep;
;             const char* a3 = a2 + kstep; const char* b3 = b2 + kstep;
;             if (last && has_next) S.a_ready(nxt);
;             if constexpr (SP2) {
;             PG8_LDB(B0, 0, 0); PG8_LDB(B1, 0, 1); PG8_SCHED; PG8_LDA(At, 0, 0); PG8_STAGE(PG8_SA(1, 1), a1 + hstep, voffA);
;             PG8_WAIT_V(8); PG8_WAIT_L(0); PG8_BAR; PG8_MMA(0, 0, At, B0); PG8_MMA(0, 1, At, B1); PG8_BAR; PG8_SCHED;
;             PG8_LDA(At, 0, 1); PG8_STAGE(PG8_SB(0, 0), b2, voffB); PG8_STAGE(PG8_SB(0, 1), b2 + hstep, voffB); PG8_STAGE(PG8_SA(0, 0), a2, voffA);
;             PG8_WAIT_V(8); PG8_WAIT_L(0); PG8_BAR; PG8_MMA(1, 0, At, B0); PG8_MMA(1, 1, At, B1); PG8_BAR; PG8_SCHED;
.LBB0_1617:
	ds_read_b128 v[144:147], v153
	ds_read_b128 v[156:159], v153 offset:1024
	ds_read_b128 v[160:163], v153 offset:2048
	ds_read_b128 v[164:167], v153 offset:3072
	ds_read_b128 v[168:171], v154
	ds_read_b128 v[172:175], v154 offset:1024
	ds_read_b128 v[176:179], v154 offset:2048
	ds_read_b128 v[180:183], v154 offset:3072
	s_add_u32 s40, s38, 0xfffc0080
	s_addc_u32 s41, s39, -1
	s_cmp_eq_u32 s61, 12
	s_cselect_b32 s43, s25, s41
	s_cselect_b32 s42, s55, s40
	s_cselect_b32 s41, s23, s60
	s_cselect_b32 s40, s56, s57
	v_lshl_add_u64 v[148:149], s[38:39], 0, v[136:137]
	s_add_i32 m0, s31, 0xc000
	ds_read_b128 v[184:187], v155
	ds_read_b128 v[188:191], v155 offset:1024
	ds_read_b128 v[192:195], v155 offset:2048
	ds_read_b128 v[196:199], v155 offset:3072
	ds_read_b128 v[200:203], v155 offset:4096
	ds_read_b128 v[204:207], v155 offset:5120
	ds_read_b128 v[208:211], v155 offset:6144
	ds_read_b128 v[212:215], v155 offset:7168
	global_load_lds_dwordx4 v[148:149], off
	v_lshl_add_u64 v[148:149], s[38:39], 0, v[138:139]
	s_add_i32 m0, s31, 0xe000
	s_nop 0
	global_load_lds_dwordx4 v[148:149], off
	s_waitcnt vmcnt(8)
	s_waitcnt lgkmcnt(0)
	s_barrier
	s_setprio 1
	s_waitcnt lgkmcnt(0)
	v_mfma_f32_16x16x32_bf16 v[124:127], v[144:147], v[184:187], v[124:127]
	v_mfma_f32_16x16x32_bf16 v[120:123], v[160:163], v[184:187], v[120:123]
	v_mfma_f32_16x16x32_bf16 v[108:111], v[144:147], v[192:195], v[108:111]
	v_mfma_f32_16x16x32_bf16 v[104:107], v[160:163], v[192:195], v[104:107]
	v_mfma_f32_16x16x32_bf16 v[92:95], v[144:147], v[200:203], v[92:95]
	v_mfma_f32_16x16x32_bf16 v[88:91], v[160:163], v[200:203], v[88:91]
	v_mfma_f32_16x16x32_bf16 v[76:79], v[144:147], v[208:211], v[76:79]
	v_mfma_f32_16x16x32_bf16 v[72:75], v[160:163], v[208:211], v[72:75]
	v_mfma_f32_16x16x32_bf16 v[124:127], v[156:159], v[188:191], v[124:127]
	v_mfma_f32_16x16x32_bf16 v[120:123], v[164:167], v[188:191], v[120:123]
	v_mfma_f32_16x16x32_bf16 v[108:111], v[156:159], v[196:199], v[108:111]
	v_mfma_f32_16x16x32_bf16 v[104:107], v[164:167], v[196:199], v[104:107]
	v_mfma_f32_16x16x32_bf16 v[92:95], v[156:159], v[204:207], v[92:95]
	v_mfma_f32_16x16x32_bf16 v[88:91], v[164:167], v[204:207], v[88:91]
	v_mfma_f32_16x16x32_bf16 v[76:79], v[156:159], v[212:215], v[76:79]
	v_mfma_f32_16x16x32_bf16 v[72:75], v[164:167], v[212:215], v[72:75]
	v_mfma_f32_16x16x32_bf16 v[116:119], v[168:171], v[184:187], v[116:119]
	v_mfma_f32_16x16x32_bf16 v[112:115], v[176:179], v[184:187], v[112:115]
	v_mfma_f32_16x16x32_bf16 v[100:103], v[168:171], v[192:195], v[100:103]
	v_mfma_f32_16x16x32_bf16 v[96:99], v[176:179], v[192:195], v[96:99]
	v_mfma_f32_16x16x32_bf16 v[84:87], v[168:171], v[200:203], v[84:87]
	v_mfma_f32_16x16x32_bf16 v[80:83], v[176:179], v[200:203], v[80:83]
	v_mfma_f32_16x16x32_bf16 v[68:71], v[168:171], v[208:211], v[68:71]
	v_mfma_f32_16x16x32_bf16 v[64:67], v[176:179], v[208:211], v[64:67]
	v_mfma_f32_16x16x32_bf16 v[116:119], v[172:175], v[188:191], v[116:119]
	v_mfma_f32_16x16x32_bf16 v[112:115], v[180:183], v[188:191], v[112:115]
	v_mfma_f32_16x16x32_bf16 v[100:103], v[172:175], v[196:199], v[100:103]
	v_mfma_f32_16x16x32_bf16 v[96:99], v[180:183], v[196:199], v[96:99]
	v_mfma_f32_16x16x32_bf16 v[84:87], v[172:175], v[204:207], v[84:87]
	v_mfma_f32_16x16x32_bf16 v[80:83], v[180:183], v[204:207], v[80:83]
	v_mfma_f32_16x16x32_bf16 v[68:71], v[172:175], v[212:215], v[68:71]
	v_mfma_f32_16x16x32_bf16 v[64:67], v[180:183], v[212:215], v[64:67]
	s_setprio 0
	s_barrier
	s_add_i32 s62, s52, s44
	v_lshl_add_u64 v[148:149], s[40:41], 0, v[130:131]
	s_mov_b32 m0, s62
	ds_read_b128 v[184:187], v155 offset:16384
	ds_read_b128 v[188:191], v155 offset:17408
	ds_read_b128 v[192:195], v155 offset:18432
	ds_read_b128 v[196:199], v155 offset:19456
	ds_read_b128 v[200:203], v155 offset:20480
	ds_read_b128 v[204:207], v155 offset:21504
	ds_read_b128 v[208:211], v155 offset:22528
	ds_read_b128 v[212:215], v155 offset:23552
	global_load_lds_dwordx4 v[148:149], off
	s_add_i32 m0, s62, 0x2000
	s_add_u32 s62, s40, 0x40000
	v_lshl_add_u64 v[216:217], s[40:41], 0, v[134:135]
	s_addc_u32 s63, s41, 0
	s_add_i32 s64, s53, s44
	global_load_lds_dwordx4 v[216:217], off
	v_lshl_add_u64 v[218:219], s[62:63], 0, v[130:131]
	s_mov_b32 m0, s64
	v_lshl_add_u64 v[220:221], s[42:43], 0, v[132:133]
	global_load_lds_dwordx4 v[218:219], off
	v_lshl_add_u64 v[218:219], s[62:63], 0, v[134:135]
	s_add_i32 m0, s64, 0x2000
	s_nop 0
	global_load_lds_dwordx4 v[218:219], off
	v_lshl_add_u64 v[218:219], s[42:43], 0, v[128:129]
	s_mov_b32 m0, s31
	s_nop 0
	global_load_lds_dwordx4 v[218:219], off
	s_mov_b32 m0, s45
	s_nop 0
	global_load_lds_dwordx4 v[220:221], off
	s_waitcnt vmcnt(8)
	s_waitcnt lgkmcnt(0)
	s_barrier
; #define PG8_STAGE(bufoff, gbase, voff) do { _Pragma("unroll") for (int _i = 0; _i < 2; ++_i) \
;         __builtin_amdgcn_global_load_lds((const unsigned*)((const char*)(gbase) + (voff)[_i]), (PG8_LAS unsigned*)(lds + (bufoff) + ldsw + _i * 8192), 16, 0, 0); } while (0)
; #define PG8_LDA(dst, b, h) do { _Pragma("unroll") for (int m = 0; m < 4; ++m) _Pragma("unroll") for (int k = 0; k < 2; ++k) dst[m][k] = *(const PG8_LAS bf16x8*)(lds + PG8_SA(b, h) + aoff + m * 2048 + k * 1024); } while (0)
; #define PG8_LDB(dst, b, h) do { _Pragma("unroll") for (int n = 0; n < 2; ++n) _Pragma("unroll") for (int k = 0; k < 2; ++k) dst[n][k] = *(const PG8_LAS bf16x8*)(lds + PG8_SB(b, h) + boff + n * 2048 + k * 1024); } while (0)
; #define PG8_MMA(ai, bj, At, Bt) do { __builtin_amdgcn_s_setprio(1); _Pragma("unroll") for (int m = 0; m < 4; ++m) _Pragma("unroll") for (int n = 0; n < 2; ++n) _Pragma("unroll") for (int k = 0; k < 2; ++k) \
;         acc[ai][bj][m][n] = __builtin_amdgcn_mfma_f32_16x16x32_bf16(Bt[n][k], At[m][k], acc[ai][bj][m][n], 0, 0, 0); __builtin_amdgcn_s_setprio(0); } while (0)
; #define PG8_WAIT_V(n) asm volatile("s_waitcnt vmcnt(" #n ")" ::: "memory")
; #define PG8_WAIT_L(n) asm volatile("s_waitcnt lgkmcnt(" #n ")" ::: "memory")
; #define PG8_BAR __builtin_amdgcn_s_barrier()
; #define PG8_SCHED __builtin_amdgcn_sched_barrier(0)
; template <class Epi, class Sched, bool ALIGN_EPI = false, bool SP2 = false>
; __device__ __forceinline__ void gemm_phase(PG8_LAS unsigned char* lds, const Gemm g, const Sched& S, const Epi& E) {
;     ...
;             PG8_WAIT_V(8); PG8_WAIT_L(0); PG8_BAR; PG8_MMA(1, 0, At, B0); PG8_MMA(1, 1, At, B1); PG8_BAR; PG8_SCHED;
;             PG8_LDB(B0, 1, 0); PG8_LDB(B1, 1, 1); PG8_SCHED; PG8_LDA(At, 1, 0); PG8_STAGE(PG8_SA(0, 1), a2 + hstep, voffA);
;             PG8_WAIT_V(8); PG8_WAIT_L(0); PG8_BAR; PG8_MMA(0, 0, At, B0); PG8_MMA(0, 1, At, B1); PG8_BAR; PG8_SCHED;
	s_setprio 1
	s_waitcnt lgkmcnt(0)
	v_mfma_f32_16x16x32_bf16 v[60:63], v[144:147], v[184:187], v[60:63]
	v_mfma_f32_16x16x32_bf16 v[56:59], v[160:163], v[184:187], v[56:59]
	v_mfma_f32_16x16x32_bf16 v[44:47], v[144:147], v[192:195], v[44:47]
	v_mfma_f32_16x16x32_bf16 v[40:43], v[160:163], v[192:195], v[40:43]
	v_mfma_f32_16x16x32_bf16 v[28:31], v[144:147], v[200:203], v[28:31]
	v_mfma_f32_16x16x32_bf16 v[24:27], v[160:163], v[200:203], v[24:27]
	v_mfma_f32_16x16x32_bf16 v[12:15], v[144:147], v[208:211], v[12:15]
	v_mfma_f32_16x16x32_bf16 v[8:11], v[160:163], v[208:211], v[8:11]
	v_mfma_f32_16x16x32_bf16 v[60:63], v[156:159], v[188:191], v[60:63]
	v_mfma_f32_16x16x32_bf16 v[56:59], v[164:167], v[188:191], v[56:59]
	v_mfma_f32_16x16x32_bf16 v[44:47], v[156:159], v[196:199], v[44:47]
	v_mfma_f32_16x16x32_bf16 v[40:43], v[164:167], v[196:199], v[40:43]
	v_mfma_f32_16x16x32_bf16 v[28:31], v[156:159], v[204:207], v[28:31]
	v_mfma_f32_16x16x32_bf16 v[24:27], v[164:167], v[204:207], v[24:27]
	v_mfma_f32_16x16x32_bf16 v[12:15], v[156:159], v[212:215], v[12:15]
	v_mfma_f32_16x16x32_bf16 v[8:11], v[164:167], v[212:215], v[8:11]
	v_mfma_f32_16x16x32_bf16 v[52:55], v[168:171], v[184:187], v[52:55]
	v_mfma_f32_16x16x32_bf16 v[48:51], v[176:179], v[184:187], v[48:51]
	v_mfma_f32_16x16x32_bf16 v[36:39], v[168:171], v[192:195], v[36:39]
	v_mfma_f32_16x16x32_bf16 v[32:35], v[176:179], v[192:195], v[32:35]
	v_mfma_f32_16x16x32_bf16 v[20:23], v[168:171], v[200:203], v[20:23]
	v_mfma_f32_16x16x32_bf16 v[16:19], v[176:179], v[200:203], v[16:19]
	v_mfma_f32_16x16x32_bf16 v[4:7], v[168:171], v[208:211], v[4:7]
	v_mfma_f32_16x16x32_bf16 v[0:3], v[176:179], v[208:211], v[0:3]
	v_mfma_f32_16x16x32_bf16 v[52:55], v[172:175], v[188:191], v[52:55]
	v_mfma_f32_16x16x32_bf16 v[48:51], v[180:183], v[188:191], v[48:51]
	v_mfma_f32_16x16x32_bf16 v[36:39], v[172:175], v[196:199], v[36:39]
	v_mfma_f32_16x16x32_bf16 v[32:35], v[180:183], v[196:199], v[32:35]
	v_mfma_f32_16x16x32_bf16 v[20:23], v[172:175], v[204:207], v[20:23]
	v_mfma_f32_16x16x32_bf16 v[16:19], v[180:183], v[204:207], v[16:19]
	v_mfma_f32_16x16x32_bf16 v[4:7], v[172:175], v[212:215], v[4:7]
	v_mfma_f32_16x16x32_bf16 v[0:3], v[180:183], v[212:215], v[0:3]
	s_setprio 0
	s_barrier
	s_add_i32 s62, 0, 0x18000
	s_add_i32 s63, 0, 0x1c000
	v_add_u32_e32 v164, s62, v151
	v_add_u32_e32 v180, s63, v151
	ds_read_b128 v[144:147], v164
	ds_read_b128 v[156:159], v164 offset:1024
	ds_read_b128 v[160:163], v164 offset:2048
	ds_read_b128 v[164:167], v164 offset:3072
	ds_read_b128 v[168:171], v180
	ds_read_b128 v[172:175], v180 offset:1024
	ds_read_b128 v[176:179], v180 offset:2048
	ds_read_b128 v[180:183], v180 offset:3072
	s_add_u32 s42, s42, 0x40000
	s_addc_u32 s43, s43, 0
	s_mov_b32 m0, s46
	v_lshl_add_u64 v[222:223], s[42:43], 0, v[128:129]
	ds_read_b128 v[184:187], v155 offset:32768
	ds_read_b128 v[188:191], v155 offset:33792
	ds_read_b128 v[192:195], v155 offset:34816
	ds_read_b128 v[196:199], v155 offset:35840
	ds_read_b128 v[200:203], v155 offset:36864
	ds_read_b128 v[204:207], v155 offset:37888
	ds_read_b128 v[208:211], v155 offset:38912
	ds_read_b128 v[212:215], v155 offset:39936
	global_load_lds_dwordx4 v[222:223], off
	v_lshl_add_u64 v[222:223], s[42:43], 0, v[132:133]
	s_mov_b32 m0, s47
	s_nop 0
	global_load_lds_dwordx4 v[222:223], off
	s_waitcnt vmcnt(8)
	s_waitcnt lgkmcnt(0)
	s_barrier
	s_setprio 1
	s_waitcnt lgkmcnt(0)
	v_mfma_f32_16x16x32_bf16 v[124:127], v[144:147], v[184:187], v[124:127]
	v_mfma_f32_16x16x32_bf16 v[120:123], v[160:163], v[184:187], v[120:123]
	v_mfma_f32_16x16x32_bf16 v[108:111], v[144:147], v[192:195], v[108:111]
	v_mfma_f32_16x16x32_bf16 v[104:107], v[160:163], v[192:195], v[104:107]
	v_mfma_f32_16x16x32_bf16 v[92:95], v[144:147], v[200:203], v[92:95]
	v_mfma_f32_16x16x32_bf16 v[88:91], v[160:163], v[200:203], v[88:91]
	v_mfma_f32_16x16x32_bf16 v[76:79], v[144:147], v[208:211], v[76:79]
	v_mfma_f32_16x16x32_bf16 v[72:75], v[160:163], v[208:211], v[72:75]
	v_mfma_f32_16x16x32_bf16 v[124:127], v[156:159], v[188:191], v[124:127]
	v_mfma_f32_16x16x32_bf16 v[120:123], v[164:167], v[188:191], v[120:123]
	v_mfma_f32_16x16x32_bf16 v[108:111], v[156:159], v[196:199], v[108:111]
	v_mfma_f32_16x16x32_bf16 v[104:107], v[164:167], v[196:199], v[104:107]
	v_mfma_f32_16x16x32_bf16 v[92:95], v[156:159], v[204:207], v[92:95]
	v_mfma_f32_16x16x32_bf16 v[88:91], v[164:167], v[204:207], v[88:91]
	v_mfma_f32_16x16x32_bf16 v[76:79], v[156:159], v[212:215], v[76:79]
	v_mfma_f32_16x16x32_bf16 v[72:75], v[164:167], v[212:215], v[72:75]
	v_mfma_f32_16x16x32_bf16 v[116:119], v[168:171], v[184:187], v[116:119]
	v_mfma_f32_16x16x32_bf16 v[112:115], v[176:179], v[184:187], v[112:115]
	v_mfma_f32_16x16x32_bf16 v[100:103], v[168:171], v[192:195], v[100:103]
	v_mfma_f32_16x16x32_bf16 v[96:99], v[176:179], v[192:195], v[96:99]
	v_mfma_f32_16x16x32_bf16 v[84:87], v[168:171], v[200:203], v[84:87]
	v_mfma_f32_16x16x32_bf16 v[80:83], v[176:179], v[200:203], v[80:83]
	v_mfma_f32_16x16x32_bf16 v[68:71], v[168:171], v[208:211], v[68:71]
	v_mfma_f32_16x16x32_bf16 v[64:67], v[176:179], v[208:211], v[64:67]
	v_mfma_f32_16x16x32_bf16 v[116:119], v[172:175], v[188:191], v[116:119]
	v_mfma_f32_16x16x32_bf16 v[112:115], v[180:183], v[188:191], v[112:115]
	v_mfma_f32_16x16x32_bf16 v[100:103], v[172:175], v[196:199], v[100:103]
	v_mfma_f32_16x16x32_bf16 v[96:99], v[180:183], v[196:199], v[96:99]
	v_mfma_f32_16x16x32_bf16 v[84:87], v[172:175], v[204:207], v[84:87]
	v_mfma_f32_16x16x32_bf16 v[80:83], v[180:183], v[204:207], v[80:83]
	v_mfma_f32_16x16x32_bf16 v[68:71], v[172:175], v[212:215], v[68:71]
	v_mfma_f32_16x16x32_bf16 v[64:67], v[180:183], v[212:215], v[64:67]
	s_setprio 0
	s_barrier
; #define PG8_STAGE(bufoff, gbase, voff) do { _Pragma("unroll") for (int _i = 0; _i < 2; ++_i) \
;         __builtin_amdgcn_global_load_lds((const unsigned*)((const char*)(gbase) + (voff)[_i]), (PG8_LAS unsigned*)(lds + (bufoff) + ldsw + _i * 8192), 16, 0, 0); } while (0)
; #define PG8_LDA(dst, b, h) do { _Pragma("unroll") for (int m = 0; m < 4; ++m) _Pragma("unroll") for (int k = 0; k < 2; ++k) dst[m][k] = *(const PG8_LAS bf16x8*)(lds + PG8_SA(b, h) + aoff + m * 2048 + k * 1024); } while (0)
; #define PG8_MMA(ai, bj, At, Bt) do { __builtin_amdgcn_s_setprio(1); _Pragma("unroll") for (int m = 0; m < 4; ++m) _Pragma("unroll") for (int n = 0; n < 2; ++n) _Pragma("unroll") for (int k = 0; k < 2; ++k) \
;         acc[ai][bj][m][n] = __builtin_amdgcn_mfma_f32_16x16x32_bf16(Bt[n][k], At[m][k], acc[ai][bj][m][n], 0, 0, 0); __builtin_amdgcn_s_setprio(0); } while (0)
; #define PG8_WAIT_V(n) asm volatile("s_waitcnt vmcnt(" #n ")" ::: "memory")
; #define PG8_WAIT_L(n) asm volatile("s_waitcnt lgkmcnt(" #n ")" ::: "memory")
; #define PG8_BAR __builtin_amdgcn_s_barrier()
; #define PG8_SCHED __builtin_amdgcn_sched_barrier(0)
; template <class Epi, class Sched, bool ALIGN_EPI = false, bool SP2 = false>
; __device__ __forceinline__ void gemm_phase(PG8_LAS unsigned char* lds, const Gemm g, const Sched& S, const Epi& E) {
;     ...
;             PG8_LDA(At, 1, 1); PG8_STAGE(PG8_SB(1, 0), b3, voffB); PG8_STAGE(PG8_SB(1, 1), b3 + hstep, voffB); PG8_STAGE(PG8_SA(1, 0), a3, voffA);
;             PG8_WAIT_V(8); PG8_WAIT_L(0); PG8_BAR; PG8_MMA(1, 0, At, B0); PG8_MMA(1, 1, At, B1); PG8_BAR; PG8_SCHED;
;     ...
;         if constexpr (ALIGN_EPI) { if (wr == 0) PG8_BAR; }
	s_add_i32 s42, s62, s44
	v_lshl_add_u64 v[148:149], v[148:149], 0, s[6:7]
	s_mov_b32 m0, s42
	ds_read_b128 v[184:187], v155 offset:49152
	ds_read_b128 v[188:191], v155 offset:50176
	ds_read_b128 v[192:195], v155 offset:51200
	ds_read_b128 v[196:199], v155 offset:52224
	ds_read_b128 v[200:203], v155 offset:53248
	ds_read_b128 v[204:207], v155 offset:54272
	ds_read_b128 v[208:211], v155 offset:55296
	ds_read_b128 v[212:215], v155 offset:56320
	global_load_lds_dwordx4 v[148:149], off
	s_add_i32 m0, s42, 0x2000
	s_add_u32 s40, s40, 0x40080
	v_lshl_add_u64 v[148:149], v[216:217], 0, s[6:7]
	s_addc_u32 s41, s41, 0
	s_add_i32 s42, s63, s44
	global_load_lds_dwordx4 v[148:149], off
	v_lshl_add_u64 v[148:149], s[40:41], 0, v[130:131]
	s_mov_b32 m0, s42
	s_nop 0
	global_load_lds_dwordx4 v[148:149], off
	v_lshl_add_u64 v[148:149], s[40:41], 0, v[134:135]
	s_add_i32 m0, s42, 0x2000
	s_nop 0
	global_load_lds_dwordx4 v[148:149], off
	v_lshl_add_u64 v[148:149], v[218:219], 0, s[6:7]
	s_mov_b32 m0, s49
	s_nop 0
	global_load_lds_dwordx4 v[148:149], off
	v_lshl_add_u64 v[148:149], v[220:221], 0, s[6:7]
	s_mov_b32 m0, s50
	s_nop 0
	global_load_lds_dwordx4 v[148:149], off
	s_waitcnt vmcnt(8)
	s_waitcnt lgkmcnt(0)
	s_barrier
	s_setprio 1
	s_waitcnt lgkmcnt(0)
	v_mfma_f32_16x16x32_bf16 v[60:63], v[144:147], v[184:187], v[60:63]
	v_mfma_f32_16x16x32_bf16 v[56:59], v[160:163], v[184:187], v[56:59]
	v_mfma_f32_16x16x32_bf16 v[44:47], v[144:147], v[192:195], v[44:47]
	v_mfma_f32_16x16x32_bf16 v[40:43], v[160:163], v[192:195], v[40:43]
	v_mfma_f32_16x16x32_bf16 v[28:31], v[144:147], v[200:203], v[28:31]
	v_mfma_f32_16x16x32_bf16 v[24:27], v[160:163], v[200:203], v[24:27]
	v_mfma_f32_16x16x32_bf16 v[12:15], v[144:147], v[208:211], v[12:15]
	v_mfma_f32_16x16x32_bf16 v[8:11], v[160:163], v[208:211], v[8:11]
	v_mfma_f32_16x16x32_bf16 v[60:63], v[156:159], v[188:191], v[60:63]
	v_mfma_f32_16x16x32_bf16 v[56:59], v[164:167], v[188:191], v[56:59]
	v_mfma_f32_16x16x32_bf16 v[44:47], v[156:159], v[196:199], v[44:47]
	v_mfma_f32_16x16x32_bf16 v[40:43], v[164:167], v[196:199], v[40:43]
	v_mfma_f32_16x16x32_bf16 v[28:31], v[156:159], v[204:207], v[28:31]
	v_mfma_f32_16x16x32_bf16 v[24:27], v[164:167], v[204:207], v[24:27]
	v_mfma_f32_16x16x32_bf16 v[12:15], v[156:159], v[212:215], v[12:15]
	v_mfma_f32_16x16x32_bf16 v[8:11], v[164:167], v[212:215], v[8:11]
	v_mfma_f32_16x16x32_bf16 v[52:55], v[168:171], v[184:187], v[52:55]
	v_mfma_f32_16x16x32_bf16 v[48:51], v[176:179], v[184:187], v[48:51]
	v_mfma_f32_16x16x32_bf16 v[36:39], v[168:171], v[192:195], v[36:39]
	v_mfma_f32_16x16x32_bf16 v[32:35], v[176:179], v[192:195], v[32:35]
	v_mfma_f32_16x16x32_bf16 v[20:23], v[168:171], v[200:203], v[20:23]
	v_mfma_f32_16x16x32_bf16 v[16:19], v[176:179], v[200:203], v[16:19]
	v_mfma_f32_16x16x32_bf16 v[4:7], v[168:171], v[208:211], v[4:7]
	v_mfma_f32_16x16x32_bf16 v[0:3], v[176:179], v[208:211], v[0:3]
	v_mfma_f32_16x16x32_bf16 v[52:55], v[172:175], v[188:191], v[52:55]
	v_mfma_f32_16x16x32_bf16 v[48:51], v[180:183], v[188:191], v[48:51]
	v_mfma_f32_16x16x32_bf16 v[36:39], v[172:175], v[196:199], v[36:39]
	v_mfma_f32_16x16x32_bf16 v[32:35], v[180:183], v[196:199], v[32:35]
	v_mfma_f32_16x16x32_bf16 v[20:23], v[172:175], v[204:207], v[20:23]
	v_mfma_f32_16x16x32_bf16 v[16:19], v[180:183], v[204:207], v[16:19]
	v_mfma_f32_16x16x32_bf16 v[4:7], v[172:175], v[212:215], v[4:7]
	v_mfma_f32_16x16x32_bf16 v[0:3], v[180:183], v[212:215], v[0:3]
	s_setprio 0
	s_add_i32 s61, s61, 2
	s_add_u32 s38, s38, 0x100
	s_addc_u32 s39, s39, 0
	s_add_u32 s57, s57, 0x100
	s_addc_u32 s60, s60, 0
	s_cmp_gt_u32 s61, 13
	s_barrier
	s_cbranch_scc0 .LBB0_1617
	s_and_b64 vcc, exec, s[8:9]
	s_cbranch_vccz .LBB0_1620
	s_barrier
